# tile-start restore barrier of the trailing wave half moved from right after the epilogue to right before the K-loop, so both halves run the next-tile scheduler and accumulator zeroing concurrently
# speedup vs baseline: 1.0089x; 1.0089x over previous
.LBB0_305:
	s_ashr_i32 s21, s20, 31
	s_lshl_b64 s[22:23], s[20:21], 20
	s_add_u32 s22, s52, s22
	s_addc_u32 s23, s53, s23
	s_and_b64 s[24:25], s[0:1], exec
	s_cselect_b32 s3, s23, s29
	s_cselect_b32 s21, s22, s28
	s_ashr_i32 s19, s18, 31
	s_lshl_b64 s[24:25], s[18:19], 20
	s_add_u32 s24, s12, s24
	s_addc_u32 s25, s13, s25
	s_and_b64 s[34:35], s[0:1], exec
	s_cselect_b32 s19, s25, s31
	s_cselect_b32 s27, s24, s30
	s_add_u32 s28, s28, 0x80080
	s_addc_u32 s29, s29, 0
	s_add_u32 s48, s30, 0x100
	v_mov_b32_e32 v2, 0
	s_addc_u32 s49, s31, 0
	s_mov_b32 s50, -2
	v_mov_b32_e32 v3, v2
	v_mov_b32_e32 v4, v2
	v_mov_b32_e32 v5, v2
	v_mov_b32_e32 v6, v2
	v_mov_b32_e32 v7, v2
	v_mov_b32_e32 v8, v2
	v_mov_b32_e32 v9, v2
	v_mov_b32_e32 v18, v2
	v_mov_b32_e32 v19, v2
	v_mov_b32_e32 v20, v2
	v_mov_b32_e32 v21, v2
	v_mov_b32_e32 v22, v2
	v_mov_b32_e32 v23, v2
	v_mov_b32_e32 v24, v2
	v_mov_b32_e32 v25, v2
	v_mov_b32_e32 v34, v2
	v_mov_b32_e32 v35, v2
	v_mov_b32_e32 v36, v2
	v_mov_b32_e32 v37, v2
	v_mov_b32_e32 v38, v2
	v_mov_b32_e32 v39, v2
	v_mov_b32_e32 v40, v2
	v_mov_b32_e32 v41, v2
	v_mov_b32_e32 v50, v2
	v_mov_b32_e32 v51, v2
	v_mov_b32_e32 v52, v2
	v_mov_b32_e32 v53, v2
	v_mov_b32_e32 v54, v2
	v_mov_b32_e32 v55, v2
	v_mov_b32_e32 v56, v2
	v_mov_b32_e32 v57, v2
	v_mov_b32_e32 v10, v2
	v_mov_b32_e32 v11, v2
	v_mov_b32_e32 v12, v2
	v_mov_b32_e32 v13, v2
	v_mov_b32_e32 v14, v2
	v_mov_b32_e32 v15, v2
	v_mov_b32_e32 v16, v2
	v_mov_b32_e32 v17, v2
	v_mov_b32_e32 v26, v2
	v_mov_b32_e32 v27, v2
	v_mov_b32_e32 v28, v2
	v_mov_b32_e32 v29, v2
	v_mov_b32_e32 v30, v2
	v_mov_b32_e32 v31, v2
	v_mov_b32_e32 v32, v2
	v_mov_b32_e32 v33, v2
	v_mov_b32_e32 v42, v2
	v_mov_b32_e32 v43, v2
	v_mov_b32_e32 v44, v2
	v_mov_b32_e32 v45, v2
	v_mov_b32_e32 v46, v2
	v_mov_b32_e32 v47, v2
	v_mov_b32_e32 v48, v2
	v_mov_b32_e32 v49, v2
	v_mov_b32_e32 v58, v2
	v_mov_b32_e32 v59, v2
	v_mov_b32_e32 v60, v2
	v_mov_b32_e32 v61, v2
	v_mov_b32_e32 v62, v2
	v_mov_b32_e32 v63, v2
	v_mov_b32_e32 v64, v2
	v_mov_b32_e32 v65, v2
	v_mov_b32_e32 v66, v2
	v_mov_b32_e32 v67, v2
	v_mov_b32_e32 v68, v2
	v_mov_b32_e32 v69, v2
	v_mov_b32_e32 v70, v2
	v_mov_b32_e32 v71, v2
	v_mov_b32_e32 v72, v2
	v_mov_b32_e32 v73, v2
	v_mov_b32_e32 v82, v2
	v_mov_b32_e32 v83, v2
	v_mov_b32_e32 v84, v2
	v_mov_b32_e32 v85, v2
	v_mov_b32_e32 v86, v2
	v_mov_b32_e32 v87, v2
	v_mov_b32_e32 v88, v2
	v_mov_b32_e32 v89, v2
	v_mov_b32_e32 v98, v2
	v_mov_b32_e32 v99, v2
	v_mov_b32_e32 v100, v2
	v_mov_b32_e32 v101, v2
	v_mov_b32_e32 v102, v2
	v_mov_b32_e32 v103, v2
	v_mov_b32_e32 v104, v2
	v_mov_b32_e32 v105, v2
	v_mov_b32_e32 v114, v2
	v_mov_b32_e32 v115, v2
	v_mov_b32_e32 v116, v2
	v_mov_b32_e32 v117, v2
	v_mov_b32_e32 v118, v2
	v_mov_b32_e32 v119, v2
	v_mov_b32_e32 v120, v2
	v_mov_b32_e32 v121, v2
	v_mov_b32_e32 v74, v2
	v_mov_b32_e32 v75, v2
	v_mov_b32_e32 v76, v2
	v_mov_b32_e32 v77, v2
	v_mov_b32_e32 v78, v2
	v_mov_b32_e32 v79, v2
	v_mov_b32_e32 v80, v2
	v_mov_b32_e32 v81, v2
	v_mov_b32_e32 v90, v2
	v_mov_b32_e32 v91, v2
	v_mov_b32_e32 v92, v2
	v_mov_b32_e32 v93, v2
	v_mov_b32_e32 v94, v2
	v_mov_b32_e32 v95, v2
	v_mov_b32_e32 v96, v2
	v_mov_b32_e32 v97, v2
	v_mov_b32_e32 v106, v2
	v_mov_b32_e32 v107, v2
	v_mov_b32_e32 v108, v2
	v_mov_b32_e32 v109, v2
	v_mov_b32_e32 v110, v2
	v_mov_b32_e32 v111, v2
	v_mov_b32_e32 v112, v2
	v_mov_b32_e32 v113, v2
	v_mov_b32_e32 v122, v2
	v_mov_b32_e32 v123, v2
	v_mov_b32_e32 v124, v2
	v_mov_b32_e32 v125, v2
	v_mov_b32_e32 v126, v2
	v_mov_b32_e32 v127, v2
	v_mov_b32_e32 v128, v2
	v_mov_b32_e32 v129, v2
	s_cmp_lt_u32 s39, 2
	s_cbranch_scc1 .Lp2_norestore
	s_andn2_b64 vcc, exec, s[4:5]
	s_cbranch_vccnz .Lp2_norestore
	s_barrier
.Lp2_norestore:
.LBB0_306:
	ds_read_b128 v[166:169], v162
	ds_read_b128 v[170:173], v162 offset:1024
	ds_read_b128 v[174:177], v162 offset:2048
	ds_read_b128 v[180:183], v162 offset:3072
	ds_read_b128 v[184:187], v163
	ds_read_b128 v[188:191], v163 offset:1024
	ds_read_b128 v[192:195], v163 offset:2048
	ds_read_b128 v[196:199], v163 offset:3072
	s_add_u32 s30, s28, 0xfff80080
	s_addc_u32 s31, s29, -1
	s_cmp_eq_u32 s50, 28
	s_cselect_b32 s35, s3, s31
	s_cselect_b32 s34, s21, s30
	s_cselect_b32 s31, s19, s49
	s_cselect_b32 s30, s27, s48
	v_lshl_add_u64 v[160:161], s[28:29], 0, v[152:153]
	s_add_i32 m0, s33, 0xc000
	ds_read_b128 v[200:203], v164
	ds_read_b128 v[204:207], v164 offset:1024
	ds_read_b128 v[208:211], v164 offset:2048
	ds_read_b128 v[212:215], v164 offset:3072
	ds_read_b128 v[216:219], v164 offset:4096
	ds_read_b128 v[220:223], v164 offset:5120
	ds_read_b128 v[224:227], v164 offset:6144
	ds_read_b128 v[228:231], v164 offset:7168
	global_load_lds_dwordx4 v[160:161], off
	v_lshl_add_u64 v[160:161], s[28:29], 0, v[154:155]
	s_add_i32 m0, s33, 0xe000
	s_nop 0
	global_load_lds_dwordx4 v[160:161], off
	s_waitcnt vmcnt(8)
	s_waitcnt lgkmcnt(0)
	s_setprio 1
	s_barrier
	v_mfma_f32_16x16x32_bf16 v[126:129], v[166:169], v[200:203], v[126:129]
	v_mfma_f32_16x16x32_bf16 v[122:125], v[174:177], v[200:203], v[122:125]
	v_mfma_f32_16x16x32_bf16 v[110:113], v[166:169], v[208:211], v[110:113]
	v_mfma_f32_16x16x32_bf16 v[106:109], v[174:177], v[208:211], v[106:109]
	v_mfma_f32_16x16x32_bf16 v[94:97], v[166:169], v[216:219], v[94:97]
	v_mfma_f32_16x16x32_bf16 v[90:93], v[174:177], v[216:219], v[90:93]
	v_mfma_f32_16x16x32_bf16 v[78:81], v[166:169], v[224:227], v[78:81]
	v_mfma_f32_16x16x32_bf16 v[74:77], v[174:177], v[224:227], v[74:77]
	v_mfma_f32_16x16x32_bf16 v[126:129], v[170:173], v[204:207], v[126:129]
	v_mfma_f32_16x16x32_bf16 v[122:125], v[180:183], v[204:207], v[122:125]
	v_mfma_f32_16x16x32_bf16 v[110:113], v[170:173], v[212:215], v[110:113]
	v_mfma_f32_16x16x32_bf16 v[106:109], v[180:183], v[212:215], v[106:109]
	v_mfma_f32_16x16x32_bf16 v[94:97], v[170:173], v[220:223], v[94:97]
	v_mfma_f32_16x16x32_bf16 v[90:93], v[180:183], v[220:223], v[90:93]
	v_mfma_f32_16x16x32_bf16 v[78:81], v[170:173], v[228:231], v[78:81]
	v_mfma_f32_16x16x32_bf16 v[74:77], v[180:183], v[228:231], v[74:77]
	v_mfma_f32_16x16x32_bf16 v[118:121], v[184:187], v[200:203], v[118:121]
	v_mfma_f32_16x16x32_bf16 v[114:117], v[192:195], v[200:203], v[114:117]
	v_mfma_f32_16x16x32_bf16 v[102:105], v[184:187], v[208:211], v[102:105]
	v_mfma_f32_16x16x32_bf16 v[98:101], v[192:195], v[208:211], v[98:101]
	v_mfma_f32_16x16x32_bf16 v[86:89], v[184:187], v[216:219], v[86:89]
	v_mfma_f32_16x16x32_bf16 v[82:85], v[192:195], v[216:219], v[82:85]
	v_mfma_f32_16x16x32_bf16 v[70:73], v[184:187], v[224:227], v[70:73]
	v_mfma_f32_16x16x32_bf16 v[66:69], v[192:195], v[224:227], v[66:69]
	v_mfma_f32_16x16x32_bf16 v[118:121], v[188:191], v[204:207], v[118:121]
	v_mfma_f32_16x16x32_bf16 v[114:117], v[196:199], v[204:207], v[114:117]
	v_mfma_f32_16x16x32_bf16 v[102:105], v[188:191], v[212:215], v[102:105]
	v_mfma_f32_16x16x32_bf16 v[98:101], v[196:199], v[212:215], v[98:101]
	v_mfma_f32_16x16x32_bf16 v[86:89], v[188:191], v[220:223], v[86:89]
	v_mfma_f32_16x16x32_bf16 v[82:85], v[196:199], v[220:223], v[82:85]
	v_mfma_f32_16x16x32_bf16 v[70:73], v[188:191], v[228:231], v[70:73]
	v_mfma_f32_16x16x32_bf16 v[66:69], v[196:199], v[228:231], v[66:69]
	s_barrier
	s_setprio 0
	s_add_i32 s51, s45, s17
	v_lshl_add_u64 v[160:161], s[30:31], 0, v[138:139]
	s_mov_b32 m0, s51
	ds_read_b128 v[200:203], v164 offset:16384
	ds_read_b128 v[204:207], v164 offset:17408
	ds_read_b128 v[208:211], v164 offset:18432
	ds_read_b128 v[212:215], v164 offset:19456
	ds_read_b128 v[216:219], v164 offset:20480
	ds_read_b128 v[220:223], v164 offset:21504
	ds_read_b128 v[224:227], v164 offset:22528
	ds_read_b128 v[228:231], v164 offset:23552
	global_load_lds_dwordx4 v[160:161], off
	s_add_i32 m0, s51, 0x2000
	s_add_u32 s56, s30, 0x80000
	v_lshl_add_u64 v[232:233], s[30:31], 0, v[142:143]
	s_addc_u32 s57, s31, 0
	s_add_i32 s51, s47, s17
	global_load_lds_dwordx4 v[232:233], off
	v_lshl_add_u64 v[234:235], s[56:57], 0, v[138:139]
	s_mov_b32 m0, s51
	v_lshl_add_u64 v[236:237], s[34:35], 0, v[140:141]
	global_load_lds_dwordx4 v[234:235], off
	v_lshl_add_u64 v[234:235], s[56:57], 0, v[142:143]
	s_add_i32 m0, s51, 0x2000
	s_nop 0
	global_load_lds_dwordx4 v[234:235], off
	v_lshl_add_u64 v[234:235], s[34:35], 0, v[136:137]
	s_mov_b32 m0, s33
	s_nop 0
	global_load_lds_dwordx4 v[234:235], off
	s_mov_b32 m0, s36
	s_nop 0
	global_load_lds_dwordx4 v[236:237], off
	s_waitcnt vmcnt(8)
	s_waitcnt lgkmcnt(0)
	s_setprio 1
	s_barrier
	v_mfma_f32_16x16x32_bf16 v[62:65], v[166:169], v[200:203], v[62:65]
	v_mfma_f32_16x16x32_bf16 v[58:61], v[174:177], v[200:203], v[58:61]
	v_mfma_f32_16x16x32_bf16 v[46:49], v[166:169], v[208:211], v[46:49]
	v_mfma_f32_16x16x32_bf16 v[42:45], v[174:177], v[208:211], v[42:45]
	v_mfma_f32_16x16x32_bf16 v[30:33], v[166:169], v[216:219], v[30:33]
	v_mfma_f32_16x16x32_bf16 v[26:29], v[174:177], v[216:219], v[26:29]
	v_mfma_f32_16x16x32_bf16 v[14:17], v[166:169], v[224:227], v[14:17]
	v_mfma_f32_16x16x32_bf16 v[10:13], v[174:177], v[224:227], v[10:13]
	v_mfma_f32_16x16x32_bf16 v[62:65], v[170:173], v[204:207], v[62:65]
	v_mfma_f32_16x16x32_bf16 v[58:61], v[180:183], v[204:207], v[58:61]
	v_mfma_f32_16x16x32_bf16 v[46:49], v[170:173], v[212:215], v[46:49]
	v_mfma_f32_16x16x32_bf16 v[42:45], v[180:183], v[212:215], v[42:45]
	v_mfma_f32_16x16x32_bf16 v[30:33], v[170:173], v[220:223], v[30:33]
	v_mfma_f32_16x16x32_bf16 v[26:29], v[180:183], v[220:223], v[26:29]
	v_mfma_f32_16x16x32_bf16 v[14:17], v[170:173], v[228:231], v[14:17]
	v_mfma_f32_16x16x32_bf16 v[10:13], v[180:183], v[228:231], v[10:13]
	v_mfma_f32_16x16x32_bf16 v[54:57], v[184:187], v[200:203], v[54:57]
	v_mfma_f32_16x16x32_bf16 v[50:53], v[192:195], v[200:203], v[50:53]
	v_mfma_f32_16x16x32_bf16 v[38:41], v[184:187], v[208:211], v[38:41]
	v_mfma_f32_16x16x32_bf16 v[34:37], v[192:195], v[208:211], v[34:37]
	v_mfma_f32_16x16x32_bf16 v[22:25], v[184:187], v[216:219], v[22:25]
	v_mfma_f32_16x16x32_bf16 v[18:21], v[192:195], v[216:219], v[18:21]
	v_mfma_f32_16x16x32_bf16 v[6:9], v[184:187], v[224:227], v[6:9]
	v_mfma_f32_16x16x32_bf16 v[2:5], v[192:195], v[224:227], v[2:5]
	v_mfma_f32_16x16x32_bf16 v[54:57], v[188:191], v[204:207], v[54:57]
	v_mfma_f32_16x16x32_bf16 v[50:53], v[196:199], v[204:207], v[50:53]
	v_mfma_f32_16x16x32_bf16 v[38:41], v[188:191], v[212:215], v[38:41]
	v_mfma_f32_16x16x32_bf16 v[34:37], v[196:199], v[212:215], v[34:37]
	v_mfma_f32_16x16x32_bf16 v[22:25], v[188:191], v[220:223], v[22:25]
	v_mfma_f32_16x16x32_bf16 v[18:21], v[196:199], v[220:223], v[18:21]
	v_mfma_f32_16x16x32_bf16 v[6:9], v[188:191], v[228:231], v[6:9]
	v_mfma_f32_16x16x32_bf16 v[2:5], v[196:199], v[228:231], v[2:5]
	s_barrier
	s_setprio 0
	s_add_i32 s51, 0, 0x18000
	v_add_u32_e32 v144, s51, v135
	s_add_i32 s56, 0, 0x1c000
	ds_read_b128 v[166:169], v144
	ds_read_b128 v[170:173], v144 offset:1024
	ds_read_b128 v[174:177], v144 offset:2048
	ds_read_b128 v[180:183], v144 offset:3072
	v_add_u32_e32 v144, s56, v135
	ds_read_b128 v[184:187], v144
	ds_read_b128 v[188:191], v144 offset:1024
	ds_read_b128 v[192:195], v144 offset:2048
	ds_read_b128 v[196:199], v144 offset:3072
	s_add_u32 s34, s34, 0x80000
	s_addc_u32 s35, s35, 0
	s_mov_b32 m0, s37
	v_lshl_add_u64 v[238:239], s[34:35], 0, v[136:137]
	ds_read_b128 v[200:203], v164 offset:32768
	ds_read_b128 v[204:207], v164 offset:33792
	ds_read_b128 v[208:211], v164 offset:34816
	ds_read_b128 v[212:215], v164 offset:35840
	ds_read_b128 v[216:219], v164 offset:36864
	ds_read_b128 v[220:223], v164 offset:37888
	ds_read_b128 v[224:227], v164 offset:38912
	ds_read_b128 v[228:231], v164 offset:39936
	global_load_lds_dwordx4 v[238:239], off
	v_lshl_add_u64 v[238:239], s[34:35], 0, v[140:141]
	s_mov_b32 m0, s38
	s_nop 0
	global_load_lds_dwordx4 v[238:239], off
	s_waitcnt vmcnt(8)
	s_waitcnt lgkmcnt(0)
	s_setprio 1
	s_barrier
	v_mfma_f32_16x16x32_bf16 v[126:129], v[166:169], v[200:203], v[126:129]
	v_mfma_f32_16x16x32_bf16 v[122:125], v[174:177], v[200:203], v[122:125]
	v_mfma_f32_16x16x32_bf16 v[110:113], v[166:169], v[208:211], v[110:113]
	v_mfma_f32_16x16x32_bf16 v[106:109], v[174:177], v[208:211], v[106:109]
	v_mfma_f32_16x16x32_bf16 v[94:97], v[166:169], v[216:219], v[94:97]
	v_mfma_f32_16x16x32_bf16 v[90:93], v[174:177], v[216:219], v[90:93]
	v_mfma_f32_16x16x32_bf16 v[78:81], v[166:169], v[224:227], v[78:81]
	v_mfma_f32_16x16x32_bf16 v[74:77], v[174:177], v[224:227], v[74:77]
	v_mfma_f32_16x16x32_bf16 v[126:129], v[170:173], v[204:207], v[126:129]
	v_mfma_f32_16x16x32_bf16 v[122:125], v[180:183], v[204:207], v[122:125]
	v_mfma_f32_16x16x32_bf16 v[110:113], v[170:173], v[212:215], v[110:113]
	v_mfma_f32_16x16x32_bf16 v[106:109], v[180:183], v[212:215], v[106:109]
	v_mfma_f32_16x16x32_bf16 v[94:97], v[170:173], v[220:223], v[94:97]
	v_mfma_f32_16x16x32_bf16 v[90:93], v[180:183], v[220:223], v[90:93]
	v_mfma_f32_16x16x32_bf16 v[78:81], v[170:173], v[228:231], v[78:81]
	v_mfma_f32_16x16x32_bf16 v[74:77], v[180:183], v[228:231], v[74:77]
	v_mfma_f32_16x16x32_bf16 v[118:121], v[184:187], v[200:203], v[118:121]
	v_mfma_f32_16x16x32_bf16 v[114:117], v[192:195], v[200:203], v[114:117]
	v_mfma_f32_16x16x32_bf16 v[102:105], v[184:187], v[208:211], v[102:105]
	v_mfma_f32_16x16x32_bf16 v[98:101], v[192:195], v[208:211], v[98:101]
	v_mfma_f32_16x16x32_bf16 v[86:89], v[184:187], v[216:219], v[86:89]
	v_mfma_f32_16x16x32_bf16 v[82:85], v[192:195], v[216:219], v[82:85]
	v_mfma_f32_16x16x32_bf16 v[70:73], v[184:187], v[224:227], v[70:73]
	v_mfma_f32_16x16x32_bf16 v[66:69], v[192:195], v[224:227], v[66:69]
	v_mfma_f32_16x16x32_bf16 v[118:121], v[188:191], v[204:207], v[118:121]
	v_mfma_f32_16x16x32_bf16 v[114:117], v[196:199], v[204:207], v[114:117]
	v_mfma_f32_16x16x32_bf16 v[102:105], v[188:191], v[212:215], v[102:105]
	v_mfma_f32_16x16x32_bf16 v[98:101], v[196:199], v[212:215], v[98:101]
	v_mfma_f32_16x16x32_bf16 v[86:89], v[188:191], v[220:223], v[86:89]
	v_mfma_f32_16x16x32_bf16 v[82:85], v[196:199], v[220:223], v[82:85]
	v_mfma_f32_16x16x32_bf16 v[70:73], v[188:191], v[228:231], v[70:73]
	v_mfma_f32_16x16x32_bf16 v[66:69], v[196:199], v[228:231], v[66:69]
	s_barrier
	s_setprio 0
	s_add_i32 s34, s51, s17
	v_lshl_add_u64 v[160:161], v[160:161], 0, s[6:7]
	s_mov_b32 m0, s34
	ds_read_b128 v[200:203], v164 offset:49152
	ds_read_b128 v[204:207], v164 offset:50176
	ds_read_b128 v[208:211], v164 offset:51200
	ds_read_b128 v[212:215], v164 offset:52224
	ds_read_b128 v[216:219], v164 offset:53248
	ds_read_b128 v[220:223], v164 offset:54272
	ds_read_b128 v[224:227], v164 offset:55296
	ds_read_b128 v[228:231], v164 offset:56320
	global_load_lds_dwordx4 v[160:161], off
	s_add_i32 m0, s34, 0x2000
	s_add_u32 s30, s30, 0x80080
	v_lshl_add_u64 v[160:161], v[232:233], 0, s[6:7]
	s_addc_u32 s31, s31, 0
	s_add_i32 s34, s56, s17
	global_load_lds_dwordx4 v[160:161], off
	v_lshl_add_u64 v[160:161], s[30:31], 0, v[138:139]
	s_mov_b32 m0, s34
	s_nop 0
	global_load_lds_dwordx4 v[160:161], off
	v_lshl_add_u64 v[160:161], s[30:31], 0, v[142:143]
	s_add_i32 m0, s34, 0x2000
	s_nop 0
	global_load_lds_dwordx4 v[160:161], off
	v_lshl_add_u64 v[160:161], v[234:235], 0, s[6:7]
	s_mov_b32 m0, s40
	s_nop 0
	global_load_lds_dwordx4 v[160:161], off
	v_lshl_add_u64 v[160:161], v[236:237], 0, s[6:7]
	s_mov_b32 m0, s41
	s_nop 0
	global_load_lds_dwordx4 v[160:161], off
	s_waitcnt vmcnt(8)
	s_waitcnt lgkmcnt(0)
	s_setprio 1
	s_barrier
	v_mfma_f32_16x16x32_bf16 v[62:65], v[166:169], v[200:203], v[62:65]
	v_mfma_f32_16x16x32_bf16 v[58:61], v[174:177], v[200:203], v[58:61]
	v_mfma_f32_16x16x32_bf16 v[46:49], v[166:169], v[208:211], v[46:49]
	v_mfma_f32_16x16x32_bf16 v[42:45], v[174:177], v[208:211], v[42:45]
	v_mfma_f32_16x16x32_bf16 v[30:33], v[166:169], v[216:219], v[30:33]
	v_mfma_f32_16x16x32_bf16 v[26:29], v[174:177], v[216:219], v[26:29]
	v_mfma_f32_16x16x32_bf16 v[14:17], v[166:169], v[224:227], v[14:17]
	v_mfma_f32_16x16x32_bf16 v[10:13], v[174:177], v[224:227], v[10:13]
	v_mfma_f32_16x16x32_bf16 v[62:65], v[170:173], v[204:207], v[62:65]
	v_mfma_f32_16x16x32_bf16 v[58:61], v[180:183], v[204:207], v[58:61]
	v_mfma_f32_16x16x32_bf16 v[46:49], v[170:173], v[212:215], v[46:49]
	v_mfma_f32_16x16x32_bf16 v[42:45], v[180:183], v[212:215], v[42:45]
	v_mfma_f32_16x16x32_bf16 v[30:33], v[170:173], v[220:223], v[30:33]
	v_mfma_f32_16x16x32_bf16 v[26:29], v[180:183], v[220:223], v[26:29]
	v_mfma_f32_16x16x32_bf16 v[14:17], v[170:173], v[228:231], v[14:17]
	v_mfma_f32_16x16x32_bf16 v[10:13], v[180:183], v[228:231], v[10:13]
	v_mfma_f32_16x16x32_bf16 v[54:57], v[184:187], v[200:203], v[54:57]
	v_mfma_f32_16x16x32_bf16 v[50:53], v[192:195], v[200:203], v[50:53]
	v_mfma_f32_16x16x32_bf16 v[38:41], v[184:187], v[208:211], v[38:41]
	v_mfma_f32_16x16x32_bf16 v[34:37], v[192:195], v[208:211], v[34:37]
	v_mfma_f32_16x16x32_bf16 v[22:25], v[184:187], v[216:219], v[22:25]
	v_mfma_f32_16x16x32_bf16 v[18:21], v[192:195], v[216:219], v[18:21]
	v_mfma_f32_16x16x32_bf16 v[6:9], v[184:187], v[224:227], v[6:9]
	v_mfma_f32_16x16x32_bf16 v[2:5], v[192:195], v[224:227], v[2:5]
	v_mfma_f32_16x16x32_bf16 v[54:57], v[188:191], v[204:207], v[54:57]
	v_mfma_f32_16x16x32_bf16 v[50:53], v[196:199], v[204:207], v[50:53]
	v_mfma_f32_16x16x32_bf16 v[38:41], v[188:191], v[212:215], v[38:41]
	v_mfma_f32_16x16x32_bf16 v[34:37], v[196:199], v[212:215], v[34:37]
	v_mfma_f32_16x16x32_bf16 v[22:25], v[188:191], v[220:223], v[22:25]
	v_mfma_f32_16x16x32_bf16 v[18:21], v[196:199], v[220:223], v[18:21]
	v_mfma_f32_16x16x32_bf16 v[6:9], v[188:191], v[228:231], v[6:9]
	v_mfma_f32_16x16x32_bf16 v[2:5], v[196:199], v[228:231], v[2:5]
	s_barrier
	s_setprio 0
	s_add_i32 s50, s50, 2
	s_add_u32 s28, s28, 0x100
	s_addc_u32 s29, s29, 0
	s_add_u32 s48, s48, 0x100
	s_addc_u32 s49, s49, 0
	s_cmp_gt_u32 s50, 29
	s_cbranch_scc0 .LBB0_306
	s_and_b64 vcc, exec, s[8:9]
	s_cbranch_vccz .LBB0_314
	s_barrier
	v_lshl_add_u32 v160, s26, 8, v133
	s_cmp_gt_i32 s2, 35
	s_mov_b64 s[26:27], -1
	s_cbranch_scc1 .LBB0_315

.LBB0_415:
	s_andn2_b64 vcc, exec, s[4:5]
	s_cbranch_vccnz .LBB0_301
	s_branch .LBB0_301

.LBB0_985:
	s_ashr_i32 s17, s16, 31
	s_lshl_b64 s[18:19], s[16:17], 19
	s_add_u32 s18, s52, s18
	s_addc_u32 s19, s53, s19
	s_and_b64 s[20:21], s[0:1], exec
	s_cselect_b32 s17, s19, s25
	s_cselect_b32 s45, s18, s24
	s_ashr_i32 s15, s14, 31
	s_lshl_b64 s[20:21], s[14:15], 19
	s_add_u32 s20, s58, s20
	s_addc_u32 s21, s59, s21
	s_and_b64 s[28:29], s[0:1], exec
	s_cselect_b32 s15, s21, s27
	s_cselect_b32 s46, s20, s26
	s_add_u32 s24, s24, 0x40080
	s_addc_u32 s25, s25, 0
	s_add_u32 s47, s26, 0x100
	v_mov_b32_e32 v2, 0
	s_addc_u32 s48, s27, 0
	s_mov_b32 s49, -2
	v_mov_b32_e32 v3, v2
	v_mov_b32_e32 v4, v2
	v_mov_b32_e32 v5, v2
	v_mov_b32_e32 v6, v2
	v_mov_b32_e32 v7, v2
	v_mov_b32_e32 v8, v2
	v_mov_b32_e32 v9, v2
	s_waitcnt vmcnt(0)
	v_mov_b32_e32 v18, v2
	v_mov_b32_e32 v19, v2
	v_mov_b32_e32 v20, v2
	v_mov_b32_e32 v21, v2
	v_mov_b32_e32 v22, v2
	v_mov_b32_e32 v23, v2
	v_mov_b32_e32 v24, v2
	v_mov_b32_e32 v25, v2
	v_mov_b32_e32 v34, v2
	v_mov_b32_e32 v35, v2
	v_mov_b32_e32 v36, v2
	v_mov_b32_e32 v37, v2
	v_mov_b32_e32 v38, v2
	v_mov_b32_e32 v39, v2
	v_mov_b32_e32 v40, v2
	v_mov_b32_e32 v41, v2
	v_mov_b32_e32 v50, v2
	v_mov_b32_e32 v51, v2
	v_mov_b32_e32 v52, v2
	v_mov_b32_e32 v53, v2
	v_mov_b32_e32 v54, v2
	v_mov_b32_e32 v55, v2
	v_mov_b32_e32 v56, v2
	v_mov_b32_e32 v57, v2
	v_mov_b32_e32 v10, v2
	v_mov_b32_e32 v11, v2
	v_mov_b32_e32 v12, v2
	v_mov_b32_e32 v13, v2
	v_mov_b32_e32 v14, v2
	v_mov_b32_e32 v15, v2
	v_mov_b32_e32 v16, v2
	v_mov_b32_e32 v17, v2
	v_mov_b32_e32 v26, v2
	v_mov_b32_e32 v27, v2
	v_mov_b32_e32 v28, v2
	v_mov_b32_e32 v29, v2
	v_mov_b32_e32 v30, v2
	v_mov_b32_e32 v31, v2
	v_mov_b32_e32 v32, v2
	v_mov_b32_e32 v33, v2
	v_mov_b32_e32 v42, v2
	v_mov_b32_e32 v43, v2
	v_mov_b32_e32 v44, v2
	v_mov_b32_e32 v45, v2
	v_mov_b32_e32 v46, v2
	v_mov_b32_e32 v47, v2
	v_mov_b32_e32 v48, v2
	v_mov_b32_e32 v49, v2
	v_mov_b32_e32 v58, v2
	v_mov_b32_e32 v59, v2
	v_mov_b32_e32 v60, v2
	v_mov_b32_e32 v61, v2
	v_mov_b32_e32 v62, v2
	v_mov_b32_e32 v63, v2
	v_mov_b32_e32 v64, v2
	v_mov_b32_e32 v65, v2
	v_mov_b32_e32 v66, v2
	v_mov_b32_e32 v67, v2
	v_mov_b32_e32 v68, v2
	v_mov_b32_e32 v69, v2
	v_mov_b32_e32 v70, v2
	v_mov_b32_e32 v71, v2
	v_mov_b32_e32 v72, v2
	v_mov_b32_e32 v73, v2
	v_mov_b32_e32 v82, v2
	v_mov_b32_e32 v83, v2
	v_mov_b32_e32 v84, v2
	v_mov_b32_e32 v85, v2
	v_mov_b32_e32 v86, v2
	v_mov_b32_e32 v87, v2
	v_mov_b32_e32 v88, v2
	v_mov_b32_e32 v89, v2
	v_mov_b32_e32 v98, v2
	v_mov_b32_e32 v99, v2
	v_mov_b32_e32 v100, v2
	v_mov_b32_e32 v101, v2
	v_mov_b32_e32 v102, v2
	v_mov_b32_e32 v103, v2
	v_mov_b32_e32 v104, v2
	v_mov_b32_e32 v105, v2
	v_mov_b32_e32 v114, v2
	v_mov_b32_e32 v115, v2
	v_mov_b32_e32 v116, v2
	v_mov_b32_e32 v117, v2
	v_mov_b32_e32 v118, v2
	v_mov_b32_e32 v119, v2
	v_mov_b32_e32 v120, v2
	v_mov_b32_e32 v121, v2
	v_mov_b32_e32 v74, v2
	v_mov_b32_e32 v75, v2
	v_mov_b32_e32 v76, v2
	v_mov_b32_e32 v77, v2
	v_mov_b32_e32 v78, v2
	v_mov_b32_e32 v79, v2
	v_mov_b32_e32 v80, v2
	v_mov_b32_e32 v81, v2
	v_mov_b32_e32 v90, v2
	v_mov_b32_e32 v91, v2
	v_mov_b32_e32 v92, v2
	v_mov_b32_e32 v93, v2
	v_mov_b32_e32 v94, v2
	v_mov_b32_e32 v95, v2
	v_mov_b32_e32 v96, v2
	v_mov_b32_e32 v97, v2
	v_mov_b32_e32 v106, v2
	v_mov_b32_e32 v107, v2
	v_mov_b32_e32 v108, v2
	v_mov_b32_e32 v109, v2
	v_mov_b32_e32 v110, v2
	v_mov_b32_e32 v111, v2
	v_mov_b32_e32 v112, v2
	v_mov_b32_e32 v113, v2
	v_mov_b32_e32 v122, v2
	v_mov_b32_e32 v123, v2
	v_mov_b32_e32 v124, v2
	v_mov_b32_e32 v125, v2
	v_mov_b32_e32 v126, v2
	v_mov_b32_e32 v127, v2
	v_mov_b32_e32 v128, v2
	v_mov_b32_e32 v129, v2
	s_cmp_lt_u32 s37, 2
	s_cbranch_scc1 .Lp5_norestore
	s_andn2_b64 vcc, exec, s[2:3]
	s_cbranch_vccnz .Lp5_norestore
	s_barrier
.Lp5_norestore:
.LBB0_986:
	ds_read_b128 v[148:151], v155
	ds_read_b128 v[158:161], v155 offset:1024
	ds_read_b128 v[162:165], v155 offset:2048
	ds_read_b128 v[166:169], v155 offset:3072
	ds_read_b128 v[170:173], v156
	ds_read_b128 v[174:177], v156 offset:1024
	ds_read_b128 v[180:183], v156 offset:2048
	ds_read_b128 v[184:187], v156 offset:3072
	s_add_u32 s26, s24, 0xfffc0080
	s_addc_u32 s27, s25, -1
	s_cmp_eq_u32 s49, 12
	s_cselect_b32 s29, s17, s27
	s_cselect_b32 s28, s45, s26
	s_cselect_b32 s27, s15, s48
	s_cselect_b32 s26, s46, s47
	v_lshl_add_u64 v[220:221], s[24:25], 0, v[138:139]
	s_add_i32 m0, s23, 0xc000
	ds_read_b128 v[188:191], v157
	ds_read_b128 v[192:195], v157 offset:1024
	ds_read_b128 v[196:199], v157 offset:2048
	ds_read_b128 v[200:203], v157 offset:3072
	ds_read_b128 v[204:207], v157 offset:4096
	ds_read_b128 v[208:211], v157 offset:5120
	ds_read_b128 v[212:215], v157 offset:6144
	ds_read_b128 v[216:219], v157 offset:7168
	global_load_lds_dwordx4 v[220:221], off
	v_lshl_add_u64 v[220:221], s[24:25], 0, v[140:141]
	s_add_i32 m0, s23, 0xe000
	s_nop 0
	global_load_lds_dwordx4 v[220:221], off
	s_waitcnt vmcnt(8)
	s_waitcnt lgkmcnt(0)
	s_setprio 1
	s_barrier
	v_mfma_f32_16x16x32_bf16 v[126:129], v[148:151], v[188:191], v[126:129]
	v_mfma_f32_16x16x32_bf16 v[122:125], v[162:165], v[188:191], v[122:125]
	v_mfma_f32_16x16x32_bf16 v[110:113], v[148:151], v[196:199], v[110:113]
	v_mfma_f32_16x16x32_bf16 v[106:109], v[162:165], v[196:199], v[106:109]
	v_mfma_f32_16x16x32_bf16 v[94:97], v[148:151], v[204:207], v[94:97]
	v_mfma_f32_16x16x32_bf16 v[90:93], v[162:165], v[204:207], v[90:93]
	v_mfma_f32_16x16x32_bf16 v[78:81], v[148:151], v[212:215], v[78:81]
	v_mfma_f32_16x16x32_bf16 v[74:77], v[162:165], v[212:215], v[74:77]
	v_mfma_f32_16x16x32_bf16 v[126:129], v[158:161], v[192:195], v[126:129]
	v_mfma_f32_16x16x32_bf16 v[122:125], v[166:169], v[192:195], v[122:125]
	v_mfma_f32_16x16x32_bf16 v[110:113], v[158:161], v[200:203], v[110:113]
	v_mfma_f32_16x16x32_bf16 v[106:109], v[166:169], v[200:203], v[106:109]
	v_mfma_f32_16x16x32_bf16 v[94:97], v[158:161], v[208:211], v[94:97]
	v_mfma_f32_16x16x32_bf16 v[90:93], v[166:169], v[208:211], v[90:93]
	v_mfma_f32_16x16x32_bf16 v[78:81], v[158:161], v[216:219], v[78:81]
	v_mfma_f32_16x16x32_bf16 v[74:77], v[166:169], v[216:219], v[74:77]
	v_mfma_f32_16x16x32_bf16 v[118:121], v[170:173], v[188:191], v[118:121]
	v_mfma_f32_16x16x32_bf16 v[114:117], v[180:183], v[188:191], v[114:117]
	v_mfma_f32_16x16x32_bf16 v[102:105], v[170:173], v[196:199], v[102:105]
	v_mfma_f32_16x16x32_bf16 v[98:101], v[180:183], v[196:199], v[98:101]
	v_mfma_f32_16x16x32_bf16 v[86:89], v[170:173], v[204:207], v[86:89]
	v_mfma_f32_16x16x32_bf16 v[82:85], v[180:183], v[204:207], v[82:85]
	v_mfma_f32_16x16x32_bf16 v[70:73], v[170:173], v[212:215], v[70:73]
	v_mfma_f32_16x16x32_bf16 v[66:69], v[180:183], v[212:215], v[66:69]
	v_mfma_f32_16x16x32_bf16 v[118:121], v[174:177], v[192:195], v[118:121]
	v_mfma_f32_16x16x32_bf16 v[114:117], v[184:187], v[192:195], v[114:117]
	v_mfma_f32_16x16x32_bf16 v[102:105], v[174:177], v[200:203], v[102:105]
	v_mfma_f32_16x16x32_bf16 v[98:101], v[184:187], v[200:203], v[98:101]
	v_mfma_f32_16x16x32_bf16 v[86:89], v[174:177], v[208:211], v[86:89]
	v_mfma_f32_16x16x32_bf16 v[82:85], v[184:187], v[208:211], v[82:85]
	v_mfma_f32_16x16x32_bf16 v[70:73], v[174:177], v[216:219], v[70:73]
	v_mfma_f32_16x16x32_bf16 v[66:69], v[184:187], v[216:219], v[66:69]
	s_barrier
	s_setprio 0
	s_add_i32 s50, s42, s30
	v_lshl_add_u64 v[220:221], s[26:27], 0, v[134:135]
	s_mov_b32 m0, s50
	ds_read_b128 v[188:191], v157 offset:16384
	ds_read_b128 v[192:195], v157 offset:17408
	ds_read_b128 v[196:199], v157 offset:18432
	ds_read_b128 v[200:203], v157 offset:19456
	ds_read_b128 v[204:207], v157 offset:20480
	ds_read_b128 v[208:211], v157 offset:21504
	ds_read_b128 v[212:215], v157 offset:22528
	ds_read_b128 v[216:219], v157 offset:23552
	global_load_lds_dwordx4 v[220:221], off
	s_add_i32 m0, s50, 0x2000
	s_add_u32 s50, s26, 0x40000
	v_lshl_add_u64 v[222:223], s[26:27], 0, v[130:131]
	s_addc_u32 s51, s27, 0
	s_add_i32 s56, s43, s30
	global_load_lds_dwordx4 v[222:223], off
	v_lshl_add_u64 v[224:225], s[50:51], 0, v[134:135]
	s_mov_b32 m0, s56
	v_lshl_add_u64 v[226:227], s[28:29], 0, v[132:133]
	global_load_lds_dwordx4 v[224:225], off
	v_lshl_add_u64 v[224:225], s[50:51], 0, v[130:131]
	s_add_i32 m0, s56, 0x2000
	s_nop 0
	global_load_lds_dwordx4 v[224:225], off
	v_lshl_add_u64 v[224:225], s[28:29], 0, v[136:137]
	s_mov_b32 m0, s23
	s_nop 0
	global_load_lds_dwordx4 v[224:225], off
	s_mov_b32 m0, s34
	s_nop 0
	global_load_lds_dwordx4 v[226:227], off
	s_waitcnt vmcnt(8)
	s_waitcnt lgkmcnt(0)
	s_setprio 1
	s_barrier
	v_mfma_f32_16x16x32_bf16 v[62:65], v[148:151], v[188:191], v[62:65]
	v_mfma_f32_16x16x32_bf16 v[58:61], v[162:165], v[188:191], v[58:61]
	v_mfma_f32_16x16x32_bf16 v[46:49], v[148:151], v[196:199], v[46:49]
	v_mfma_f32_16x16x32_bf16 v[42:45], v[162:165], v[196:199], v[42:45]
	v_mfma_f32_16x16x32_bf16 v[30:33], v[148:151], v[204:207], v[30:33]
	v_mfma_f32_16x16x32_bf16 v[26:29], v[162:165], v[204:207], v[26:29]
	v_mfma_f32_16x16x32_bf16 v[14:17], v[148:151], v[212:215], v[14:17]
	v_mfma_f32_16x16x32_bf16 v[10:13], v[162:165], v[212:215], v[10:13]
	v_mfma_f32_16x16x32_bf16 v[62:65], v[158:161], v[192:195], v[62:65]
	v_mfma_f32_16x16x32_bf16 v[58:61], v[166:169], v[192:195], v[58:61]
	v_mfma_f32_16x16x32_bf16 v[46:49], v[158:161], v[200:203], v[46:49]
	v_mfma_f32_16x16x32_bf16 v[42:45], v[166:169], v[200:203], v[42:45]
	v_mfma_f32_16x16x32_bf16 v[30:33], v[158:161], v[208:211], v[30:33]
	v_mfma_f32_16x16x32_bf16 v[26:29], v[166:169], v[208:211], v[26:29]
	v_mfma_f32_16x16x32_bf16 v[14:17], v[158:161], v[216:219], v[14:17]
	v_mfma_f32_16x16x32_bf16 v[10:13], v[166:169], v[216:219], v[10:13]
	v_mfma_f32_16x16x32_bf16 v[54:57], v[170:173], v[188:191], v[54:57]
	v_mfma_f32_16x16x32_bf16 v[50:53], v[180:183], v[188:191], v[50:53]
	v_mfma_f32_16x16x32_bf16 v[38:41], v[170:173], v[196:199], v[38:41]
	v_mfma_f32_16x16x32_bf16 v[34:37], v[180:183], v[196:199], v[34:37]
	v_mfma_f32_16x16x32_bf16 v[22:25], v[170:173], v[204:207], v[22:25]
	v_mfma_f32_16x16x32_bf16 v[18:21], v[180:183], v[204:207], v[18:21]
	v_mfma_f32_16x16x32_bf16 v[6:9], v[170:173], v[212:215], v[6:9]
	v_mfma_f32_16x16x32_bf16 v[2:5], v[180:183], v[212:215], v[2:5]
	v_mfma_f32_16x16x32_bf16 v[54:57], v[174:177], v[192:195], v[54:57]
	v_mfma_f32_16x16x32_bf16 v[50:53], v[184:187], v[192:195], v[50:53]
	v_mfma_f32_16x16x32_bf16 v[38:41], v[174:177], v[200:203], v[38:41]
	v_mfma_f32_16x16x32_bf16 v[34:37], v[184:187], v[200:203], v[34:37]
	v_mfma_f32_16x16x32_bf16 v[22:25], v[174:177], v[208:211], v[22:25]
	v_mfma_f32_16x16x32_bf16 v[18:21], v[184:187], v[208:211], v[18:21]
	v_mfma_f32_16x16x32_bf16 v[6:9], v[174:177], v[216:219], v[6:9]
	v_mfma_f32_16x16x32_bf16 v[2:5], v[184:187], v[216:219], v[2:5]
	s_barrier
	s_setprio 0
	s_add_i32 s50, 0, 0x18000
	s_add_i32 s51, 0, 0x1c000
	v_add_u32_e32 v166, s50, v153
	v_add_u32_e32 v179, s51, v153
	ds_read_b128 v[148:151], v166
	ds_read_b128 v[158:161], v166 offset:1024
	ds_read_b128 v[162:165], v166 offset:2048
	ds_read_b128 v[166:169], v166 offset:3072
	ds_read_b128 v[170:173], v179
	ds_read_b128 v[174:177], v179 offset:1024
	ds_read_b128 v[180:183], v179 offset:2048
	ds_read_b128 v[184:187], v179 offset:3072
	s_add_u32 s28, s28, 0x40000
	s_addc_u32 s29, s29, 0
	s_mov_b32 m0, s35
	v_lshl_add_u64 v[228:229], s[28:29], 0, v[136:137]
	ds_read_b128 v[188:191], v157 offset:32768
	ds_read_b128 v[192:195], v157 offset:33792
	ds_read_b128 v[196:199], v157 offset:34816
	ds_read_b128 v[200:203], v157 offset:35840
	ds_read_b128 v[204:207], v157 offset:36864
	ds_read_b128 v[208:211], v157 offset:37888
	ds_read_b128 v[212:215], v157 offset:38912
	ds_read_b128 v[216:219], v157 offset:39936
	global_load_lds_dwordx4 v[228:229], off
	v_lshl_add_u64 v[228:229], s[28:29], 0, v[132:133]
	s_mov_b32 m0, s36
	s_nop 0
	global_load_lds_dwordx4 v[228:229], off
	s_waitcnt vmcnt(8)
	s_waitcnt lgkmcnt(0)
	s_setprio 1
	s_barrier
	v_mfma_f32_16x16x32_bf16 v[126:129], v[148:151], v[188:191], v[126:129]
	v_mfma_f32_16x16x32_bf16 v[122:125], v[162:165], v[188:191], v[122:125]
	v_mfma_f32_16x16x32_bf16 v[110:113], v[148:151], v[196:199], v[110:113]
	v_mfma_f32_16x16x32_bf16 v[106:109], v[162:165], v[196:199], v[106:109]
	v_mfma_f32_16x16x32_bf16 v[94:97], v[148:151], v[204:207], v[94:97]
	v_mfma_f32_16x16x32_bf16 v[90:93], v[162:165], v[204:207], v[90:93]
	v_mfma_f32_16x16x32_bf16 v[78:81], v[148:151], v[212:215], v[78:81]
	v_mfma_f32_16x16x32_bf16 v[74:77], v[162:165], v[212:215], v[74:77]
	v_mfma_f32_16x16x32_bf16 v[126:129], v[158:161], v[192:195], v[126:129]
	v_mfma_f32_16x16x32_bf16 v[122:125], v[166:169], v[192:195], v[122:125]
	v_mfma_f32_16x16x32_bf16 v[110:113], v[158:161], v[200:203], v[110:113]
	v_mfma_f32_16x16x32_bf16 v[106:109], v[166:169], v[200:203], v[106:109]
	v_mfma_f32_16x16x32_bf16 v[94:97], v[158:161], v[208:211], v[94:97]
	v_mfma_f32_16x16x32_bf16 v[90:93], v[166:169], v[208:211], v[90:93]
	v_mfma_f32_16x16x32_bf16 v[78:81], v[158:161], v[216:219], v[78:81]
	v_mfma_f32_16x16x32_bf16 v[74:77], v[166:169], v[216:219], v[74:77]
	v_mfma_f32_16x16x32_bf16 v[118:121], v[170:173], v[188:191], v[118:121]
	v_mfma_f32_16x16x32_bf16 v[114:117], v[180:183], v[188:191], v[114:117]
	v_mfma_f32_16x16x32_bf16 v[102:105], v[170:173], v[196:199], v[102:105]
	v_mfma_f32_16x16x32_bf16 v[98:101], v[180:183], v[196:199], v[98:101]
	v_mfma_f32_16x16x32_bf16 v[86:89], v[170:173], v[204:207], v[86:89]
	v_mfma_f32_16x16x32_bf16 v[82:85], v[180:183], v[204:207], v[82:85]
	v_mfma_f32_16x16x32_bf16 v[70:73], v[170:173], v[212:215], v[70:73]
	v_mfma_f32_16x16x32_bf16 v[66:69], v[180:183], v[212:215], v[66:69]
	v_mfma_f32_16x16x32_bf16 v[118:121], v[174:177], v[192:195], v[118:121]
	v_mfma_f32_16x16x32_bf16 v[114:117], v[184:187], v[192:195], v[114:117]
	v_mfma_f32_16x16x32_bf16 v[102:105], v[174:177], v[200:203], v[102:105]
	v_mfma_f32_16x16x32_bf16 v[98:101], v[184:187], v[200:203], v[98:101]
	v_mfma_f32_16x16x32_bf16 v[86:89], v[174:177], v[208:211], v[86:89]
	v_mfma_f32_16x16x32_bf16 v[82:85], v[184:187], v[208:211], v[82:85]
	v_mfma_f32_16x16x32_bf16 v[70:73], v[174:177], v[216:219], v[70:73]
	v_mfma_f32_16x16x32_bf16 v[66:69], v[184:187], v[216:219], v[66:69]
	s_barrier
	s_setprio 0
	s_add_i32 s28, s50, s30
	v_lshl_add_u64 v[220:221], v[220:221], 0, s[4:5]
	s_mov_b32 m0, s28
	ds_read_b128 v[188:191], v157 offset:49152
	ds_read_b128 v[192:195], v157 offset:50176
	ds_read_b128 v[196:199], v157 offset:51200
	ds_read_b128 v[200:203], v157 offset:52224
	ds_read_b128 v[204:207], v157 offset:53248
	ds_read_b128 v[208:211], v157 offset:54272
	ds_read_b128 v[212:215], v157 offset:55296
	ds_read_b128 v[216:219], v157 offset:56320
	global_load_lds_dwordx4 v[220:221], off
	s_add_i32 m0, s28, 0x2000
	s_add_u32 s26, s26, 0x40080
	v_lshl_add_u64 v[220:221], v[222:223], 0, s[4:5]
	s_addc_u32 s27, s27, 0
	s_add_i32 s28, s51, s30
	global_load_lds_dwordx4 v[220:221], off
	v_lshl_add_u64 v[220:221], s[26:27], 0, v[134:135]
	s_mov_b32 m0, s28
	s_nop 0
	global_load_lds_dwordx4 v[220:221], off
	v_lshl_add_u64 v[220:221], s[26:27], 0, v[130:131]
	s_add_i32 m0, s28, 0x2000
	s_nop 0
	global_load_lds_dwordx4 v[220:221], off
	v_lshl_add_u64 v[220:221], v[224:225], 0, s[4:5]
	s_mov_b32 m0, s38
	s_nop 0
	global_load_lds_dwordx4 v[220:221], off
	v_lshl_add_u64 v[220:221], v[226:227], 0, s[4:5]
	s_mov_b32 m0, s39
	s_nop 0
	global_load_lds_dwordx4 v[220:221], off
	s_waitcnt vmcnt(8)
	s_waitcnt lgkmcnt(0)
	s_setprio 1
	s_barrier
	v_mfma_f32_16x16x32_bf16 v[62:65], v[148:151], v[188:191], v[62:65]
	v_mfma_f32_16x16x32_bf16 v[58:61], v[162:165], v[188:191], v[58:61]
	v_mfma_f32_16x16x32_bf16 v[46:49], v[148:151], v[196:199], v[46:49]
	v_mfma_f32_16x16x32_bf16 v[42:45], v[162:165], v[196:199], v[42:45]
	v_mfma_f32_16x16x32_bf16 v[30:33], v[148:151], v[204:207], v[30:33]
	v_mfma_f32_16x16x32_bf16 v[26:29], v[162:165], v[204:207], v[26:29]
	v_mfma_f32_16x16x32_bf16 v[14:17], v[148:151], v[212:215], v[14:17]
	v_mfma_f32_16x16x32_bf16 v[10:13], v[162:165], v[212:215], v[10:13]
	v_mfma_f32_16x16x32_bf16 v[62:65], v[158:161], v[192:195], v[62:65]
	v_mfma_f32_16x16x32_bf16 v[58:61], v[166:169], v[192:195], v[58:61]
	v_mfma_f32_16x16x32_bf16 v[46:49], v[158:161], v[200:203], v[46:49]
	v_mfma_f32_16x16x32_bf16 v[42:45], v[166:169], v[200:203], v[42:45]
	v_mfma_f32_16x16x32_bf16 v[30:33], v[158:161], v[208:211], v[30:33]
	v_mfma_f32_16x16x32_bf16 v[26:29], v[166:169], v[208:211], v[26:29]
	v_mfma_f32_16x16x32_bf16 v[14:17], v[158:161], v[216:219], v[14:17]
	v_mfma_f32_16x16x32_bf16 v[10:13], v[166:169], v[216:219], v[10:13]
	v_mfma_f32_16x16x32_bf16 v[54:57], v[170:173], v[188:191], v[54:57]
	v_mfma_f32_16x16x32_bf16 v[50:53], v[180:183], v[188:191], v[50:53]
	v_mfma_f32_16x16x32_bf16 v[38:41], v[170:173], v[196:199], v[38:41]
	v_mfma_f32_16x16x32_bf16 v[34:37], v[180:183], v[196:199], v[34:37]
	v_mfma_f32_16x16x32_bf16 v[22:25], v[170:173], v[204:207], v[22:25]
	v_mfma_f32_16x16x32_bf16 v[18:21], v[180:183], v[204:207], v[18:21]
	v_mfma_f32_16x16x32_bf16 v[6:9], v[170:173], v[212:215], v[6:9]
	v_mfma_f32_16x16x32_bf16 v[2:5], v[180:183], v[212:215], v[2:5]
	v_mfma_f32_16x16x32_bf16 v[54:57], v[174:177], v[192:195], v[54:57]
	v_mfma_f32_16x16x32_bf16 v[50:53], v[184:187], v[192:195], v[50:53]
	v_mfma_f32_16x16x32_bf16 v[38:41], v[174:177], v[200:203], v[38:41]
	v_mfma_f32_16x16x32_bf16 v[34:37], v[184:187], v[200:203], v[34:37]
	v_mfma_f32_16x16x32_bf16 v[22:25], v[174:177], v[208:211], v[22:25]
	v_mfma_f32_16x16x32_bf16 v[18:21], v[184:187], v[208:211], v[18:21]
	v_mfma_f32_16x16x32_bf16 v[6:9], v[174:177], v[216:219], v[6:9]
	v_mfma_f32_16x16x32_bf16 v[2:5], v[184:187], v[216:219], v[2:5]
	s_barrier
	s_setprio 0
	s_add_i32 s49, s49, 2
	s_add_u32 s24, s24, 0x100
	s_addc_u32 s25, s25, 0
	s_add_u32 s47, s47, 0x100
	s_addc_u32 s48, s48, 0
	s_cmp_gt_u32 s49, 13
	s_cbranch_scc0 .LBB0_986
	s_and_b64 vcc, exec, s[8:9]
	s_cbranch_vccz .LBB0_989
	s_barrier
.LBB0_989:
	v_lshl_add_u32 v150, s22, 8, v152
	v_lshl_or_b32 v148, s44, 8, v154
	v_ashrrev_i32_e32 v151, 31, v150
	v_lshlrev_b64 v[158:159], 13, v[150:151]
	v_ashrrev_i32_e32 v149, 31, v148
	v_lshl_add_u64 v[158:159], s[64:65], 0, v[158:159]
	v_lshlrev_b64 v[148:149], 1, v[148:149]
	v_lshl_add_u64 v[162:163], v[158:159], 0, v[148:149]
	v_mov_b32_e32 v228, 0x20000
	v_mov_b32_e32 v229, 0
	v_lshl_add_u64 v[222:223], v[162:163], 0, v[228:229]
	v_lshl_add_u64 v[224:225], v[222:223], 0, v[228:229]
	v_lshl_add_u64 v[226:227], v[224:225], 0, v[228:229]
	global_load_dwordx4 v[190:193], v[162:163], off
	global_load_dwordx4 v[194:197], v[162:163], off offset:256
	global_load_dwordx4 v[198:201], v[222:223], off
	global_load_dwordx4 v[202:205], v[222:223], off offset:256
	global_load_dwordx4 v[206:209], v[224:225], off
	global_load_dwordx4 v[210:213], v[224:225], off offset:256
	global_load_dwordx4 v[214:217], v[226:227], off
	global_load_dwordx4 v[218:221], v[226:227], off offset:256
	v_lshl_add_u64 v[222:223], v[228:229], 3, v[162:163]
	v_lshl_add_u64 v[224:225], v[222:223], 0, v[228:229]
	v_lshl_add_u64 v[226:227], v[224:225], 0, v[228:229]
	v_lshl_add_u64 v[228:229], v[226:227], 0, v[228:229]
	v_lshlrev_b64 v[164:165], 12, v[150:151]
	v_lshl_add_u64 v[164:165], s[54:55], 0, v[164:165]
	v_lshl_add_u64 v[164:165], v[164:165], 0, v[148:149]
	s_andn2_b64 vcc, exec, s[0:1]
	s_mov_b64 s[0:1], -1
	s_waitcnt vmcnt(7)
	v_lshlrev_b32_e32 v166, 16, v190
	v_and_b32_e32 v167, 0xffff0000, v190
	v_lshlrev_b32_e32 v158, 16, v191
	v_and_b32_e32 v159, 0xffff0000, v191
	v_lshlrev_b32_e32 v168, 16, v192
	v_and_b32_e32 v169, 0xffff0000, v192
	v_lshlrev_b32_e32 v160, 16, v193
	v_and_b32_e32 v161, 0xffff0000, v193
	global_load_dwordx4 v[190:193], v[222:223], off
	v_pk_mul_f32 v[126:127], v[126:127], v[166:167]
	v_pk_mul_f32 v[128:129], v[128:129], v[158:159]
	v_pk_mul_f32 v[158:159], v[122:123], v[168:169]
	v_pk_mul_f32 v[160:161], v[124:125], v[160:161]
	v_cvt_pk_bf16_f32 v122, v126, v127
	v_cvt_pk_bf16_f32 v123, v128, v129
	v_cvt_pk_bf16_f32 v124, v158, v159
	v_cvt_pk_bf16_f32 v125, v160, v161
	global_store_dwordx4 v[164:165], v[122:125], off
	s_nop 0
	v_or_b32_e32 v126, 16, v150
	v_ashrrev_i32_e32 v127, 31, v126
	v_lshlrev_b64 v[128:129], 13, v[126:127]
	v_lshl_add_u64 v[128:129], s[64:65], 0, v[128:129]
	v_lshl_add_u64 v[128:129], v[128:129], 0, v[148:149]
	s_waitcnt vmcnt(8)
	v_lshlrev_b32_e32 v158, 16, v194
	v_and_b32_e32 v159, 0xffff0000, v194
	v_lshlrev_b32_e32 v122, 16, v195
	v_and_b32_e32 v123, 0xffff0000, v195
	v_lshlrev_b32_e32 v160, 16, v196
	v_and_b32_e32 v161, 0xffff0000, v196
	v_lshlrev_b32_e32 v124, 16, v197
	v_and_b32_e32 v125, 0xffff0000, v197
	global_load_dwordx4 v[194:197], v[222:223], off offset:256
	v_pk_mul_f32 v[118:119], v[118:119], v[158:159]
	v_pk_mul_f32 v[120:121], v[120:121], v[122:123]
	v_pk_mul_f32 v[122:123], v[114:115], v[160:161]
	v_pk_mul_f32 v[124:125], v[116:117], v[124:125]
	v_cvt_pk_bf16_f32 v114, v118, v119
	v_cvt_pk_bf16_f32 v115, v120, v121
	v_cvt_pk_bf16_f32 v116, v122, v123
	v_cvt_pk_bf16_f32 v117, v124, v125
	global_store_dwordx4 v[164:165], v[114:117], off offset:256
	s_nop 0
	v_lshlrev_b64 v[118:119], 12, v[126:127]
	v_lshl_add_u64 v[118:119], s[54:55], 0, v[118:119]
	v_lshl_add_u64 v[118:119], v[118:119], 0, v[148:149]
	s_waitcnt vmcnt(9)
	v_lshlrev_b32_e32 v120, 16, v198
	v_and_b32_e32 v121, 0xffff0000, v198
	v_lshlrev_b32_e32 v114, 16, v199
	v_and_b32_e32 v115, 0xffff0000, v199
	v_lshlrev_b32_e32 v122, 16, v200
	v_and_b32_e32 v123, 0xffff0000, v200
	v_lshlrev_b32_e32 v116, 16, v201
	v_and_b32_e32 v117, 0xffff0000, v201
	global_load_dwordx4 v[198:201], v[224:225], off
	v_pk_mul_f32 v[110:111], v[110:111], v[120:121]
	v_pk_mul_f32 v[112:113], v[112:113], v[114:115]
	v_pk_mul_f32 v[114:115], v[106:107], v[122:123]
	v_pk_mul_f32 v[116:117], v[108:109], v[116:117]
	v_cvt_pk_bf16_f32 v106, v110, v111
	v_cvt_pk_bf16_f32 v107, v112, v113
	v_cvt_pk_bf16_f32 v108, v114, v115
	v_cvt_pk_bf16_f32 v109, v116, v117
	global_store_dwordx4 v[118:119], v[106:109], off
	s_nop 0
	v_or_b32_e32 v110, 32, v150
	v_ashrrev_i32_e32 v111, 31, v110
	v_lshlrev_b64 v[112:113], 13, v[110:111]
	v_lshl_add_u64 v[112:113], s[64:65], 0, v[112:113]
	v_lshl_add_u64 v[112:113], v[112:113], 0, v[148:149]
	s_waitcnt vmcnt(10)
	v_lshlrev_b32_e32 v114, 16, v202
	v_and_b32_e32 v115, 0xffff0000, v202
	v_lshlrev_b32_e32 v106, 16, v203
	v_and_b32_e32 v107, 0xffff0000, v203
	v_lshlrev_b32_e32 v116, 16, v204
	v_and_b32_e32 v117, 0xffff0000, v204
	v_lshlrev_b32_e32 v108, 16, v205
	v_and_b32_e32 v109, 0xffff0000, v205
	global_load_dwordx4 v[202:205], v[224:225], off offset:256
	v_pk_mul_f32 v[102:103], v[102:103], v[114:115]
	v_pk_mul_f32 v[104:105], v[104:105], v[106:107]
	v_pk_mul_f32 v[106:107], v[98:99], v[116:117]
	v_pk_mul_f32 v[108:109], v[100:101], v[108:109]
	v_cvt_pk_bf16_f32 v98, v102, v103
	v_cvt_pk_bf16_f32 v99, v104, v105
	v_cvt_pk_bf16_f32 v100, v106, v107
	v_cvt_pk_bf16_f32 v101, v108, v109
	global_store_dwordx4 v[118:119], v[98:101], off offset:256
	s_nop 0
	v_lshlrev_b64 v[102:103], 12, v[110:111]
	v_lshl_add_u64 v[102:103], s[54:55], 0, v[102:103]
	v_lshl_add_u64 v[102:103], v[102:103], 0, v[148:149]
	s_waitcnt vmcnt(11)
	v_lshlrev_b32_e32 v104, 16, v206
	v_and_b32_e32 v105, 0xffff0000, v206
	v_lshlrev_b32_e32 v98, 16, v207
	v_and_b32_e32 v99, 0xffff0000, v207
	v_lshlrev_b32_e32 v106, 16, v208
	v_and_b32_e32 v107, 0xffff0000, v208
	v_lshlrev_b32_e32 v100, 16, v209
	v_and_b32_e32 v101, 0xffff0000, v209
	global_load_dwordx4 v[206:209], v[226:227], off
	v_pk_mul_f32 v[94:95], v[94:95], v[104:105]
	v_pk_mul_f32 v[96:97], v[96:97], v[98:99]
	v_pk_mul_f32 v[98:99], v[90:91], v[106:107]
	v_pk_mul_f32 v[100:101], v[92:93], v[100:101]
	v_cvt_pk_bf16_f32 v90, v94, v95
	v_cvt_pk_bf16_f32 v91, v96, v97
	v_cvt_pk_bf16_f32 v92, v98, v99
	v_cvt_pk_bf16_f32 v93, v100, v101
	global_store_dwordx4 v[102:103], v[90:93], off
	s_nop 0
	v_or_b32_e32 v94, 48, v150
	v_ashrrev_i32_e32 v95, 31, v94
	v_lshlrev_b64 v[96:97], 13, v[94:95]
	v_lshl_add_u64 v[96:97], s[64:65], 0, v[96:97]
	v_lshl_add_u64 v[96:97], v[96:97], 0, v[148:149]
	s_waitcnt vmcnt(12)
	v_lshlrev_b32_e32 v98, 16, v210
	v_and_b32_e32 v99, 0xffff0000, v210
	v_lshlrev_b32_e32 v90, 16, v211
	v_and_b32_e32 v91, 0xffff0000, v211
	v_lshlrev_b32_e32 v100, 16, v212
	v_and_b32_e32 v101, 0xffff0000, v212
	v_lshlrev_b32_e32 v92, 16, v213
	v_and_b32_e32 v93, 0xffff0000, v213
	global_load_dwordx4 v[210:213], v[226:227], off offset:256
	v_pk_mul_f32 v[86:87], v[86:87], v[98:99]
	v_pk_mul_f32 v[88:89], v[88:89], v[90:91]
	v_pk_mul_f32 v[90:91], v[82:83], v[100:101]
	v_pk_mul_f32 v[92:93], v[84:85], v[92:93]
	v_cvt_pk_bf16_f32 v82, v86, v87
	v_cvt_pk_bf16_f32 v83, v88, v89
	v_cvt_pk_bf16_f32 v84, v90, v91
	v_cvt_pk_bf16_f32 v85, v92, v93
	global_store_dwordx4 v[102:103], v[82:85], off offset:256
	s_nop 0
	v_lshlrev_b64 v[86:87], 12, v[94:95]
	v_lshl_add_u64 v[86:87], s[54:55], 0, v[86:87]
	v_lshl_add_u64 v[86:87], v[86:87], 0, v[148:149]
	s_waitcnt vmcnt(13)
	v_lshlrev_b32_e32 v88, 16, v214
	v_and_b32_e32 v89, 0xffff0000, v214
	v_lshlrev_b32_e32 v82, 16, v215
	v_and_b32_e32 v83, 0xffff0000, v215
	v_lshlrev_b32_e32 v90, 16, v216
	v_and_b32_e32 v91, 0xffff0000, v216
	v_lshlrev_b32_e32 v84, 16, v217
	v_and_b32_e32 v85, 0xffff0000, v217
	global_load_dwordx4 v[214:217], v[228:229], off
	v_pk_mul_f32 v[78:79], v[78:79], v[88:89]
	v_pk_mul_f32 v[80:81], v[80:81], v[82:83]
	v_pk_mul_f32 v[82:83], v[74:75], v[90:91]
	v_pk_mul_f32 v[84:85], v[76:77], v[84:85]
	v_cvt_pk_bf16_f32 v74, v78, v79
	v_cvt_pk_bf16_f32 v75, v80, v81
	v_cvt_pk_bf16_f32 v76, v82, v83
	v_cvt_pk_bf16_f32 v77, v84, v85
	global_store_dwordx4 v[86:87], v[74:77], off
	s_nop 0
	v_add_u32_e32 v78, 0x80, v150
	v_ashrrev_i32_e32 v79, 31, v78
	v_lshlrev_b64 v[80:81], 13, v[78:79]
	v_lshl_add_u64 v[80:81], s[64:65], 0, v[80:81]
	v_lshl_add_u64 v[80:81], v[80:81], 0, v[148:149]
	s_waitcnt vmcnt(14)
	v_lshlrev_b32_e32 v82, 16, v218
	v_and_b32_e32 v83, 0xffff0000, v218
	v_lshlrev_b32_e32 v74, 16, v219
	v_and_b32_e32 v75, 0xffff0000, v219
	v_lshlrev_b32_e32 v84, 16, v220
	v_and_b32_e32 v85, 0xffff0000, v220
	v_lshlrev_b32_e32 v76, 16, v221
	v_and_b32_e32 v77, 0xffff0000, v221
	global_load_dwordx4 v[218:221], v[228:229], off offset:256
	v_pk_mul_f32 v[70:71], v[70:71], v[82:83]
	v_pk_mul_f32 v[72:73], v[72:73], v[74:75]
	v_pk_mul_f32 v[74:75], v[66:67], v[84:85]
	v_pk_mul_f32 v[76:77], v[68:69], v[76:77]
	v_cvt_pk_bf16_f32 v66, v70, v71
	v_cvt_pk_bf16_f32 v67, v72, v73
	v_cvt_pk_bf16_f32 v68, v74, v75
	v_cvt_pk_bf16_f32 v69, v76, v77
	global_store_dwordx4 v[86:87], v[66:69], off offset:256
	s_nop 0
	v_lshlrev_b64 v[70:71], 12, v[78:79]
	v_lshl_add_u64 v[70:71], s[54:55], 0, v[70:71]
	v_lshl_add_u64 v[70:71], v[70:71], 0, v[148:149]
	s_waitcnt vmcnt(15)
	v_lshlrev_b32_e32 v72, 16, v190
	v_and_b32_e32 v73, 0xffff0000, v190
	v_lshlrev_b32_e32 v66, 16, v191
	v_and_b32_e32 v67, 0xffff0000, v191
	v_lshlrev_b32_e32 v74, 16, v192
	v_and_b32_e32 v75, 0xffff0000, v192
	v_lshlrev_b32_e32 v68, 16, v193
	v_and_b32_e32 v69, 0xffff0000, v193
	v_pk_mul_f32 v[62:63], v[62:63], v[72:73]
	v_pk_mul_f32 v[64:65], v[64:65], v[66:67]
	v_pk_mul_f32 v[66:67], v[58:59], v[74:75]
	v_pk_mul_f32 v[68:69], v[60:61], v[68:69]
	v_cvt_pk_bf16_f32 v58, v62, v63
	v_cvt_pk_bf16_f32 v59, v64, v65
	v_cvt_pk_bf16_f32 v60, v66, v67
	v_cvt_pk_bf16_f32 v61, v68, v69
	global_store_dwordx4 v[70:71], v[58:61], off
	s_nop 0
	v_add_u32_e32 v62, 0x90, v150
	v_ashrrev_i32_e32 v63, 31, v62
	v_lshlrev_b64 v[64:65], 13, v[62:63]
	v_lshl_add_u64 v[64:65], s[64:65], 0, v[64:65]
	v_lshl_add_u64 v[64:65], v[64:65], 0, v[148:149]
	s_waitcnt vmcnt(14)
	v_lshlrev_b32_e32 v66, 16, v194
	v_and_b32_e32 v67, 0xffff0000, v194
	v_lshlrev_b32_e32 v58, 16, v195
	v_and_b32_e32 v59, 0xffff0000, v195
	v_lshlrev_b32_e32 v68, 16, v196
	v_and_b32_e32 v69, 0xffff0000, v196
	v_lshlrev_b32_e32 v60, 16, v197
	v_and_b32_e32 v61, 0xffff0000, v197
	v_pk_mul_f32 v[54:55], v[54:55], v[66:67]
	v_pk_mul_f32 v[56:57], v[56:57], v[58:59]
	v_pk_mul_f32 v[58:59], v[50:51], v[68:69]
	v_pk_mul_f32 v[60:61], v[52:53], v[60:61]
	v_cvt_pk_bf16_f32 v50, v54, v55
	v_cvt_pk_bf16_f32 v51, v56, v57
	v_cvt_pk_bf16_f32 v52, v58, v59
	v_cvt_pk_bf16_f32 v53, v60, v61
	global_store_dwordx4 v[70:71], v[50:53], off offset:256
	s_nop 0
	v_lshlrev_b64 v[54:55], 12, v[62:63]
	v_lshl_add_u64 v[54:55], s[54:55], 0, v[54:55]
	v_lshl_add_u64 v[54:55], v[54:55], 0, v[148:149]
	s_waitcnt vmcnt(13)
	v_lshlrev_b32_e32 v56, 16, v198
	v_and_b32_e32 v57, 0xffff0000, v198
	v_lshlrev_b32_e32 v50, 16, v199
	v_and_b32_e32 v51, 0xffff0000, v199
	v_lshlrev_b32_e32 v58, 16, v200
	v_and_b32_e32 v59, 0xffff0000, v200
	v_lshlrev_b32_e32 v52, 16, v201
	v_and_b32_e32 v53, 0xffff0000, v201
	v_pk_mul_f32 v[46:47], v[46:47], v[56:57]
	v_pk_mul_f32 v[48:49], v[48:49], v[50:51]
	v_pk_mul_f32 v[50:51], v[42:43], v[58:59]
	v_pk_mul_f32 v[52:53], v[44:45], v[52:53]
	v_cvt_pk_bf16_f32 v42, v46, v47
	v_cvt_pk_bf16_f32 v43, v48, v49
	v_cvt_pk_bf16_f32 v44, v50, v51
	v_cvt_pk_bf16_f32 v45, v52, v53
	global_store_dwordx4 v[54:55], v[42:45], off
	s_nop 0
	v_add_u32_e32 v46, 0xa0, v150
	v_ashrrev_i32_e32 v47, 31, v46
	v_lshlrev_b64 v[48:49], 13, v[46:47]
	v_lshl_add_u64 v[48:49], s[64:65], 0, v[48:49]
	v_lshl_add_u64 v[48:49], v[48:49], 0, v[148:149]
	s_waitcnt vmcnt(12)
	v_lshlrev_b32_e32 v50, 16, v202
	v_and_b32_e32 v51, 0xffff0000, v202
	v_lshlrev_b32_e32 v42, 16, v203
	v_and_b32_e32 v43, 0xffff0000, v203
	v_lshlrev_b32_e32 v52, 16, v204
	v_and_b32_e32 v53, 0xffff0000, v204
	v_lshlrev_b32_e32 v44, 16, v205
	v_and_b32_e32 v45, 0xffff0000, v205
	v_pk_mul_f32 v[38:39], v[38:39], v[50:51]
	v_pk_mul_f32 v[40:41], v[40:41], v[42:43]
	v_pk_mul_f32 v[42:43], v[34:35], v[52:53]
	v_pk_mul_f32 v[44:45], v[36:37], v[44:45]
	v_cvt_pk_bf16_f32 v34, v38, v39
	v_cvt_pk_bf16_f32 v35, v40, v41
	v_cvt_pk_bf16_f32 v36, v42, v43
	v_cvt_pk_bf16_f32 v37, v44, v45
	global_store_dwordx4 v[54:55], v[34:37], off offset:256
	s_nop 0
	v_lshlrev_b64 v[38:39], 12, v[46:47]
	v_lshl_add_u64 v[38:39], s[54:55], 0, v[38:39]
	v_lshl_add_u64 v[38:39], v[38:39], 0, v[148:149]
	s_waitcnt vmcnt(11)
	v_lshlrev_b32_e32 v40, 16, v206
	v_and_b32_e32 v41, 0xffff0000, v206
	v_lshlrev_b32_e32 v34, 16, v207
	v_and_b32_e32 v35, 0xffff0000, v207
	v_lshlrev_b32_e32 v42, 16, v208
	v_and_b32_e32 v43, 0xffff0000, v208
	v_lshlrev_b32_e32 v36, 16, v209
	v_and_b32_e32 v37, 0xffff0000, v209
	v_pk_mul_f32 v[30:31], v[30:31], v[40:41]
	v_pk_mul_f32 v[32:33], v[32:33], v[34:35]
	v_pk_mul_f32 v[34:35], v[26:27], v[42:43]
	v_pk_mul_f32 v[36:37], v[28:29], v[36:37]
	v_cvt_pk_bf16_f32 v26, v30, v31
	v_cvt_pk_bf16_f32 v27, v32, v33
	v_cvt_pk_bf16_f32 v28, v34, v35
	v_cvt_pk_bf16_f32 v29, v36, v37
	global_store_dwordx4 v[38:39], v[26:29], off
	s_nop 0
	v_add_u32_e32 v30, 0xb0, v150
	v_ashrrev_i32_e32 v31, 31, v30
	v_lshlrev_b64 v[32:33], 13, v[30:31]
	v_lshl_add_u64 v[32:33], s[64:65], 0, v[32:33]
	v_lshl_add_u64 v[32:33], v[32:33], 0, v[148:149]
	s_waitcnt vmcnt(10)
	v_lshlrev_b32_e32 v34, 16, v210
	v_and_b32_e32 v35, 0xffff0000, v210
	v_lshlrev_b32_e32 v26, 16, v211
	v_and_b32_e32 v27, 0xffff0000, v211
	v_lshlrev_b32_e32 v36, 16, v212
	v_and_b32_e32 v37, 0xffff0000, v212
	v_lshlrev_b32_e32 v28, 16, v213
	v_and_b32_e32 v29, 0xffff0000, v213
	v_pk_mul_f32 v[22:23], v[22:23], v[34:35]
	v_pk_mul_f32 v[24:25], v[24:25], v[26:27]
	v_pk_mul_f32 v[26:27], v[18:19], v[36:37]
	v_pk_mul_f32 v[28:29], v[20:21], v[28:29]
	v_cvt_pk_bf16_f32 v18, v22, v23
	v_cvt_pk_bf16_f32 v19, v24, v25
	v_cvt_pk_bf16_f32 v20, v26, v27
	v_cvt_pk_bf16_f32 v21, v28, v29
	global_store_dwordx4 v[38:39], v[18:21], off offset:256
	s_nop 0
	v_lshlrev_b64 v[22:23], 12, v[30:31]
	v_lshl_add_u64 v[22:23], s[54:55], 0, v[22:23]
	v_lshl_add_u64 v[22:23], v[22:23], 0, v[148:149]
	s_waitcnt vmcnt(9)
	v_lshlrev_b32_e32 v24, 16, v214
	v_and_b32_e32 v25, 0xffff0000, v214
	v_lshlrev_b32_e32 v18, 16, v215
	v_and_b32_e32 v19, 0xffff0000, v215
	v_lshlrev_b32_e32 v26, 16, v216
	v_and_b32_e32 v27, 0xffff0000, v216
	v_lshlrev_b32_e32 v20, 16, v217
	v_and_b32_e32 v21, 0xffff0000, v217
	v_pk_mul_f32 v[14:15], v[14:15], v[24:25]
	v_pk_mul_f32 v[16:17], v[16:17], v[18:19]
	v_pk_mul_f32 v[18:19], v[10:11], v[26:27]
	v_pk_mul_f32 v[20:21], v[12:13], v[20:21]
	v_cvt_pk_bf16_f32 v10, v14, v15
	v_cvt_pk_bf16_f32 v11, v16, v17
	v_cvt_pk_bf16_f32 v12, v18, v19
	v_cvt_pk_bf16_f32 v13, v20, v21
	global_store_dwordx4 v[22:23], v[10:13], off
	s_nop 0
	s_waitcnt vmcnt(8)
	v_lshlrev_b32_e32 v14, 16, v218
	v_and_b32_e32 v15, 0xffff0000, v218
	v_lshlrev_b32_e32 v10, 16, v219
	v_and_b32_e32 v11, 0xffff0000, v219
	v_lshlrev_b32_e32 v16, 16, v220
	v_and_b32_e32 v17, 0xffff0000, v220
	v_lshlrev_b32_e32 v12, 16, v221
	v_and_b32_e32 v13, 0xffff0000, v221
	v_pk_mul_f32 v[6:7], v[6:7], v[14:15]
	v_pk_mul_f32 v[8:9], v[8:9], v[10:11]
	v_pk_mul_f32 v[10:11], v[2:3], v[16:17]
	v_pk_mul_f32 v[12:13], v[4:5], v[12:13]
	v_cvt_pk_bf16_f32 v2, v6, v7
	v_cvt_pk_bf16_f32 v3, v8, v9
	v_cvt_pk_bf16_f32 v4, v10, v11
	v_cvt_pk_bf16_f32 v5, v12, v13
	global_store_dwordx4 v[22:23], v[2:5], off offset:256
	s_cbranch_vccnz .LBB0_982
	s_andn2_b64 vcc, exec, s[2:3]
	s_cbranch_vccnz .LBB0_981
	s_branch .LBB0_981

.LBB0_1053:
	s_ashr_i32 s17, s16, 31
	s_lshl_b64 s[18:19], s[16:17], 19
	s_add_u32 s18, s70, s18
	s_addc_u32 s19, s58, s19
	s_and_b64 s[20:21], s[4:5], exec
	s_cselect_b32 s17, s19, s25
	s_cselect_b32 s46, s18, s24
	s_ashr_i32 s15, s14, 31
	s_lshl_b64 s[20:21], s[14:15], 19
	s_add_u32 s20, s68, s20
	s_addc_u32 s21, s69, s21
	s_and_b64 s[28:29], s[4:5], exec
	s_cselect_b32 s15, s21, s27
	s_cselect_b32 s47, s20, s26
	s_add_u32 s24, s24, 0x40080
	s_addc_u32 s25, s25, 0
	s_add_u32 s48, s26, 0x100
	v_mov_b32_e32 v10, 0
	s_addc_u32 s49, s27, 0
	s_mov_b32 s50, -2
	v_mov_b32_e32 v11, v10
	v_mov_b32_e32 v12, v10
	v_mov_b32_e32 v13, v10
	v_mov_b32_e32 v14, v10
	v_mov_b32_e32 v15, v10
	v_mov_b32_e32 v16, v10
	v_mov_b32_e32 v17, v10
	v_mov_b32_e32 v26, v10
	v_mov_b32_e32 v27, v10
	v_mov_b32_e32 v28, v10
	v_mov_b32_e32 v29, v10
	v_mov_b32_e32 v30, v10
	v_mov_b32_e32 v31, v10
	v_mov_b32_e32 v32, v10
	v_mov_b32_e32 v33, v10
	v_mov_b32_e32 v42, v10
	v_mov_b32_e32 v43, v10
	v_mov_b32_e32 v44, v10
	v_mov_b32_e32 v45, v10
	v_mov_b32_e32 v46, v10
	v_mov_b32_e32 v47, v10
	v_mov_b32_e32 v48, v10
	v_mov_b32_e32 v49, v10
	v_mov_b32_e32 v58, v10
	v_mov_b32_e32 v59, v10
	v_mov_b32_e32 v60, v10
	v_mov_b32_e32 v61, v10
	v_mov_b32_e32 v62, v10
	v_mov_b32_e32 v63, v10
	v_mov_b32_e32 v64, v10
	v_mov_b32_e32 v65, v10
	v_mov_b32_e32 v2, v10
	v_mov_b32_e32 v3, v10
	v_mov_b32_e32 v4, v10
	v_mov_b32_e32 v5, v10
	v_mov_b32_e32 v6, v10
	v_mov_b32_e32 v7, v10
	v_mov_b32_e32 v8, v10
	v_mov_b32_e32 v9, v10
	s_waitcnt vmcnt(0)
	v_mov_b32_e32 v18, v10
	v_mov_b32_e32 v19, v10
	v_mov_b32_e32 v20, v10
	v_mov_b32_e32 v21, v10
	v_mov_b32_e32 v22, v10
	v_mov_b32_e32 v23, v10
	v_mov_b32_e32 v24, v10
	v_mov_b32_e32 v25, v10
	v_mov_b32_e32 v34, v10
	v_mov_b32_e32 v35, v10
	v_mov_b32_e32 v36, v10
	v_mov_b32_e32 v37, v10
	v_mov_b32_e32 v38, v10
	v_mov_b32_e32 v39, v10
	v_mov_b32_e32 v40, v10
	v_mov_b32_e32 v41, v10
	v_mov_b32_e32 v50, v10
	v_mov_b32_e32 v51, v10
	v_mov_b32_e32 v52, v10
	v_mov_b32_e32 v53, v10
	v_mov_b32_e32 v54, v10
	v_mov_b32_e32 v55, v10
	v_mov_b32_e32 v56, v10
	v_mov_b32_e32 v57, v10
	v_mov_b32_e32 v74, v10
	v_mov_b32_e32 v75, v10
	v_mov_b32_e32 v76, v10
	v_mov_b32_e32 v77, v10
	v_mov_b32_e32 v78, v10
	v_mov_b32_e32 v79, v10
	v_mov_b32_e32 v80, v10
	v_mov_b32_e32 v81, v10
	v_mov_b32_e32 v90, v10
	v_mov_b32_e32 v91, v10
	v_mov_b32_e32 v92, v10
	v_mov_b32_e32 v93, v10
	v_mov_b32_e32 v94, v10
	v_mov_b32_e32 v95, v10
	v_mov_b32_e32 v96, v10
	v_mov_b32_e32 v97, v10
	v_mov_b32_e32 v106, v10
	v_mov_b32_e32 v107, v10
	v_mov_b32_e32 v108, v10
	v_mov_b32_e32 v109, v10
	v_mov_b32_e32 v110, v10
	v_mov_b32_e32 v111, v10
	v_mov_b32_e32 v112, v10
	v_mov_b32_e32 v113, v10
	v_mov_b32_e32 v122, v10
	v_mov_b32_e32 v123, v10
	v_mov_b32_e32 v124, v10
	v_mov_b32_e32 v125, v10
	v_mov_b32_e32 v126, v10
	v_mov_b32_e32 v127, v10
	v_mov_b32_e32 v128, v10
	v_mov_b32_e32 v129, v10
	v_mov_b32_e32 v66, v10
	v_mov_b32_e32 v67, v10
	v_mov_b32_e32 v68, v10
	v_mov_b32_e32 v69, v10
	v_mov_b32_e32 v70, v10
	v_mov_b32_e32 v71, v10
	v_mov_b32_e32 v72, v10
	v_mov_b32_e32 v73, v10
	v_mov_b32_e32 v82, v10
	v_mov_b32_e32 v83, v10
	v_mov_b32_e32 v84, v10
	v_mov_b32_e32 v85, v10
	v_mov_b32_e32 v86, v10
	v_mov_b32_e32 v87, v10
	v_mov_b32_e32 v88, v10
	v_mov_b32_e32 v89, v10
	v_mov_b32_e32 v98, v10
	v_mov_b32_e32 v99, v10
	v_mov_b32_e32 v100, v10
	v_mov_b32_e32 v101, v10
	v_mov_b32_e32 v102, v10
	v_mov_b32_e32 v103, v10
	v_mov_b32_e32 v104, v10
	v_mov_b32_e32 v105, v10
	v_mov_b32_e32 v114, v10
	v_mov_b32_e32 v115, v10
	v_mov_b32_e32 v116, v10
	v_mov_b32_e32 v117, v10
	v_mov_b32_e32 v118, v10
	v_mov_b32_e32 v119, v10
	v_mov_b32_e32 v120, v10
	v_mov_b32_e32 v121, v10
	s_cmp_lt_u32 s37, 2
	s_cbranch_scc1 .Lp6_norestore
	s_andn2_b64 vcc, exec, s[0:1]
	s_cbranch_vccnz .Lp6_norestore
	s_barrier
.Lp6_norestore:
.LBB0_1054:
	ds_read_b128 v[148:151], v155
	ds_read_b128 v[158:161], v155 offset:1024
	ds_read_b128 v[162:165], v155 offset:2048
	ds_read_b128 v[166:169], v155 offset:3072
	ds_read_b128 v[170:173], v156
	ds_read_b128 v[174:177], v156 offset:1024
	ds_read_b128 v[180:183], v156 offset:2048
	ds_read_b128 v[184:187], v156 offset:3072
	s_add_u32 s26, s24, 0xfffc0080
	s_addc_u32 s27, s25, -1
	s_cmp_eq_u32 s50, 12
	s_cselect_b32 s29, s17, s27
	s_cselect_b32 s28, s46, s26
	s_cselect_b32 s27, s15, s49
	s_cselect_b32 s26, s47, s48
	v_lshl_add_u64 v[220:221], s[24:25], 0, v[138:139]
	s_add_i32 m0, s23, 0xc000
	ds_read_b128 v[188:191], v157
	ds_read_b128 v[192:195], v157 offset:1024
	ds_read_b128 v[196:199], v157 offset:2048
	ds_read_b128 v[200:203], v157 offset:3072
	ds_read_b128 v[204:207], v157 offset:4096
	ds_read_b128 v[208:211], v157 offset:5120
	ds_read_b128 v[212:215], v157 offset:6144
	ds_read_b128 v[216:219], v157 offset:7168
	global_load_lds_dwordx4 v[220:221], off
	v_lshl_add_u64 v[220:221], s[24:25], 0, v[140:141]
	s_add_i32 m0, s23, 0xe000
	s_nop 0
	global_load_lds_dwordx4 v[220:221], off
	s_waitcnt vmcnt(8)
	s_waitcnt lgkmcnt(0)
	s_setprio 1
	s_barrier
	v_mfma_f32_16x16x32_bf16 v[118:121], v[148:151], v[188:191], v[118:121]
	v_mfma_f32_16x16x32_bf16 v[114:117], v[162:165], v[188:191], v[114:117]
	v_mfma_f32_16x16x32_bf16 v[102:105], v[148:151], v[196:199], v[102:105]
	v_mfma_f32_16x16x32_bf16 v[98:101], v[162:165], v[196:199], v[98:101]
	v_mfma_f32_16x16x32_bf16 v[86:89], v[148:151], v[204:207], v[86:89]
	v_mfma_f32_16x16x32_bf16 v[82:85], v[162:165], v[204:207], v[82:85]
	v_mfma_f32_16x16x32_bf16 v[70:73], v[148:151], v[212:215], v[70:73]
	v_mfma_f32_16x16x32_bf16 v[66:69], v[162:165], v[212:215], v[66:69]
	v_mfma_f32_16x16x32_bf16 v[118:121], v[158:161], v[192:195], v[118:121]
	v_mfma_f32_16x16x32_bf16 v[114:117], v[166:169], v[192:195], v[114:117]
	v_mfma_f32_16x16x32_bf16 v[102:105], v[158:161], v[200:203], v[102:105]
	v_mfma_f32_16x16x32_bf16 v[98:101], v[166:169], v[200:203], v[98:101]
	v_mfma_f32_16x16x32_bf16 v[86:89], v[158:161], v[208:211], v[86:89]
	v_mfma_f32_16x16x32_bf16 v[82:85], v[166:169], v[208:211], v[82:85]
	v_mfma_f32_16x16x32_bf16 v[70:73], v[158:161], v[216:219], v[70:73]
	v_mfma_f32_16x16x32_bf16 v[66:69], v[166:169], v[216:219], v[66:69]
	v_mfma_f32_16x16x32_bf16 v[126:129], v[170:173], v[188:191], v[126:129]
	v_mfma_f32_16x16x32_bf16 v[122:125], v[180:183], v[188:191], v[122:125]
	v_mfma_f32_16x16x32_bf16 v[110:113], v[170:173], v[196:199], v[110:113]
	v_mfma_f32_16x16x32_bf16 v[106:109], v[180:183], v[196:199], v[106:109]
	v_mfma_f32_16x16x32_bf16 v[94:97], v[170:173], v[204:207], v[94:97]
	v_mfma_f32_16x16x32_bf16 v[90:93], v[180:183], v[204:207], v[90:93]
	v_mfma_f32_16x16x32_bf16 v[78:81], v[170:173], v[212:215], v[78:81]
	v_mfma_f32_16x16x32_bf16 v[74:77], v[180:183], v[212:215], v[74:77]
	v_mfma_f32_16x16x32_bf16 v[126:129], v[174:177], v[192:195], v[126:129]
	v_mfma_f32_16x16x32_bf16 v[122:125], v[184:187], v[192:195], v[122:125]
	v_mfma_f32_16x16x32_bf16 v[110:113], v[174:177], v[200:203], v[110:113]
	v_mfma_f32_16x16x32_bf16 v[106:109], v[184:187], v[200:203], v[106:109]
	v_mfma_f32_16x16x32_bf16 v[94:97], v[174:177], v[208:211], v[94:97]
	v_mfma_f32_16x16x32_bf16 v[90:93], v[184:187], v[208:211], v[90:93]
	v_mfma_f32_16x16x32_bf16 v[78:81], v[174:177], v[216:219], v[78:81]
	v_mfma_f32_16x16x32_bf16 v[74:77], v[184:187], v[216:219], v[74:77]
	s_barrier
	s_setprio 0
	s_add_i32 s51, s42, s30
	v_lshl_add_u64 v[220:221], s[26:27], 0, v[134:135]
	s_mov_b32 m0, s51
	ds_read_b128 v[188:191], v157 offset:16384
	ds_read_b128 v[192:195], v157 offset:17408
	ds_read_b128 v[196:199], v157 offset:18432
	ds_read_b128 v[200:203], v157 offset:19456
	ds_read_b128 v[204:207], v157 offset:20480
	ds_read_b128 v[208:211], v157 offset:21504
	ds_read_b128 v[212:215], v157 offset:22528
	ds_read_b128 v[216:219], v157 offset:23552
	global_load_lds_dwordx4 v[220:221], off
	s_add_i32 m0, s51, 0x2000
	s_add_u32 s56, s26, 0x40000
	v_lshl_add_u64 v[222:223], s[26:27], 0, v[130:131]
	s_addc_u32 s57, s27, 0
	s_add_i32 s51, s43, s30
	global_load_lds_dwordx4 v[222:223], off
	v_lshl_add_u64 v[224:225], s[56:57], 0, v[134:135]
	s_mov_b32 m0, s51
	v_lshl_add_u64 v[226:227], s[28:29], 0, v[132:133]
	global_load_lds_dwordx4 v[224:225], off
	v_lshl_add_u64 v[224:225], s[56:57], 0, v[130:131]
	s_add_i32 m0, s51, 0x2000
	s_nop 0
	global_load_lds_dwordx4 v[224:225], off
	v_lshl_add_u64 v[224:225], s[28:29], 0, v[136:137]
	s_mov_b32 m0, s23
	s_nop 0
	global_load_lds_dwordx4 v[224:225], off
	s_mov_b32 m0, s34
	s_nop 0
	global_load_lds_dwordx4 v[226:227], off
	s_waitcnt vmcnt(8)
	s_waitcnt lgkmcnt(0)
	s_setprio 1
	s_barrier
	v_mfma_f32_16x16x32_bf16 v[54:57], v[148:151], v[188:191], v[54:57]
	v_mfma_f32_16x16x32_bf16 v[50:53], v[162:165], v[188:191], v[50:53]
	v_mfma_f32_16x16x32_bf16 v[38:41], v[148:151], v[196:199], v[38:41]
	v_mfma_f32_16x16x32_bf16 v[34:37], v[162:165], v[196:199], v[34:37]
	v_mfma_f32_16x16x32_bf16 v[22:25], v[148:151], v[204:207], v[22:25]
	v_mfma_f32_16x16x32_bf16 v[18:21], v[162:165], v[204:207], v[18:21]
	v_mfma_f32_16x16x32_bf16 v[6:9], v[148:151], v[212:215], v[6:9]
	v_mfma_f32_16x16x32_bf16 v[2:5], v[162:165], v[212:215], v[2:5]
	v_mfma_f32_16x16x32_bf16 v[54:57], v[158:161], v[192:195], v[54:57]
	v_mfma_f32_16x16x32_bf16 v[50:53], v[166:169], v[192:195], v[50:53]
	v_mfma_f32_16x16x32_bf16 v[38:41], v[158:161], v[200:203], v[38:41]
	v_mfma_f32_16x16x32_bf16 v[34:37], v[166:169], v[200:203], v[34:37]
	v_mfma_f32_16x16x32_bf16 v[22:25], v[158:161], v[208:211], v[22:25]
	v_mfma_f32_16x16x32_bf16 v[18:21], v[166:169], v[208:211], v[18:21]
	v_mfma_f32_16x16x32_bf16 v[6:9], v[158:161], v[216:219], v[6:9]
	v_mfma_f32_16x16x32_bf16 v[2:5], v[166:169], v[216:219], v[2:5]
	v_mfma_f32_16x16x32_bf16 v[62:65], v[170:173], v[188:191], v[62:65]
	v_mfma_f32_16x16x32_bf16 v[58:61], v[180:183], v[188:191], v[58:61]
	v_mfma_f32_16x16x32_bf16 v[46:49], v[170:173], v[196:199], v[46:49]
	v_mfma_f32_16x16x32_bf16 v[42:45], v[180:183], v[196:199], v[42:45]
	v_mfma_f32_16x16x32_bf16 v[30:33], v[170:173], v[204:207], v[30:33]
	v_mfma_f32_16x16x32_bf16 v[26:29], v[180:183], v[204:207], v[26:29]
	v_mfma_f32_16x16x32_bf16 v[14:17], v[170:173], v[212:215], v[14:17]
	v_mfma_f32_16x16x32_bf16 v[10:13], v[180:183], v[212:215], v[10:13]
	v_mfma_f32_16x16x32_bf16 v[62:65], v[174:177], v[192:195], v[62:65]
	v_mfma_f32_16x16x32_bf16 v[58:61], v[184:187], v[192:195], v[58:61]
	v_mfma_f32_16x16x32_bf16 v[46:49], v[174:177], v[200:203], v[46:49]
	v_mfma_f32_16x16x32_bf16 v[42:45], v[184:187], v[200:203], v[42:45]
	v_mfma_f32_16x16x32_bf16 v[30:33], v[174:177], v[208:211], v[30:33]
	v_mfma_f32_16x16x32_bf16 v[26:29], v[184:187], v[208:211], v[26:29]
	v_mfma_f32_16x16x32_bf16 v[14:17], v[174:177], v[216:219], v[14:17]
	v_mfma_f32_16x16x32_bf16 v[10:13], v[184:187], v[216:219], v[10:13]
	s_barrier
	s_setprio 0
	s_add_i32 s51, 0, 0x18000
	s_add_i32 s56, 0, 0x1c000
	v_add_u32_e32 v166, s51, v153
	v_add_u32_e32 v179, s56, v153
	ds_read_b128 v[148:151], v166
	ds_read_b128 v[158:161], v166 offset:1024
	ds_read_b128 v[162:165], v166 offset:2048
	ds_read_b128 v[166:169], v166 offset:3072
	ds_read_b128 v[170:173], v179
	ds_read_b128 v[174:177], v179 offset:1024
	ds_read_b128 v[180:183], v179 offset:2048
	ds_read_b128 v[184:187], v179 offset:3072
	s_add_u32 s28, s28, 0x40000
	s_addc_u32 s29, s29, 0
	s_mov_b32 m0, s35
	v_lshl_add_u64 v[228:229], s[28:29], 0, v[136:137]
	ds_read_b128 v[188:191], v157 offset:32768
	ds_read_b128 v[192:195], v157 offset:33792
	ds_read_b128 v[196:199], v157 offset:34816
	ds_read_b128 v[200:203], v157 offset:35840
	ds_read_b128 v[204:207], v157 offset:36864
	ds_read_b128 v[208:211], v157 offset:37888
	ds_read_b128 v[212:215], v157 offset:38912
	ds_read_b128 v[216:219], v157 offset:39936
	global_load_lds_dwordx4 v[228:229], off
	v_lshl_add_u64 v[228:229], s[28:29], 0, v[132:133]
	s_mov_b32 m0, s36
	s_nop 0
	global_load_lds_dwordx4 v[228:229], off
	s_waitcnt vmcnt(8)
	s_waitcnt lgkmcnt(0)
	s_setprio 1
	s_barrier
	v_mfma_f32_16x16x32_bf16 v[118:121], v[148:151], v[188:191], v[118:121]
	v_mfma_f32_16x16x32_bf16 v[114:117], v[162:165], v[188:191], v[114:117]
	v_mfma_f32_16x16x32_bf16 v[102:105], v[148:151], v[196:199], v[102:105]
	v_mfma_f32_16x16x32_bf16 v[98:101], v[162:165], v[196:199], v[98:101]
	v_mfma_f32_16x16x32_bf16 v[86:89], v[148:151], v[204:207], v[86:89]
	v_mfma_f32_16x16x32_bf16 v[82:85], v[162:165], v[204:207], v[82:85]
	v_mfma_f32_16x16x32_bf16 v[70:73], v[148:151], v[212:215], v[70:73]
	v_mfma_f32_16x16x32_bf16 v[66:69], v[162:165], v[212:215], v[66:69]
	v_mfma_f32_16x16x32_bf16 v[118:121], v[158:161], v[192:195], v[118:121]
	v_mfma_f32_16x16x32_bf16 v[114:117], v[166:169], v[192:195], v[114:117]
	v_mfma_f32_16x16x32_bf16 v[102:105], v[158:161], v[200:203], v[102:105]
	v_mfma_f32_16x16x32_bf16 v[98:101], v[166:169], v[200:203], v[98:101]
	v_mfma_f32_16x16x32_bf16 v[86:89], v[158:161], v[208:211], v[86:89]
	v_mfma_f32_16x16x32_bf16 v[82:85], v[166:169], v[208:211], v[82:85]
	v_mfma_f32_16x16x32_bf16 v[70:73], v[158:161], v[216:219], v[70:73]
	v_mfma_f32_16x16x32_bf16 v[66:69], v[166:169], v[216:219], v[66:69]
	v_mfma_f32_16x16x32_bf16 v[126:129], v[170:173], v[188:191], v[126:129]
	v_mfma_f32_16x16x32_bf16 v[122:125], v[180:183], v[188:191], v[122:125]
	v_mfma_f32_16x16x32_bf16 v[110:113], v[170:173], v[196:199], v[110:113]
	v_mfma_f32_16x16x32_bf16 v[106:109], v[180:183], v[196:199], v[106:109]
	v_mfma_f32_16x16x32_bf16 v[94:97], v[170:173], v[204:207], v[94:97]
	v_mfma_f32_16x16x32_bf16 v[90:93], v[180:183], v[204:207], v[90:93]
	v_mfma_f32_16x16x32_bf16 v[78:81], v[170:173], v[212:215], v[78:81]
	v_mfma_f32_16x16x32_bf16 v[74:77], v[180:183], v[212:215], v[74:77]
	v_mfma_f32_16x16x32_bf16 v[126:129], v[174:177], v[192:195], v[126:129]
	v_mfma_f32_16x16x32_bf16 v[122:125], v[184:187], v[192:195], v[122:125]
	v_mfma_f32_16x16x32_bf16 v[110:113], v[174:177], v[200:203], v[110:113]
	v_mfma_f32_16x16x32_bf16 v[106:109], v[184:187], v[200:203], v[106:109]
	v_mfma_f32_16x16x32_bf16 v[94:97], v[174:177], v[208:211], v[94:97]
	v_mfma_f32_16x16x32_bf16 v[90:93], v[184:187], v[208:211], v[90:93]
	v_mfma_f32_16x16x32_bf16 v[78:81], v[174:177], v[216:219], v[78:81]
	v_mfma_f32_16x16x32_bf16 v[74:77], v[184:187], v[216:219], v[74:77]
	s_barrier
	s_setprio 0
	s_add_i32 s28, s51, s30
	v_lshl_add_u64 v[220:221], v[220:221], 0, s[2:3]
	s_mov_b32 m0, s28
	ds_read_b128 v[188:191], v157 offset:49152
	ds_read_b128 v[192:195], v157 offset:50176
	ds_read_b128 v[196:199], v157 offset:51200
	ds_read_b128 v[200:203], v157 offset:52224
	ds_read_b128 v[204:207], v157 offset:53248
	ds_read_b128 v[208:211], v157 offset:54272
	ds_read_b128 v[212:215], v157 offset:55296
	ds_read_b128 v[216:219], v157 offset:56320
	global_load_lds_dwordx4 v[220:221], off
	s_add_i32 m0, s28, 0x2000
	s_add_u32 s26, s26, 0x40080
	v_lshl_add_u64 v[220:221], v[222:223], 0, s[2:3]
	s_addc_u32 s27, s27, 0
	s_add_i32 s28, s56, s30
	global_load_lds_dwordx4 v[220:221], off
	v_lshl_add_u64 v[220:221], s[26:27], 0, v[134:135]
	s_mov_b32 m0, s28
	s_nop 0
	global_load_lds_dwordx4 v[220:221], off
	v_lshl_add_u64 v[220:221], s[26:27], 0, v[130:131]
	s_add_i32 m0, s28, 0x2000
	s_nop 0
	global_load_lds_dwordx4 v[220:221], off
	v_lshl_add_u64 v[220:221], v[224:225], 0, s[2:3]
	s_mov_b32 m0, s38
	s_nop 0
	global_load_lds_dwordx4 v[220:221], off
	v_lshl_add_u64 v[220:221], v[226:227], 0, s[2:3]
	s_mov_b32 m0, s39
	s_nop 0
	global_load_lds_dwordx4 v[220:221], off
	s_waitcnt vmcnt(8)
	s_waitcnt lgkmcnt(0)
	s_setprio 1
	s_barrier
	v_mfma_f32_16x16x32_bf16 v[54:57], v[148:151], v[188:191], v[54:57]
	v_mfma_f32_16x16x32_bf16 v[50:53], v[162:165], v[188:191], v[50:53]
	v_mfma_f32_16x16x32_bf16 v[38:41], v[148:151], v[196:199], v[38:41]
	v_mfma_f32_16x16x32_bf16 v[34:37], v[162:165], v[196:199], v[34:37]
	v_mfma_f32_16x16x32_bf16 v[22:25], v[148:151], v[204:207], v[22:25]
	v_mfma_f32_16x16x32_bf16 v[18:21], v[162:165], v[204:207], v[18:21]
	v_mfma_f32_16x16x32_bf16 v[6:9], v[148:151], v[212:215], v[6:9]
	v_mfma_f32_16x16x32_bf16 v[2:5], v[162:165], v[212:215], v[2:5]
	v_mfma_f32_16x16x32_bf16 v[54:57], v[158:161], v[192:195], v[54:57]
	v_mfma_f32_16x16x32_bf16 v[50:53], v[166:169], v[192:195], v[50:53]
	v_mfma_f32_16x16x32_bf16 v[38:41], v[158:161], v[200:203], v[38:41]
	v_mfma_f32_16x16x32_bf16 v[34:37], v[166:169], v[200:203], v[34:37]
	v_mfma_f32_16x16x32_bf16 v[22:25], v[158:161], v[208:211], v[22:25]
	v_mfma_f32_16x16x32_bf16 v[18:21], v[166:169], v[208:211], v[18:21]
	v_mfma_f32_16x16x32_bf16 v[6:9], v[158:161], v[216:219], v[6:9]
	v_mfma_f32_16x16x32_bf16 v[2:5], v[166:169], v[216:219], v[2:5]
	v_mfma_f32_16x16x32_bf16 v[62:65], v[170:173], v[188:191], v[62:65]
	v_mfma_f32_16x16x32_bf16 v[58:61], v[180:183], v[188:191], v[58:61]
	v_mfma_f32_16x16x32_bf16 v[46:49], v[170:173], v[196:199], v[46:49]
	v_mfma_f32_16x16x32_bf16 v[42:45], v[180:183], v[196:199], v[42:45]
	v_mfma_f32_16x16x32_bf16 v[30:33], v[170:173], v[204:207], v[30:33]
	v_mfma_f32_16x16x32_bf16 v[26:29], v[180:183], v[204:207], v[26:29]
	v_mfma_f32_16x16x32_bf16 v[14:17], v[170:173], v[212:215], v[14:17]
	v_mfma_f32_16x16x32_bf16 v[10:13], v[180:183], v[212:215], v[10:13]
	v_mfma_f32_16x16x32_bf16 v[62:65], v[174:177], v[192:195], v[62:65]
	v_mfma_f32_16x16x32_bf16 v[58:61], v[184:187], v[192:195], v[58:61]
	v_mfma_f32_16x16x32_bf16 v[46:49], v[174:177], v[200:203], v[46:49]
	v_mfma_f32_16x16x32_bf16 v[42:45], v[184:187], v[200:203], v[42:45]
	v_mfma_f32_16x16x32_bf16 v[30:33], v[174:177], v[208:211], v[30:33]
	v_mfma_f32_16x16x32_bf16 v[26:29], v[184:187], v[208:211], v[26:29]
	v_mfma_f32_16x16x32_bf16 v[14:17], v[174:177], v[216:219], v[14:17]
	v_mfma_f32_16x16x32_bf16 v[10:13], v[184:187], v[216:219], v[10:13]
	s_barrier
	s_setprio 0
	s_add_i32 s50, s50, 2
	s_add_u32 s24, s24, 0x100
	s_addc_u32 s25, s25, 0
	s_add_u32 s48, s48, 0x100
	s_addc_u32 s49, s49, 0
	s_cmp_gt_u32 s50, 13
	s_cbranch_scc0 .LBB0_1054
	s_and_b64 vcc, exec, s[8:9]
	s_cbranch_vccz .LBB0_1057
	s_barrier
.LBB0_1057:
	v_lshl_add_u32 v150, s22, 8, v152
	v_lshl_or_b32 v148, s45, 7, v154
	v_ashrrev_i32_e32 v151, 31, v150
	v_ashrrev_i32_e32 v149, 31, v148
	v_lshlrev_b64 v[162:163], 13, v[150:151]
	v_lshlrev_b64 v[148:149], 1, v[148:149]
	v_lshl_add_u64 v[162:163], s[64:65], 0, v[162:163]
	v_lshlrev_b64 v[158:159], 12, v[150:151]
	v_lshl_add_u64 v[162:163], v[162:163], 0, v[148:149]
	v_lshl_add_u64 v[158:159], s[54:55], 0, v[158:159]
	v_add_co_u32_e32 v162, vcc, 0x1000, v162
	v_lshl_add_u64 v[166:167], v[158:159], 0, v[148:149]
	s_nop 0
	v_addc_co_u32_e32 v163, vcc, 0, v163, vcc
	global_load_dwordx4 v[158:161], v[166:167], off
	v_mul_f32_e32 v126, 0xbfb8aa3b, v126
	global_load_dwordx4 v[162:165], v[162:163], off
	v_mul_f32_e32 v122, 0xbfb8aa3b, v122
	v_mul_f32_e32 v127, 0xbfb8aa3b, v127
	v_mul_f32_e32 v123, 0xbfb8aa3b, v123
	v_mul_f32_e32 v128, 0xbfb8aa3b, v128
	v_mul_f32_e32 v124, 0xbfb8aa3b, v124
	v_mul_f32_e32 v129, 0xbfb8aa3b, v129
	v_mul_f32_e32 v125, 0xbfb8aa3b, v125
	v_exp_f32_e32 v126, v126
	v_exp_f32_e32 v151, v122
	v_exp_f32_e32 v127, v127
	v_exp_f32_e32 v168, v123
	v_exp_f32_e32 v128, v128
	v_exp_f32_e32 v169, v124
	v_exp_f32_e32 v129, v129
	v_exp_f32_e32 v170, v125
	v_add_f32_e32 v171, 1.0, v126
	v_add_f32_e32 v151, 1.0, v151
	v_add_f32_e32 v172, 1.0, v127
	v_add_f32_e32 v173, 1.0, v168
	v_add_f32_e32 v174, 1.0, v128
	v_add_f32_e32 v175, 1.0, v169
	v_add_f32_e32 v176, 1.0, v129
	v_add_f32_e32 v177, 1.0, v170
	v_rcp_f32_e32 v168, v171
	v_rcp_f32_e32 v170, v151
	v_rcp_f32_e32 v169, v172
	v_rcp_f32_e32 v171, v173
	v_rcp_f32_e32 v172, v174
	v_rcp_f32_e32 v174, v175
	v_rcp_f32_e32 v173, v176
	v_rcp_f32_e32 v175, v177
	v_or_b32_e32 v122, 16, v150
	v_ashrrev_i32_e32 v123, 31, v122
	v_lshlrev_b64 v[124:125], 13, v[122:123]
	v_pk_mul_f32 v[118:119], v[118:119], v[168:169]
	v_pk_mul_f32 v[120:121], v[120:121], v[172:173]
	v_pk_mul_f32 v[114:115], v[114:115], v[170:171]
	v_pk_mul_f32 v[116:117], v[116:117], v[174:175]
	v_lshl_add_u64 v[124:125], s[64:65], 0, v[124:125]
	v_lshlrev_b64 v[122:123], 12, v[122:123]
	v_lshl_add_u64 v[126:127], v[124:125], 0, v[148:149]
	v_lshl_add_u64 v[122:123], s[54:55], 0, v[122:123]
	v_lshl_add_u64 v[128:129], v[122:123], 0, v[148:149]
	global_load_dwordx4 v[122:125], v[128:129], off
	v_mul_f32_e32 v110, 0xbfb8aa3b, v110
	v_mul_f32_e32 v106, 0xbfb8aa3b, v106
	v_mul_f32_e32 v111, 0xbfb8aa3b, v111
	v_mul_f32_e32 v107, 0xbfb8aa3b, v107
	v_mul_f32_e32 v112, 0xbfb8aa3b, v112
	v_mul_f32_e32 v108, 0xbfb8aa3b, v108
	v_mul_f32_e32 v113, 0xbfb8aa3b, v113
	v_mul_f32_e32 v109, 0xbfb8aa3b, v109
	v_exp_f32_e32 v110, v110
	v_exp_f32_e32 v111, v111
	v_exp_f32_e32 v112, v112
	v_exp_f32_e32 v113, v113
	v_mul_f32_e32 v94, 0xbfb8aa3b, v94
	v_mul_f32_e32 v90, 0xbfb8aa3b, v90
	v_add_f32_e32 v151, 1.0, v112
	v_mul_f32_e32 v95, 0xbfb8aa3b, v95
	v_mul_f32_e32 v91, 0xbfb8aa3b, v91
	v_mul_f32_e32 v96, 0xbfb8aa3b, v96
	v_mul_f32_e32 v92, 0xbfb8aa3b, v92
	v_mul_f32_e32 v97, 0xbfb8aa3b, v97
	v_mul_f32_e32 v93, 0xbfb8aa3b, v93
	v_exp_f32_e32 v94, v94
	v_exp_f32_e32 v95, v95
	v_exp_f32_e32 v96, v96
	v_exp_f32_e32 v97, v97
	v_mul_f32_e32 v78, 0xbfb8aa3b, v78
	v_mul_f32_e32 v74, 0xbfb8aa3b, v74
	v_mul_f32_e32 v79, 0xbfb8aa3b, v79
	v_mul_f32_e32 v75, 0xbfb8aa3b, v75
	v_mul_f32_e32 v80, 0xbfb8aa3b, v80
	v_mul_f32_e32 v76, 0xbfb8aa3b, v76
	v_mul_f32_e32 v81, 0xbfb8aa3b, v81
	v_mul_f32_e32 v77, 0xbfb8aa3b, v77
	s_waitcnt vmcnt(0)
	v_lshlrev_b32_e32 v168, 16, v158
	v_and_b32_e32 v169, 0xffff0000, v158
	v_lshlrev_b32_e32 v158, 16, v159
	v_and_b32_e32 v159, 0xffff0000, v159
	v_lshlrev_b32_e32 v170, 16, v160
	v_and_b32_e32 v171, 0xffff0000, v160
	v_lshlrev_b32_e32 v160, 16, v161
	v_and_b32_e32 v161, 0xffff0000, v161
	v_lshlrev_b32_e32 v172, 16, v162
	v_and_b32_e32 v173, 0xffff0000, v162
	v_lshlrev_b32_e32 v162, 16, v163
	v_and_b32_e32 v163, 0xffff0000, v163
	v_lshlrev_b32_e32 v174, 16, v164
	v_and_b32_e32 v175, 0xffff0000, v164
	v_lshlrev_b32_e32 v164, 16, v165
	v_and_b32_e32 v165, 0xffff0000, v165
	v_pk_fma_f32 v[118:119], v[118:119], v[172:173], v[168:169]
	v_pk_fma_f32 v[120:121], v[120:121], v[162:163], v[158:159]
	v_pk_fma_f32 v[158:159], v[114:115], v[174:175], v[170:171]
	v_pk_fma_f32 v[160:161], v[116:117], v[164:165], v[160:161]
	v_cvt_pk_bf16_f32 v114, v118, v119
	v_cvt_pk_bf16_f32 v115, v120, v121
	v_cvt_pk_bf16_f32 v116, v158, v159
	v_cvt_pk_bf16_f32 v117, v160, v161
	global_store_dwordx4 v[166:167], v[114:117], off
	v_exp_f32_e32 v118, v106
	v_exp_f32_e32 v119, v107
	v_add_co_u32_e32 v114, vcc, s44, v126
	v_exp_f32_e32 v120, v108
	s_nop 0
	v_addc_co_u32_e32 v115, vcc, 0, v127, vcc
	global_load_dwordx4 v[114:117], v[114:115], off
	v_exp_f32_e32 v121, v109
	v_add_f32_e32 v126, 1.0, v110
	v_add_f32_e32 v118, 1.0, v118
	v_add_f32_e32 v127, 1.0, v111
	v_add_f32_e32 v119, 1.0, v119
	v_add_f32_e32 v158, 1.0, v120
	v_add_f32_e32 v159, 1.0, v113
	v_add_f32_e32 v160, 1.0, v121
	v_rcp_f32_e32 v112, v126
	v_rcp_f32_e32 v118, v118
	v_rcp_f32_e32 v113, v127
	v_rcp_f32_e32 v119, v119
	v_rcp_f32_e32 v120, v151
	v_rcp_f32_e32 v126, v158
	v_rcp_f32_e32 v121, v159
	v_rcp_f32_e32 v127, v160
	v_or_b32_e32 v106, 32, v150
	v_ashrrev_i32_e32 v107, 31, v106
	v_lshlrev_b64 v[108:109], 13, v[106:107]
	v_lshl_add_u64 v[108:109], s[64:65], 0, v[108:109]
	v_pk_mul_f32 v[102:103], v[102:103], v[112:113]
	v_pk_mul_f32 v[104:105], v[104:105], v[120:121]
	v_pk_mul_f32 v[98:99], v[98:99], v[118:119]
	v_pk_mul_f32 v[100:101], v[100:101], v[126:127]
	v_lshlrev_b32_e32 v112, 16, v122
	v_and_b32_e32 v113, 0xffff0000, v122
	v_lshlrev_b32_e32 v118, 16, v123
	v_and_b32_e32 v119, 0xffff0000, v123
	v_lshlrev_b32_e32 v120, 16, v124
	v_and_b32_e32 v121, 0xffff0000, v124
	v_lshlrev_b32_e32 v122, 16, v125
	v_and_b32_e32 v123, 0xffff0000, v125
	v_lshlrev_b64 v[106:107], 12, v[106:107]
	v_lshl_add_u64 v[108:109], v[108:109], 0, v[148:149]
	v_lshl_add_u64 v[106:107], s[54:55], 0, v[106:107]
	v_add_co_u32_e32 v158, vcc, s44, v108
	v_lshl_add_u64 v[110:111], v[106:107], 0, v[148:149]
	s_nop 0
	v_addc_co_u32_e32 v159, vcc, 0, v109, vcc
	global_load_dwordx4 v[106:109], v[110:111], off
	v_exp_f32_e32 v78, v78
	v_exp_f32_e32 v79, v79
	v_exp_f32_e32 v80, v80
	v_exp_f32_e32 v81, v81
	v_mul_f32_e32 v62, 0xbfb8aa3b, v62
	v_mul_f32_e32 v58, 0xbfb8aa3b, v58
	v_mul_f32_e32 v63, 0xbfb8aa3b, v63
	v_mul_f32_e32 v59, 0xbfb8aa3b, v59
	v_mul_f32_e32 v64, 0xbfb8aa3b, v64
	v_mul_f32_e32 v60, 0xbfb8aa3b, v60
	v_mul_f32_e32 v65, 0xbfb8aa3b, v65
	v_mul_f32_e32 v61, 0xbfb8aa3b, v61
	v_exp_f32_e32 v62, v62
	v_exp_f32_e32 v63, v63
	v_exp_f32_e32 v64, v64
	v_exp_f32_e32 v65, v65
	v_mul_f32_e32 v46, 0xbfb8aa3b, v46
	v_mul_f32_e32 v42, 0xbfb8aa3b, v42
	v_mul_f32_e32 v47, 0xbfb8aa3b, v47
	v_mul_f32_e32 v43, 0xbfb8aa3b, v43
	v_mul_f32_e32 v48, 0xbfb8aa3b, v48
	v_mul_f32_e32 v44, 0xbfb8aa3b, v44
	v_mul_f32_e32 v49, 0xbfb8aa3b, v49
	v_mul_f32_e32 v45, 0xbfb8aa3b, v45
	v_exp_f32_e32 v46, v46
	v_exp_f32_e32 v47, v47
	v_exp_f32_e32 v48, v48
	v_exp_f32_e32 v49, v49
	v_mul_f32_e32 v30, 0xbfb8aa3b, v30
	v_mul_f32_e32 v26, 0xbfb8aa3b, v26
	v_mul_f32_e32 v31, 0xbfb8aa3b, v31
	v_mul_f32_e32 v27, 0xbfb8aa3b, v27
	v_mul_f32_e32 v32, 0xbfb8aa3b, v32
	v_mul_f32_e32 v28, 0xbfb8aa3b, v28
	v_mul_f32_e32 v33, 0xbfb8aa3b, v33
	v_mul_f32_e32 v29, 0xbfb8aa3b, v29
	v_exp_f32_e32 v30, v30
	v_exp_f32_e32 v31, v31
	s_waitcnt vmcnt(1)
	v_lshlrev_b32_e32 v124, 16, v114
	v_and_b32_e32 v125, 0xffff0000, v114
	v_lshlrev_b32_e32 v114, 16, v115
	v_and_b32_e32 v115, 0xffff0000, v115
	v_lshlrev_b32_e32 v126, 16, v116
	v_and_b32_e32 v127, 0xffff0000, v116
	v_lshlrev_b32_e32 v116, 16, v117
	v_and_b32_e32 v117, 0xffff0000, v117
	v_pk_fma_f32 v[102:103], v[102:103], v[124:125], v[112:113]
	v_pk_fma_f32 v[104:105], v[104:105], v[114:115], v[118:119]
	v_pk_fma_f32 v[112:113], v[98:99], v[126:127], v[120:121]
	v_pk_fma_f32 v[114:115], v[100:101], v[116:117], v[122:123]
	v_cvt_pk_bf16_f32 v98, v102, v103
	v_cvt_pk_bf16_f32 v99, v104, v105
	v_cvt_pk_bf16_f32 v100, v112, v113
	v_cvt_pk_bf16_f32 v101, v114, v115
	global_store_dwordx4 v[128:129], v[98:101], off
	global_load_dwordx4 v[98:101], v[158:159], off
	v_exp_f32_e32 v102, v90
	v_exp_f32_e32 v103, v91
	v_exp_f32_e32 v104, v92
	v_exp_f32_e32 v105, v93
	v_or_b32_e32 v90, 48, v150
	v_ashrrev_i32_e32 v91, 31, v90
	v_add_f32_e32 v112, 1.0, v94
	v_add_f32_e32 v102, 1.0, v102
	v_add_f32_e32 v113, 1.0, v95
	v_add_f32_e32 v103, 1.0, v103
	v_add_f32_e32 v114, 1.0, v96
	v_add_f32_e32 v115, 1.0, v104
	v_add_f32_e32 v116, 1.0, v97
	v_add_f32_e32 v117, 1.0, v105
	v_lshlrev_b64 v[92:93], 13, v[90:91]
	v_rcp_f32_e32 v96, v112
	v_rcp_f32_e32 v102, v102
	v_rcp_f32_e32 v97, v113
	v_rcp_f32_e32 v103, v103
	v_rcp_f32_e32 v104, v114
	v_rcp_f32_e32 v112, v115
	v_rcp_f32_e32 v105, v116
	v_rcp_f32_e32 v113, v117
	v_lshlrev_b64 v[90:91], 12, v[90:91]
	v_lshl_add_u64 v[92:93], s[64:65], 0, v[92:93]
	v_lshl_add_u64 v[90:91], s[54:55], 0, v[90:91]
	v_lshl_add_u64 v[92:93], v[92:93], 0, v[148:149]
	v_lshl_add_u64 v[94:95], v[90:91], 0, v[148:149]
	v_add_co_u32_e32 v114, vcc, s44, v92
	v_pk_mul_f32 v[86:87], v[86:87], v[96:97]
	s_nop 0
	v_addc_co_u32_e32 v115, vcc, 0, v93, vcc
	global_load_dwordx4 v[90:93], v[94:95], off
	v_pk_mul_f32 v[88:89], v[88:89], v[104:105]
	v_pk_mul_f32 v[82:83], v[82:83], v[102:103]
	v_pk_mul_f32 v[84:85], v[84:85], v[112:113]
	s_waitcnt vmcnt(3)
	v_lshlrev_b32_e32 v96, 16, v106
	v_and_b32_e32 v97, 0xffff0000, v106
	v_lshlrev_b32_e32 v102, 16, v107
	v_and_b32_e32 v103, 0xffff0000, v107
	v_lshlrev_b32_e32 v104, 16, v108
	v_and_b32_e32 v105, 0xffff0000, v108
	v_lshlrev_b32_e32 v106, 16, v109
	v_and_b32_e32 v107, 0xffff0000, v109
	v_exp_f32_e32 v32, v32
	v_exp_f32_e32 v33, v33
	v_mul_f32_e32 v14, 0xbfb8aa3b, v14
	v_mul_f32_e32 v10, 0xbfb8aa3b, v10
	v_mul_f32_e32 v15, 0xbfb8aa3b, v15
	v_mul_f32_e32 v11, 0xbfb8aa3b, v11
	v_mul_f32_e32 v16, 0xbfb8aa3b, v16
	v_mul_f32_e32 v12, 0xbfb8aa3b, v12
	v_mul_f32_e32 v17, 0xbfb8aa3b, v17
	v_mul_f32_e32 v13, 0xbfb8aa3b, v13
	v_exp_f32_e32 v14, v14
	v_exp_f32_e32 v10, v10
	v_exp_f32_e32 v15, v15
	v_exp_f32_e32 v11, v11
	v_exp_f32_e32 v16, v16
	v_exp_f32_e32 v12, v12
	v_exp_f32_e32 v17, v17
	v_exp_f32_e32 v13, v13
	v_add_f32_e32 v14, 1.0, v14
	v_add_f32_e32 v15, 1.0, v15
	v_add_f32_e32 v16, 1.0, v16
	v_add_f32_e32 v17, 1.0, v17
	s_waitcnt vmcnt(1)
	v_lshlrev_b32_e32 v108, 16, v98
	v_and_b32_e32 v109, 0xffff0000, v98
	v_lshlrev_b32_e32 v98, 16, v99
	v_and_b32_e32 v99, 0xffff0000, v99
	v_lshlrev_b32_e32 v112, 16, v100
	v_and_b32_e32 v113, 0xffff0000, v100
	v_lshlrev_b32_e32 v100, 16, v101
	v_and_b32_e32 v101, 0xffff0000, v101
	v_pk_fma_f32 v[86:87], v[86:87], v[108:109], v[96:97]
	v_pk_fma_f32 v[88:89], v[88:89], v[98:99], v[102:103]
	v_pk_fma_f32 v[96:97], v[82:83], v[112:113], v[104:105]
	v_pk_fma_f32 v[98:99], v[84:85], v[100:101], v[106:107]
	v_cvt_pk_bf16_f32 v82, v86, v87
	v_cvt_pk_bf16_f32 v83, v88, v89
	v_cvt_pk_bf16_f32 v84, v96, v97
	v_cvt_pk_bf16_f32 v85, v98, v99
	global_store_dwordx4 v[110:111], v[82:85], off
	global_load_dwordx4 v[82:85], v[114:115], off
	v_exp_f32_e32 v86, v74
	v_exp_f32_e32 v87, v75
	v_exp_f32_e32 v88, v76
	v_exp_f32_e32 v89, v77
	v_add_f32_e32 v96, 1.0, v78
	v_add_f32_e32 v86, 1.0, v86
	v_add_f32_e32 v97, 1.0, v79
	v_add_f32_e32 v87, 1.0, v87
	v_add_f32_e32 v98, 1.0, v80
	v_add_f32_e32 v99, 1.0, v88
	v_add_f32_e32 v100, 1.0, v81
	v_add_f32_e32 v101, 1.0, v89
	v_rcp_f32_e32 v80, v96
	v_rcp_f32_e32 v86, v86
	v_rcp_f32_e32 v81, v97
	v_rcp_f32_e32 v87, v87
	v_rcp_f32_e32 v88, v98
	v_rcp_f32_e32 v96, v99
	v_rcp_f32_e32 v89, v100
	v_rcp_f32_e32 v97, v101
	v_add_u32_e32 v74, 0x80, v150
	v_ashrrev_i32_e32 v75, 31, v74
	v_lshlrev_b64 v[76:77], 13, v[74:75]
	v_lshl_add_u64 v[76:77], s[64:65], 0, v[76:77]
	v_pk_mul_f32 v[70:71], v[70:71], v[80:81]
	v_pk_mul_f32 v[72:73], v[72:73], v[88:89]
	v_pk_mul_f32 v[66:67], v[66:67], v[86:87]
	v_pk_mul_f32 v[68:69], v[68:69], v[96:97]
	s_waitcnt vmcnt(2)
	v_lshlrev_b32_e32 v80, 16, v90
	v_and_b32_e32 v81, 0xffff0000, v90
	v_lshlrev_b32_e32 v86, 16, v91
	v_and_b32_e32 v87, 0xffff0000, v91
	v_lshlrev_b32_e32 v88, 16, v92
	v_and_b32_e32 v89, 0xffff0000, v92
	v_lshlrev_b32_e32 v90, 16, v93
	v_and_b32_e32 v91, 0xffff0000, v93
	v_lshlrev_b64 v[74:75], 12, v[74:75]
	v_lshl_add_u64 v[76:77], v[76:77], 0, v[148:149]
	v_lshl_add_u64 v[74:75], s[54:55], 0, v[74:75]
	v_add_co_u32_e32 v98, vcc, s44, v76
	v_lshl_add_u64 v[78:79], v[74:75], 0, v[148:149]
	s_nop 0
	v_addc_co_u32_e32 v99, vcc, 0, v77, vcc
	global_load_dwordx4 v[74:77], v[78:79], off
	s_waitcnt vmcnt(1)
	v_lshlrev_b32_e32 v92, 16, v82
	v_and_b32_e32 v93, 0xffff0000, v82
	v_lshlrev_b32_e32 v82, 16, v83
	v_and_b32_e32 v83, 0xffff0000, v83
	v_lshlrev_b32_e32 v96, 16, v84
	v_and_b32_e32 v97, 0xffff0000, v84
	v_lshlrev_b32_e32 v84, 16, v85
	v_and_b32_e32 v85, 0xffff0000, v85
	v_pk_fma_f32 v[70:71], v[70:71], v[92:93], v[80:81]
	v_pk_fma_f32 v[72:73], v[72:73], v[82:83], v[86:87]
	v_pk_fma_f32 v[80:81], v[66:67], v[96:97], v[88:89]
	v_pk_fma_f32 v[82:83], v[68:69], v[84:85], v[90:91]
	v_cvt_pk_bf16_f32 v66, v70, v71
	v_cvt_pk_bf16_f32 v67, v72, v73
	v_cvt_pk_bf16_f32 v68, v80, v81
	v_cvt_pk_bf16_f32 v69, v82, v83
	global_store_dwordx4 v[94:95], v[66:69], off
	global_load_dwordx4 v[66:69], v[98:99], off
	v_exp_f32_e32 v70, v58
	v_exp_f32_e32 v71, v59
	v_exp_f32_e32 v72, v60
	v_exp_f32_e32 v73, v61
	v_add_u32_e32 v58, 0x90, v150
	v_ashrrev_i32_e32 v59, 31, v58
	v_add_f32_e32 v80, 1.0, v62
	v_add_f32_e32 v70, 1.0, v70
	v_add_f32_e32 v81, 1.0, v63
	v_add_f32_e32 v71, 1.0, v71
	v_add_f32_e32 v82, 1.0, v64
	v_add_f32_e32 v83, 1.0, v72
	v_add_f32_e32 v84, 1.0, v65
	v_add_f32_e32 v85, 1.0, v73
	v_lshlrev_b64 v[60:61], 13, v[58:59]
	v_rcp_f32_e32 v64, v80
	v_rcp_f32_e32 v70, v70
	v_rcp_f32_e32 v65, v81
	v_rcp_f32_e32 v71, v71
	v_rcp_f32_e32 v72, v82
	v_rcp_f32_e32 v80, v83
	v_rcp_f32_e32 v73, v84
	v_rcp_f32_e32 v81, v85
	v_lshlrev_b64 v[58:59], 12, v[58:59]
	v_lshl_add_u64 v[60:61], s[64:65], 0, v[60:61]
	v_lshl_add_u64 v[58:59], s[54:55], 0, v[58:59]
	v_lshl_add_u64 v[60:61], v[60:61], 0, v[148:149]
	v_lshl_add_u64 v[62:63], v[58:59], 0, v[148:149]
	v_add_co_u32_e32 v82, vcc, s44, v60
	v_pk_mul_f32 v[54:55], v[54:55], v[64:65]
	s_nop 0
	v_addc_co_u32_e32 v83, vcc, 0, v61, vcc
	global_load_dwordx4 v[58:61], v[62:63], off
	v_pk_mul_f32 v[56:57], v[56:57], v[72:73]
	v_pk_mul_f32 v[50:51], v[50:51], v[70:71]
	v_pk_mul_f32 v[52:53], v[52:53], v[80:81]
	s_waitcnt vmcnt(3)
	v_lshlrev_b32_e32 v64, 16, v74
	v_and_b32_e32 v65, 0xffff0000, v74
	v_lshlrev_b32_e32 v70, 16, v75
	v_and_b32_e32 v71, 0xffff0000, v75
	v_lshlrev_b32_e32 v72, 16, v76
	v_and_b32_e32 v73, 0xffff0000, v76
	v_lshlrev_b32_e32 v74, 16, v77
	v_and_b32_e32 v75, 0xffff0000, v77
	s_waitcnt vmcnt(1)
	v_lshlrev_b32_e32 v76, 16, v66
	v_and_b32_e32 v77, 0xffff0000, v66
	v_lshlrev_b32_e32 v66, 16, v67
	v_and_b32_e32 v67, 0xffff0000, v67
	v_lshlrev_b32_e32 v80, 16, v68
	v_and_b32_e32 v81, 0xffff0000, v68
	v_lshlrev_b32_e32 v68, 16, v69
	v_and_b32_e32 v69, 0xffff0000, v69
	v_pk_fma_f32 v[54:55], v[54:55], v[76:77], v[64:65]
	v_pk_fma_f32 v[56:57], v[56:57], v[66:67], v[70:71]
	v_pk_fma_f32 v[64:65], v[50:51], v[80:81], v[72:73]
	v_pk_fma_f32 v[66:67], v[52:53], v[68:69], v[74:75]
	v_cvt_pk_bf16_f32 v50, v54, v55
	v_cvt_pk_bf16_f32 v51, v56, v57
	v_cvt_pk_bf16_f32 v52, v64, v65
	v_cvt_pk_bf16_f32 v53, v66, v67
	global_store_dwordx4 v[78:79], v[50:53], off
	global_load_dwordx4 v[50:53], v[82:83], off
	v_exp_f32_e32 v54, v42
	v_exp_f32_e32 v55, v43
	v_exp_f32_e32 v56, v44
	v_exp_f32_e32 v57, v45
	v_add_f32_e32 v64, 1.0, v46
	v_add_f32_e32 v54, 1.0, v54
	v_add_f32_e32 v65, 1.0, v47
	v_add_f32_e32 v55, 1.0, v55
	v_add_f32_e32 v66, 1.0, v48
	v_add_f32_e32 v67, 1.0, v56
	v_add_f32_e32 v68, 1.0, v49
	v_add_f32_e32 v69, 1.0, v57
	v_rcp_f32_e32 v48, v64
	v_rcp_f32_e32 v54, v54
	v_rcp_f32_e32 v49, v65
	v_rcp_f32_e32 v55, v55
	v_rcp_f32_e32 v56, v66
	v_rcp_f32_e32 v64, v67
	v_rcp_f32_e32 v57, v68
	v_rcp_f32_e32 v65, v69
	v_add_u32_e32 v42, 0xa0, v150
	v_ashrrev_i32_e32 v43, 31, v42
	v_lshlrev_b64 v[44:45], 13, v[42:43]
	v_lshl_add_u64 v[44:45], s[64:65], 0, v[44:45]
	v_pk_mul_f32 v[38:39], v[38:39], v[48:49]
	v_pk_mul_f32 v[40:41], v[40:41], v[56:57]
	v_pk_mul_f32 v[34:35], v[34:35], v[54:55]
	v_pk_mul_f32 v[36:37], v[36:37], v[64:65]
	s_waitcnt vmcnt(2)
	v_lshlrev_b32_e32 v48, 16, v58
	v_and_b32_e32 v49, 0xffff0000, v58
	v_lshlrev_b32_e32 v54, 16, v59
	v_and_b32_e32 v55, 0xffff0000, v59
	v_lshlrev_b32_e32 v56, 16, v60
	v_and_b32_e32 v57, 0xffff0000, v60
	v_lshlrev_b32_e32 v58, 16, v61
	v_and_b32_e32 v59, 0xffff0000, v61
	v_lshlrev_b64 v[42:43], 12, v[42:43]
	v_lshl_add_u64 v[44:45], v[44:45], 0, v[148:149]
	v_lshl_add_u64 v[42:43], s[54:55], 0, v[42:43]
	v_add_co_u32_e32 v66, vcc, s44, v44
	v_lshl_add_u64 v[46:47], v[42:43], 0, v[148:149]
	s_nop 0
	v_addc_co_u32_e32 v67, vcc, 0, v45, vcc
	global_load_dwordx4 v[42:45], v[46:47], off
	s_waitcnt vmcnt(1)
	v_lshlrev_b32_e32 v60, 16, v50
	v_and_b32_e32 v61, 0xffff0000, v50
	v_lshlrev_b32_e32 v50, 16, v51
	v_and_b32_e32 v51, 0xffff0000, v51
	v_lshlrev_b32_e32 v64, 16, v52
	v_and_b32_e32 v65, 0xffff0000, v52
	v_lshlrev_b32_e32 v52, 16, v53
	v_and_b32_e32 v53, 0xffff0000, v53
	v_pk_fma_f32 v[38:39], v[38:39], v[60:61], v[48:49]
	v_pk_fma_f32 v[40:41], v[40:41], v[50:51], v[54:55]
	v_pk_fma_f32 v[48:49], v[34:35], v[64:65], v[56:57]
	v_pk_fma_f32 v[50:51], v[36:37], v[52:53], v[58:59]
	v_cvt_pk_bf16_f32 v34, v38, v39
	v_cvt_pk_bf16_f32 v35, v40, v41
	v_cvt_pk_bf16_f32 v36, v48, v49
	v_cvt_pk_bf16_f32 v37, v50, v51
	global_store_dwordx4 v[62:63], v[34:37], off
	global_load_dwordx4 v[34:37], v[66:67], off
	v_exp_f32_e32 v38, v26
	v_exp_f32_e32 v39, v27
	v_exp_f32_e32 v40, v28
	v_exp_f32_e32 v41, v29
	v_add_u32_e32 v26, 0xb0, v150
	v_ashrrev_i32_e32 v27, 31, v26
	v_add_f32_e32 v48, 1.0, v30
	v_add_f32_e32 v38, 1.0, v38
	v_add_f32_e32 v49, 1.0, v31
	v_add_f32_e32 v39, 1.0, v39
	v_add_f32_e32 v50, 1.0, v32
	v_add_f32_e32 v51, 1.0, v40
	v_add_f32_e32 v52, 1.0, v33
	v_add_f32_e32 v53, 1.0, v41
	v_lshlrev_b64 v[28:29], 13, v[26:27]
	v_rcp_f32_e32 v32, v48
	v_rcp_f32_e32 v38, v38
	v_rcp_f32_e32 v33, v49
	v_rcp_f32_e32 v39, v39
	v_rcp_f32_e32 v40, v50
	v_rcp_f32_e32 v48, v51
	v_rcp_f32_e32 v41, v52
	v_rcp_f32_e32 v49, v53
	v_lshlrev_b64 v[26:27], 12, v[26:27]
	v_lshl_add_u64 v[28:29], s[64:65], 0, v[28:29]
	v_lshl_add_u64 v[26:27], s[54:55], 0, v[26:27]
	v_lshl_add_u64 v[28:29], v[28:29], 0, v[148:149]
	v_lshl_add_u64 v[30:31], v[26:27], 0, v[148:149]
	v_add_co_u32_e32 v50, vcc, s44, v28
	v_pk_mul_f32 v[22:23], v[22:23], v[32:33]
	s_nop 0
	v_addc_co_u32_e32 v51, vcc, 0, v29, vcc
	global_load_dwordx4 v[26:29], v[30:31], off
	v_pk_mul_f32 v[24:25], v[24:25], v[40:41]
	v_pk_mul_f32 v[18:19], v[18:19], v[38:39]
	v_pk_mul_f32 v[20:21], v[20:21], v[48:49]
	s_waitcnt vmcnt(3)
	v_lshlrev_b32_e32 v32, 16, v42
	v_and_b32_e32 v33, 0xffff0000, v42
	v_lshlrev_b32_e32 v38, 16, v43
	v_and_b32_e32 v39, 0xffff0000, v43
	v_lshlrev_b32_e32 v40, 16, v44
	v_and_b32_e32 v41, 0xffff0000, v44
	v_lshlrev_b32_e32 v42, 16, v45
	v_and_b32_e32 v43, 0xffff0000, v45
	s_andn2_b64 vcc, exec, s[4:5]
	s_mov_b64 s[4:5], -1
	s_waitcnt vmcnt(1)
	v_lshlrev_b32_e32 v44, 16, v34
	v_and_b32_e32 v45, 0xffff0000, v34
	v_lshlrev_b32_e32 v34, 16, v35
	v_and_b32_e32 v35, 0xffff0000, v35
	v_lshlrev_b32_e32 v48, 16, v36
	v_and_b32_e32 v49, 0xffff0000, v36
	v_lshlrev_b32_e32 v36, 16, v37
	v_and_b32_e32 v37, 0xffff0000, v37
	v_pk_fma_f32 v[22:23], v[22:23], v[44:45], v[32:33]
	v_pk_fma_f32 v[24:25], v[24:25], v[34:35], v[38:39]
	v_pk_fma_f32 v[32:33], v[18:19], v[48:49], v[40:41]
	v_pk_fma_f32 v[34:35], v[20:21], v[36:37], v[42:43]
	v_cvt_pk_bf16_f32 v18, v22, v23
	v_cvt_pk_bf16_f32 v19, v24, v25
	v_cvt_pk_bf16_f32 v20, v32, v33
	v_cvt_pk_bf16_f32 v21, v34, v35
	global_store_dwordx4 v[46:47], v[18:21], off
	global_load_dwordx4 v[18:21], v[50:51], off
	v_add_f32_e32 v22, 1.0, v10
	v_add_f32_e32 v23, 1.0, v11
	v_add_f32_e32 v24, 1.0, v12
	v_add_f32_e32 v25, 1.0, v13
	v_rcp_f32_e32 v10, v14
	v_rcp_f32_e32 v12, v22
	v_rcp_f32_e32 v11, v15
	v_rcp_f32_e32 v13, v23
	v_rcp_f32_e32 v14, v16
	v_rcp_f32_e32 v16, v24
	v_rcp_f32_e32 v15, v17
	v_rcp_f32_e32 v17, v25
	v_pk_mul_f32 v[6:7], v[6:7], v[10:11]
	v_pk_mul_f32 v[2:3], v[2:3], v[12:13]
	v_pk_mul_f32 v[8:9], v[8:9], v[14:15]
	v_pk_mul_f32 v[4:5], v[4:5], v[16:17]
	s_waitcnt vmcnt(2)
	v_lshlrev_b32_e32 v10, 16, v26
	v_and_b32_e32 v11, 0xffff0000, v26
	v_lshlrev_b32_e32 v12, 16, v27
	v_and_b32_e32 v13, 0xffff0000, v27
	v_lshlrev_b32_e32 v14, 16, v28
	v_and_b32_e32 v15, 0xffff0000, v28
	v_lshlrev_b32_e32 v16, 16, v29
	v_and_b32_e32 v17, 0xffff0000, v29
	s_waitcnt vmcnt(0)
	v_lshlrev_b32_e32 v22, 16, v18
	v_and_b32_e32 v23, 0xffff0000, v18
	v_lshlrev_b32_e32 v18, 16, v19
	v_and_b32_e32 v19, 0xffff0000, v19
	v_lshlrev_b32_e32 v24, 16, v20
	v_and_b32_e32 v25, 0xffff0000, v20
	v_lshlrev_b32_e32 v20, 16, v21
	v_and_b32_e32 v21, 0xffff0000, v21
	v_pk_fma_f32 v[6:7], v[6:7], v[22:23], v[10:11]
	v_pk_fma_f32 v[8:9], v[8:9], v[18:19], v[12:13]
	v_pk_fma_f32 v[10:11], v[2:3], v[24:25], v[14:15]
	v_pk_fma_f32 v[12:13], v[4:5], v[20:21], v[16:17]
	v_cvt_pk_bf16_f32 v2, v6, v7
	v_cvt_pk_bf16_f32 v3, v8, v9
	v_cvt_pk_bf16_f32 v4, v10, v11
	v_cvt_pk_bf16_f32 v5, v12, v13
	global_store_dwordx4 v[30:31], v[2:5], off
	s_cbranch_vccnz .LBB0_1050
	s_andn2_b64 vcc, exec, s[0:1]
	s_cbranch_vccnz .LBB0_1049
	s_branch .LBB0_1049

.LBB0_1123:
	s_ashr_i32 s21, s20, 31
	s_lshl_b64 s[22:23], s[20:21], 20
	s_add_u32 s22, s54, s22
	s_addc_u32 s23, s55, s23
	s_and_b64 s[24:25], s[8:9], exec
	s_cselect_b32 s21, s23, s31
	s_cselect_b32 s27, s22, s30
	s_ashr_i32 s19, s18, 31
	s_lshl_b64 s[24:25], s[18:19], 20
	v_readlane_b32 s36, v241, 44
	v_readlane_b32 s37, v241, 45
	s_add_u32 s24, s36, s24
	s_addc_u32 s25, s37, s25
	s_and_b64 s[36:37], s[8:9], exec
	s_cselect_b32 s19, s25, s35
	s_cselect_b32 s29, s24, s34
	s_add_u32 s30, s30, 0x80080
	s_addc_u32 s31, s31, 0
	s_add_u32 s57, s34, 0x100
	v_mov_b32_e32 v2, 0
	s_addc_u32 s58, s35, 0
	s_mov_b32 s59, -2
	s_waitcnt lgkmcnt(0)
	v_mov_b32_e32 v3, v2
	v_mov_b32_e32 v4, v2
	v_mov_b32_e32 v5, v2
	v_mov_b32_e32 v6, v2
	v_mov_b32_e32 v7, v2
	v_mov_b32_e32 v8, v2
	v_mov_b32_e32 v9, v2
	s_waitcnt vmcnt(0)
	v_mov_b32_e32 v18, v2
	v_mov_b32_e32 v19, v2
	v_mov_b32_e32 v20, v2
	v_mov_b32_e32 v21, v2
	v_mov_b32_e32 v22, v2
	v_mov_b32_e32 v23, v2
	v_mov_b32_e32 v24, v2
	v_mov_b32_e32 v25, v2
	v_mov_b32_e32 v34, v2
	v_mov_b32_e32 v35, v2
	v_mov_b32_e32 v36, v2
	v_mov_b32_e32 v37, v2
	v_mov_b32_e32 v38, v2
	v_mov_b32_e32 v39, v2
	v_mov_b32_e32 v40, v2
	v_mov_b32_e32 v41, v2
	v_mov_b32_e32 v50, v2
	v_mov_b32_e32 v51, v2
	v_mov_b32_e32 v52, v2
	v_mov_b32_e32 v53, v2
	v_mov_b32_e32 v54, v2
	v_mov_b32_e32 v55, v2
	v_mov_b32_e32 v56, v2
	v_mov_b32_e32 v57, v2
	v_mov_b32_e32 v10, v2
	v_mov_b32_e32 v11, v2
	v_mov_b32_e32 v12, v2
	v_mov_b32_e32 v13, v2
	v_mov_b32_e32 v14, v2
	v_mov_b32_e32 v15, v2
	v_mov_b32_e32 v16, v2
	v_mov_b32_e32 v17, v2
	v_mov_b32_e32 v26, v2
	v_mov_b32_e32 v27, v2
	v_mov_b32_e32 v28, v2
	v_mov_b32_e32 v29, v2
	v_mov_b32_e32 v30, v2
	v_mov_b32_e32 v31, v2
	v_mov_b32_e32 v32, v2
	v_mov_b32_e32 v33, v2
	v_mov_b32_e32 v42, v2
	v_mov_b32_e32 v43, v2
	v_mov_b32_e32 v44, v2
	v_mov_b32_e32 v45, v2
	v_mov_b32_e32 v46, v2
	v_mov_b32_e32 v47, v2
	v_mov_b32_e32 v48, v2
	v_mov_b32_e32 v49, v2
	v_mov_b32_e32 v58, v2
	v_mov_b32_e32 v59, v2
	v_mov_b32_e32 v60, v2
	v_mov_b32_e32 v61, v2
	v_mov_b32_e32 v62, v2
	v_mov_b32_e32 v63, v2
	v_mov_b32_e32 v64, v2
	v_mov_b32_e32 v65, v2
	v_mov_b32_e32 v66, v2
	v_mov_b32_e32 v67, v2
	v_mov_b32_e32 v68, v2
	v_mov_b32_e32 v69, v2
	v_mov_b32_e32 v70, v2
	v_mov_b32_e32 v71, v2
	v_mov_b32_e32 v72, v2
	v_mov_b32_e32 v73, v2
	v_mov_b32_e32 v82, v2
	v_mov_b32_e32 v83, v2
	v_mov_b32_e32 v84, v2
	v_mov_b32_e32 v85, v2
	v_mov_b32_e32 v94, v2
	v_mov_b32_e32 v95, v2
	v_mov_b32_e32 v96, v2
	v_mov_b32_e32 v97, v2
	v_mov_b32_e32 v114, v2
	v_mov_b32_e32 v115, v2
	v_mov_b32_e32 v116, v2
	v_mov_b32_e32 v117, v2
	v_mov_b32_e32 v118, v2
	v_mov_b32_e32 v119, v2
	v_mov_b32_e32 v120, v2
	v_mov_b32_e32 v121, v2
	v_mov_b32_e32 v130, v2
	v_mov_b32_e32 v131, v2
	v_mov_b32_e32 v132, v2
	v_mov_b32_e32 v133, v2
	v_mov_b32_e32 v134, v2
	v_mov_b32_e32 v135, v2
	v_mov_b32_e32 v136, v2
	v_mov_b32_e32 v137, v2
	v_mov_b32_e32 v74, v2
	v_mov_b32_e32 v75, v2
	v_mov_b32_e32 v76, v2
	v_mov_b32_e32 v77, v2
	v_mov_b32_e32 v78, v2
	v_mov_b32_e32 v79, v2
	v_mov_b32_e32 v80, v2
	v_mov_b32_e32 v81, v2
	v_mov_b32_e32 v106, v2
	v_mov_b32_e32 v107, v2
	v_mov_b32_e32 v108, v2
	v_mov_b32_e32 v109, v2
	v_mov_b32_e32 v110, v2
	v_mov_b32_e32 v111, v2
	v_mov_b32_e32 v112, v2
	v_mov_b32_e32 v113, v2
	v_mov_b32_e32 v122, v2
	v_mov_b32_e32 v123, v2
	v_mov_b32_e32 v124, v2
	v_mov_b32_e32 v125, v2
	v_mov_b32_e32 v126, v2
	v_mov_b32_e32 v127, v2
	v_mov_b32_e32 v128, v2
	v_mov_b32_e32 v129, v2
	v_mov_b32_e32 v138, v2
	v_mov_b32_e32 v139, v2
	v_mov_b32_e32 v140, v2
	v_mov_b32_e32 v141, v2
	v_mov_b32_e32 v142, v2
	v_mov_b32_e32 v143, v2
	v_mov_b32_e32 v144, v2
	v_mov_b32_e32 v145, v2
	s_cmp_lt_u32 s42, 2
	s_cbranch_scc1 .Lp7_norestore
	s_andn2_b64 vcc, exec, s[0:1]
	s_cbranch_vccnz .Lp7_norestore
	s_barrier
.Lp7_norestore:
.LBB0_1124:
	ds_read_b128 v[86:89], v182
	ds_read_b128 v[90:93], v182 offset:1024
	ds_read_b128 v[98:101], v182 offset:2048
	ds_read_b128 v[102:105], v182 offset:3072
	ds_read_b128 v[164:167], v183
	ds_read_b128 v[168:171], v183 offset:1024
	ds_read_b128 v[172:175], v183 offset:2048
	ds_read_b128 v[186:189], v183 offset:3072
	s_add_u32 s34, s30, 0xfff80080
	s_addc_u32 s35, s31, -1
	s_cmp_eq_u32 s59, 28
	s_cselect_b32 s37, s21, s35
	s_cselect_b32 s36, s27, s34
	s_cselect_b32 s35, s19, s58
	s_cselect_b32 s34, s29, s57
	v_lshl_add_u64 v[176:177], s[30:31], 0, v[156:157]
	s_add_i32 m0, s38, 0xc000
	ds_read_b128 v[190:193], v184
	ds_read_b128 v[194:197], v184 offset:1024
	ds_read_b128 v[198:201], v184 offset:2048
	ds_read_b128 v[202:205], v184 offset:3072
	ds_read_b128 v[206:209], v184 offset:4096
	ds_read_b128 v[210:213], v184 offset:5120
	ds_read_b128 v[214:217], v184 offset:6144
	ds_read_b128 v[218:221], v184 offset:7168
	global_load_lds_dwordx4 v[176:177], off
	v_lshl_add_u64 v[176:177], s[30:31], 0, v[158:159]
	s_add_i32 m0, s38, 0xe000
	s_nop 0
	global_load_lds_dwordx4 v[176:177], off
	s_waitcnt vmcnt(8)
	s_waitcnt lgkmcnt(0)
	s_setprio 1
	s_barrier
	v_mfma_f32_16x16x32_bf16 v[142:145], v[86:89], v[190:193], v[142:145]
	v_mfma_f32_16x16x32_bf16 v[138:141], v[98:101], v[190:193], v[138:141]
	v_mfma_f32_16x16x32_bf16 v[126:129], v[86:89], v[198:201], v[126:129]
	v_mfma_f32_16x16x32_bf16 v[122:125], v[98:101], v[198:201], v[122:125]
	v_mfma_f32_16x16x32_bf16 v[110:113], v[86:89], v[206:209], v[110:113]
	v_mfma_f32_16x16x32_bf16 v[106:109], v[98:101], v[206:209], v[106:109]
	v_mfma_f32_16x16x32_bf16 v[78:81], v[86:89], v[214:217], v[78:81]
	v_mfma_f32_16x16x32_bf16 v[74:77], v[98:101], v[214:217], v[74:77]
	v_mfma_f32_16x16x32_bf16 v[142:145], v[90:93], v[194:197], v[142:145]
	v_mfma_f32_16x16x32_bf16 v[138:141], v[102:105], v[194:197], v[138:141]
	v_mfma_f32_16x16x32_bf16 v[126:129], v[90:93], v[202:205], v[126:129]
	v_mfma_f32_16x16x32_bf16 v[122:125], v[102:105], v[202:205], v[122:125]
	v_mfma_f32_16x16x32_bf16 v[110:113], v[90:93], v[210:213], v[110:113]
	v_mfma_f32_16x16x32_bf16 v[106:109], v[102:105], v[210:213], v[106:109]
	v_mfma_f32_16x16x32_bf16 v[78:81], v[90:93], v[218:221], v[78:81]
	v_mfma_f32_16x16x32_bf16 v[74:77], v[102:105], v[218:221], v[74:77]
	v_mfma_f32_16x16x32_bf16 v[134:137], v[164:167], v[190:193], v[134:137]
	v_mfma_f32_16x16x32_bf16 v[130:133], v[172:175], v[190:193], v[130:133]
	v_mfma_f32_16x16x32_bf16 v[118:121], v[164:167], v[198:201], v[118:121]
	v_mfma_f32_16x16x32_bf16 v[114:117], v[172:175], v[198:201], v[114:117]
	v_mfma_f32_16x16x32_bf16 v[94:97], v[164:167], v[206:209], v[94:97]
	v_mfma_f32_16x16x32_bf16 v[82:85], v[172:175], v[206:209], v[82:85]
	v_mfma_f32_16x16x32_bf16 v[70:73], v[164:167], v[214:217], v[70:73]
	v_mfma_f32_16x16x32_bf16 v[66:69], v[172:175], v[214:217], v[66:69]
	v_mfma_f32_16x16x32_bf16 v[134:137], v[168:171], v[194:197], v[134:137]
	v_mfma_f32_16x16x32_bf16 v[130:133], v[186:189], v[194:197], v[130:133]
	v_mfma_f32_16x16x32_bf16 v[118:121], v[168:171], v[202:205], v[118:121]
	v_mfma_f32_16x16x32_bf16 v[114:117], v[186:189], v[202:205], v[114:117]
	v_mfma_f32_16x16x32_bf16 v[94:97], v[168:171], v[210:213], v[94:97]
	v_mfma_f32_16x16x32_bf16 v[82:85], v[186:189], v[210:213], v[82:85]
	v_mfma_f32_16x16x32_bf16 v[70:73], v[168:171], v[218:221], v[70:73]
	v_mfma_f32_16x16x32_bf16 v[66:69], v[186:189], v[218:221], v[66:69]
	s_barrier
	s_setprio 0
	s_add_i32 s68, s51, s33
	v_lshl_add_u64 v[176:177], s[34:35], 0, v[150:151]
	s_mov_b32 m0, s68
	ds_read_b128 v[190:193], v184 offset:16384
	ds_read_b128 v[194:197], v184 offset:17408
	ds_read_b128 v[198:201], v184 offset:18432
	ds_read_b128 v[202:205], v184 offset:19456
	ds_read_b128 v[206:209], v184 offset:20480
	ds_read_b128 v[210:213], v184 offset:21504
	ds_read_b128 v[214:217], v184 offset:22528
	ds_read_b128 v[218:221], v184 offset:23552
	global_load_lds_dwordx4 v[176:177], off
	s_add_i32 m0, s68, 0x2000
	s_add_u32 s68, s34, 0x80000
	v_lshl_add_u64 v[222:223], s[34:35], 0, v[154:155]
	s_addc_u32 s69, s35, 0
	s_add_i32 s70, s56, s33
	global_load_lds_dwordx4 v[222:223], off
	v_lshl_add_u64 v[224:225], s[68:69], 0, v[150:151]
	s_mov_b32 m0, s70
	v_lshl_add_u64 v[226:227], s[36:37], 0, v[152:153]
	global_load_lds_dwordx4 v[224:225], off
	v_lshl_add_u64 v[224:225], s[68:69], 0, v[154:155]
	s_add_i32 m0, s70, 0x2000
	s_nop 0
	global_load_lds_dwordx4 v[224:225], off
	v_lshl_add_u64 v[224:225], s[36:37], 0, v[148:149]
	s_mov_b32 m0, s38
	s_nop 0
	global_load_lds_dwordx4 v[224:225], off
	s_mov_b32 m0, s39
	s_nop 0
	global_load_lds_dwordx4 v[226:227], off
	s_waitcnt vmcnt(8)
	s_waitcnt lgkmcnt(0)
	s_setprio 1
	s_barrier
	v_mfma_f32_16x16x32_bf16 v[62:65], v[86:89], v[190:193], v[62:65]
	v_mfma_f32_16x16x32_bf16 v[58:61], v[98:101], v[190:193], v[58:61]
	v_mfma_f32_16x16x32_bf16 v[46:49], v[86:89], v[198:201], v[46:49]
	v_mfma_f32_16x16x32_bf16 v[42:45], v[98:101], v[198:201], v[42:45]
	v_mfma_f32_16x16x32_bf16 v[30:33], v[86:89], v[206:209], v[30:33]
	v_mfma_f32_16x16x32_bf16 v[26:29], v[98:101], v[206:209], v[26:29]
	v_mfma_f32_16x16x32_bf16 v[14:17], v[86:89], v[214:217], v[14:17]
	v_mfma_f32_16x16x32_bf16 v[10:13], v[98:101], v[214:217], v[10:13]
	v_mfma_f32_16x16x32_bf16 v[62:65], v[90:93], v[194:197], v[62:65]
	v_mfma_f32_16x16x32_bf16 v[58:61], v[102:105], v[194:197], v[58:61]
	v_mfma_f32_16x16x32_bf16 v[46:49], v[90:93], v[202:205], v[46:49]
	v_mfma_f32_16x16x32_bf16 v[42:45], v[102:105], v[202:205], v[42:45]
	v_mfma_f32_16x16x32_bf16 v[30:33], v[90:93], v[210:213], v[30:33]
	v_mfma_f32_16x16x32_bf16 v[26:29], v[102:105], v[210:213], v[26:29]
	v_mfma_f32_16x16x32_bf16 v[14:17], v[90:93], v[218:221], v[14:17]
	v_mfma_f32_16x16x32_bf16 v[10:13], v[102:105], v[218:221], v[10:13]
	v_mfma_f32_16x16x32_bf16 v[54:57], v[164:167], v[190:193], v[54:57]
	v_mfma_f32_16x16x32_bf16 v[50:53], v[172:175], v[190:193], v[50:53]
	v_mfma_f32_16x16x32_bf16 v[38:41], v[164:167], v[198:201], v[38:41]
	v_mfma_f32_16x16x32_bf16 v[34:37], v[172:175], v[198:201], v[34:37]
	v_mfma_f32_16x16x32_bf16 v[22:25], v[164:167], v[206:209], v[22:25]
	v_mfma_f32_16x16x32_bf16 v[18:21], v[172:175], v[206:209], v[18:21]
	v_mfma_f32_16x16x32_bf16 v[6:9], v[164:167], v[214:217], v[6:9]
	v_mfma_f32_16x16x32_bf16 v[2:5], v[172:175], v[214:217], v[2:5]
	v_mfma_f32_16x16x32_bf16 v[54:57], v[168:171], v[194:197], v[54:57]
	v_mfma_f32_16x16x32_bf16 v[50:53], v[186:189], v[194:197], v[50:53]
	v_mfma_f32_16x16x32_bf16 v[38:41], v[168:171], v[202:205], v[38:41]
	v_mfma_f32_16x16x32_bf16 v[34:37], v[186:189], v[202:205], v[34:37]
	v_mfma_f32_16x16x32_bf16 v[22:25], v[168:171], v[210:213], v[22:25]
	v_mfma_f32_16x16x32_bf16 v[18:21], v[186:189], v[210:213], v[18:21]
	v_mfma_f32_16x16x32_bf16 v[6:9], v[168:171], v[218:221], v[6:9]
	v_mfma_f32_16x16x32_bf16 v[2:5], v[186:189], v[218:221], v[2:5]
	s_barrier
	s_setprio 0
	s_add_i32 s68, 0, 0x18000
	s_add_i32 s69, 0, 0x1c000
	v_add_u32_e32 v102, s68, v180
	v_add_u32_e32 v185, s69, v180
	ds_read_b128 v[86:89], v102
	ds_read_b128 v[90:93], v102 offset:1024
	ds_read_b128 v[98:101], v102 offset:2048
	ds_read_b128 v[102:105], v102 offset:3072
	ds_read_b128 v[164:167], v185
	ds_read_b128 v[168:171], v185 offset:1024
	ds_read_b128 v[172:175], v185 offset:2048
	ds_read_b128 v[186:189], v185 offset:3072
	s_add_u32 s36, s36, 0x80000
	s_addc_u32 s37, s37, 0
	s_mov_b32 m0, s40
	v_lshl_add_u64 v[228:229], s[36:37], 0, v[148:149]
	ds_read_b128 v[190:193], v184 offset:32768
	ds_read_b128 v[194:197], v184 offset:33792
	ds_read_b128 v[198:201], v184 offset:34816
	ds_read_b128 v[202:205], v184 offset:35840
	ds_read_b128 v[206:209], v184 offset:36864
	ds_read_b128 v[210:213], v184 offset:37888
	ds_read_b128 v[214:217], v184 offset:38912
	ds_read_b128 v[218:221], v184 offset:39936
	global_load_lds_dwordx4 v[228:229], off
	v_lshl_add_u64 v[228:229], s[36:37], 0, v[152:153]
	s_mov_b32 m0, s41
	s_nop 0
	global_load_lds_dwordx4 v[228:229], off
	s_waitcnt vmcnt(8)
	s_waitcnt lgkmcnt(0)
	s_setprio 1
	s_barrier
	v_mfma_f32_16x16x32_bf16 v[142:145], v[86:89], v[190:193], v[142:145]
	v_mfma_f32_16x16x32_bf16 v[138:141], v[98:101], v[190:193], v[138:141]
	v_mfma_f32_16x16x32_bf16 v[126:129], v[86:89], v[198:201], v[126:129]
	v_mfma_f32_16x16x32_bf16 v[122:125], v[98:101], v[198:201], v[122:125]
	v_mfma_f32_16x16x32_bf16 v[110:113], v[86:89], v[206:209], v[110:113]
	v_mfma_f32_16x16x32_bf16 v[106:109], v[98:101], v[206:209], v[106:109]
	v_mfma_f32_16x16x32_bf16 v[78:81], v[86:89], v[214:217], v[78:81]
	v_mfma_f32_16x16x32_bf16 v[74:77], v[98:101], v[214:217], v[74:77]
	v_mfma_f32_16x16x32_bf16 v[142:145], v[90:93], v[194:197], v[142:145]
	v_mfma_f32_16x16x32_bf16 v[138:141], v[102:105], v[194:197], v[138:141]
	v_mfma_f32_16x16x32_bf16 v[126:129], v[90:93], v[202:205], v[126:129]
	v_mfma_f32_16x16x32_bf16 v[122:125], v[102:105], v[202:205], v[122:125]
	v_mfma_f32_16x16x32_bf16 v[110:113], v[90:93], v[210:213], v[110:113]
	v_mfma_f32_16x16x32_bf16 v[106:109], v[102:105], v[210:213], v[106:109]
	v_mfma_f32_16x16x32_bf16 v[78:81], v[90:93], v[218:221], v[78:81]
	v_mfma_f32_16x16x32_bf16 v[74:77], v[102:105], v[218:221], v[74:77]
	v_mfma_f32_16x16x32_bf16 v[134:137], v[164:167], v[190:193], v[134:137]
	v_mfma_f32_16x16x32_bf16 v[130:133], v[172:175], v[190:193], v[130:133]
	v_mfma_f32_16x16x32_bf16 v[118:121], v[164:167], v[198:201], v[118:121]
	v_mfma_f32_16x16x32_bf16 v[114:117], v[172:175], v[198:201], v[114:117]
	v_mfma_f32_16x16x32_bf16 v[94:97], v[164:167], v[206:209], v[94:97]
	v_mfma_f32_16x16x32_bf16 v[82:85], v[172:175], v[206:209], v[82:85]
	v_mfma_f32_16x16x32_bf16 v[70:73], v[164:167], v[214:217], v[70:73]
	v_mfma_f32_16x16x32_bf16 v[66:69], v[172:175], v[214:217], v[66:69]
	v_mfma_f32_16x16x32_bf16 v[134:137], v[168:171], v[194:197], v[134:137]
	v_mfma_f32_16x16x32_bf16 v[130:133], v[186:189], v[194:197], v[130:133]
	v_mfma_f32_16x16x32_bf16 v[118:121], v[168:171], v[202:205], v[118:121]
	v_mfma_f32_16x16x32_bf16 v[114:117], v[186:189], v[202:205], v[114:117]
	v_mfma_f32_16x16x32_bf16 v[94:97], v[168:171], v[210:213], v[94:97]
	v_mfma_f32_16x16x32_bf16 v[82:85], v[186:189], v[210:213], v[82:85]
	v_mfma_f32_16x16x32_bf16 v[70:73], v[168:171], v[218:221], v[70:73]
	v_mfma_f32_16x16x32_bf16 v[66:69], v[186:189], v[218:221], v[66:69]
	s_barrier
	s_setprio 0
	s_add_i32 s36, s68, s33
	v_lshl_add_u64 v[176:177], v[176:177], 0, s[2:3]
	s_mov_b32 m0, s36
	ds_read_b128 v[190:193], v184 offset:49152
	ds_read_b128 v[194:197], v184 offset:50176
	ds_read_b128 v[198:201], v184 offset:51200
	ds_read_b128 v[202:205], v184 offset:52224
	ds_read_b128 v[206:209], v184 offset:53248
	ds_read_b128 v[210:213], v184 offset:54272
	ds_read_b128 v[214:217], v184 offset:55296
	ds_read_b128 v[218:221], v184 offset:56320
	global_load_lds_dwordx4 v[176:177], off
	s_add_i32 m0, s36, 0x2000
	s_add_u32 s34, s34, 0x80080
	v_lshl_add_u64 v[176:177], v[222:223], 0, s[2:3]
	s_addc_u32 s35, s35, 0
	s_add_i32 s36, s69, s33
	global_load_lds_dwordx4 v[176:177], off
	v_lshl_add_u64 v[176:177], s[34:35], 0, v[150:151]
	s_mov_b32 m0, s36
	s_nop 0
	global_load_lds_dwordx4 v[176:177], off
	v_lshl_add_u64 v[176:177], s[34:35], 0, v[154:155]
	s_add_i32 m0, s36, 0x2000
	s_nop 0
	global_load_lds_dwordx4 v[176:177], off
	v_lshl_add_u64 v[176:177], v[224:225], 0, s[2:3]
	s_mov_b32 m0, s43
	s_nop 0
	global_load_lds_dwordx4 v[176:177], off
	v_lshl_add_u64 v[176:177], v[226:227], 0, s[2:3]
	s_mov_b32 m0, s44
	s_nop 0
	global_load_lds_dwordx4 v[176:177], off
	s_waitcnt vmcnt(8)
	s_waitcnt lgkmcnt(0)
	s_setprio 1
	s_barrier
	v_mfma_f32_16x16x32_bf16 v[62:65], v[86:89], v[190:193], v[62:65]
	v_mfma_f32_16x16x32_bf16 v[58:61], v[98:101], v[190:193], v[58:61]
	v_mfma_f32_16x16x32_bf16 v[46:49], v[86:89], v[198:201], v[46:49]
	v_mfma_f32_16x16x32_bf16 v[42:45], v[98:101], v[198:201], v[42:45]
	v_mfma_f32_16x16x32_bf16 v[30:33], v[86:89], v[206:209], v[30:33]
	v_mfma_f32_16x16x32_bf16 v[26:29], v[98:101], v[206:209], v[26:29]
	v_mfma_f32_16x16x32_bf16 v[14:17], v[86:89], v[214:217], v[14:17]
	v_mfma_f32_16x16x32_bf16 v[10:13], v[98:101], v[214:217], v[10:13]
	v_mfma_f32_16x16x32_bf16 v[62:65], v[90:93], v[194:197], v[62:65]
	v_mfma_f32_16x16x32_bf16 v[58:61], v[102:105], v[194:197], v[58:61]
	v_mfma_f32_16x16x32_bf16 v[46:49], v[90:93], v[202:205], v[46:49]
	v_mfma_f32_16x16x32_bf16 v[42:45], v[102:105], v[202:205], v[42:45]
	v_mfma_f32_16x16x32_bf16 v[30:33], v[90:93], v[210:213], v[30:33]
	v_mfma_f32_16x16x32_bf16 v[26:29], v[102:105], v[210:213], v[26:29]
	v_mfma_f32_16x16x32_bf16 v[14:17], v[90:93], v[218:221], v[14:17]
	v_mfma_f32_16x16x32_bf16 v[10:13], v[102:105], v[218:221], v[10:13]
	v_mfma_f32_16x16x32_bf16 v[54:57], v[164:167], v[190:193], v[54:57]
	v_mfma_f32_16x16x32_bf16 v[50:53], v[172:175], v[190:193], v[50:53]
	v_mfma_f32_16x16x32_bf16 v[38:41], v[164:167], v[198:201], v[38:41]
	v_mfma_f32_16x16x32_bf16 v[34:37], v[172:175], v[198:201], v[34:37]
	v_mfma_f32_16x16x32_bf16 v[22:25], v[164:167], v[206:209], v[22:25]
	v_mfma_f32_16x16x32_bf16 v[18:21], v[172:175], v[206:209], v[18:21]
	v_mfma_f32_16x16x32_bf16 v[6:9], v[164:167], v[214:217], v[6:9]
	v_mfma_f32_16x16x32_bf16 v[2:5], v[172:175], v[214:217], v[2:5]
	v_mfma_f32_16x16x32_bf16 v[54:57], v[168:171], v[194:197], v[54:57]
	v_mfma_f32_16x16x32_bf16 v[50:53], v[186:189], v[194:197], v[50:53]
	v_mfma_f32_16x16x32_bf16 v[38:41], v[168:171], v[202:205], v[38:41]
	v_mfma_f32_16x16x32_bf16 v[34:37], v[186:189], v[202:205], v[34:37]
	v_mfma_f32_16x16x32_bf16 v[22:25], v[168:171], v[210:213], v[22:25]
	v_mfma_f32_16x16x32_bf16 v[18:21], v[186:189], v[210:213], v[18:21]
	v_mfma_f32_16x16x32_bf16 v[6:9], v[168:171], v[218:221], v[6:9]
	v_mfma_f32_16x16x32_bf16 v[2:5], v[186:189], v[218:221], v[2:5]
	s_barrier
	s_setprio 0
	s_add_i32 s59, s59, 2
	s_add_u32 s30, s30, 0x100
	s_addc_u32 s31, s31, 0
	s_add_u32 s57, s57, 0x100
	s_addc_u32 s58, s58, 0
	s_cmp_gt_u32 s59, 29
	s_cbranch_scc0 .LBB0_1124
	s_and_b64 vcc, exec, s[16:17]
	s_cbranch_vccz .LBB0_1127
	s_barrier

.LBB0_1143:
	s_or_b64 exec, exec, s[26:27]
	s_andn2_b64 vcc, exec, s[8:9]
	s_mov_b64 s[8:9], -1
	s_cbranch_vccnz .LBB0_1120
	s_andn2_b64 vcc, exec, s[0:1]
	s_cbranch_vccnz .LBB0_1119
	s_branch .LBB0_1119

.LBB0_1207:
	s_ashr_i32 s21, s20, 31
	s_lshl_b64 s[22:23], s[20:21], 20
	s_add_u32 s22, s52, s22
	s_addc_u32 s23, s53, s23
	s_and_b64 s[24:25], s[0:1], exec
	s_cselect_b32 s21, s23, s27
	s_cselect_b32 s50, s22, s26
	s_ashr_i32 s19, s18, 31
	s_lshl_b64 s[24:25], s[18:19], 20
	v_readlane_b32 s30, v240, 23
	v_readlane_b32 s31, v240, 24
	s_add_u32 s24, s30, s24
	s_addc_u32 s25, s31, s25
	s_and_b64 s[30:31], s[0:1], exec
	s_cselect_b32 s19, s25, s29
	s_cselect_b32 s51, s24, s28
	s_add_u32 s26, s26, 0x80080
	s_addc_u32 s27, s27, 0
	s_add_u32 s56, s28, 0x100
	v_mov_b32_e32 v2, 0
	s_addc_u32 s57, s29, 0
	s_mov_b32 s58, -2
	v_mov_b32_e32 v3, v2
	v_mov_b32_e32 v4, v2
	v_mov_b32_e32 v5, v2
	v_mov_b32_e32 v6, v2
	v_mov_b32_e32 v7, v2
	v_mov_b32_e32 v8, v2
	v_mov_b32_e32 v9, v2
	s_waitcnt vmcnt(0)
	v_mov_b32_e32 v18, v2
	v_mov_b32_e32 v19, v2
	v_mov_b32_e32 v20, v2
	v_mov_b32_e32 v21, v2
	v_mov_b32_e32 v22, v2
	v_mov_b32_e32 v23, v2
	v_mov_b32_e32 v24, v2
	v_mov_b32_e32 v25, v2
	v_mov_b32_e32 v34, v2
	v_mov_b32_e32 v35, v2
	v_mov_b32_e32 v36, v2
	v_mov_b32_e32 v37, v2
	v_mov_b32_e32 v38, v2
	v_mov_b32_e32 v39, v2
	v_mov_b32_e32 v40, v2
	v_mov_b32_e32 v41, v2
	v_mov_b32_e32 v50, v2
	v_mov_b32_e32 v51, v2
	v_mov_b32_e32 v52, v2
	v_mov_b32_e32 v53, v2
	v_mov_b32_e32 v54, v2
	v_mov_b32_e32 v55, v2
	v_mov_b32_e32 v56, v2
	v_mov_b32_e32 v57, v2
	v_mov_b32_e32 v10, v2
	v_mov_b32_e32 v11, v2
	v_mov_b32_e32 v12, v2
	v_mov_b32_e32 v13, v2
	v_mov_b32_e32 v14, v2
	v_mov_b32_e32 v15, v2
	v_mov_b32_e32 v16, v2
	v_mov_b32_e32 v17, v2
	v_mov_b32_e32 v26, v2
	v_mov_b32_e32 v27, v2
	v_mov_b32_e32 v28, v2
	v_mov_b32_e32 v29, v2
	v_mov_b32_e32 v30, v2
	v_mov_b32_e32 v31, v2
	v_mov_b32_e32 v32, v2
	v_mov_b32_e32 v33, v2
	v_mov_b32_e32 v42, v2
	v_mov_b32_e32 v43, v2
	v_mov_b32_e32 v44, v2
	v_mov_b32_e32 v45, v2
	v_mov_b32_e32 v46, v2
	v_mov_b32_e32 v47, v2
	v_mov_b32_e32 v48, v2
	v_mov_b32_e32 v49, v2
	v_mov_b32_e32 v58, v2
	v_mov_b32_e32 v59, v2
	v_mov_b32_e32 v60, v2
	v_mov_b32_e32 v61, v2
	v_mov_b32_e32 v62, v2
	v_mov_b32_e32 v63, v2
	v_mov_b32_e32 v64, v2
	v_mov_b32_e32 v65, v2
	v_mov_b32_e32 v66, v2
	v_mov_b32_e32 v67, v2
	v_mov_b32_e32 v68, v2
	v_mov_b32_e32 v69, v2
	v_mov_b32_e32 v70, v2
	v_mov_b32_e32 v71, v2
	v_mov_b32_e32 v72, v2
	v_mov_b32_e32 v73, v2
	v_mov_b32_e32 v82, v2
	v_mov_b32_e32 v83, v2
	v_mov_b32_e32 v84, v2
	v_mov_b32_e32 v85, v2
	v_mov_b32_e32 v86, v2
	v_mov_b32_e32 v87, v2
	v_mov_b32_e32 v88, v2
	v_mov_b32_e32 v89, v2
	v_mov_b32_e32 v114, v2
	v_mov_b32_e32 v115, v2
	v_mov_b32_e32 v116, v2
	v_mov_b32_e32 v117, v2
	v_mov_b32_e32 v118, v2
	v_mov_b32_e32 v119, v2
	v_mov_b32_e32 v120, v2
	v_mov_b32_e32 v121, v2
	v_mov_b32_e32 v130, v2
	v_mov_b32_e32 v131, v2
	v_mov_b32_e32 v132, v2
	v_mov_b32_e32 v133, v2
	v_mov_b32_e32 v134, v2
	v_mov_b32_e32 v135, v2
	v_mov_b32_e32 v136, v2
	v_mov_b32_e32 v137, v2
	v_mov_b32_e32 v74, v2
	v_mov_b32_e32 v75, v2
	v_mov_b32_e32 v76, v2
	v_mov_b32_e32 v77, v2
	v_mov_b32_e32 v78, v2
	v_mov_b32_e32 v79, v2
	v_mov_b32_e32 v80, v2
	v_mov_b32_e32 v81, v2
	v_mov_b32_e32 v90, v2
	v_mov_b32_e32 v91, v2
	v_mov_b32_e32 v92, v2
	v_mov_b32_e32 v93, v2
	v_mov_b32_e32 v94, v2
	v_mov_b32_e32 v95, v2
	v_mov_b32_e32 v96, v2
	v_mov_b32_e32 v97, v2
	v_mov_b32_e32 v122, v2
	v_mov_b32_e32 v123, v2
	v_mov_b32_e32 v124, v2
	v_mov_b32_e32 v125, v2
	v_mov_b32_e32 v126, v2
	v_mov_b32_e32 v127, v2
	v_mov_b32_e32 v128, v2
	v_mov_b32_e32 v129, v2
	v_mov_b32_e32 v138, v2
	v_mov_b32_e32 v139, v2
	v_mov_b32_e32 v140, v2
	v_mov_b32_e32 v141, v2
	v_mov_b32_e32 v142, v2
	v_mov_b32_e32 v143, v2
	v_mov_b32_e32 v144, v2
	v_mov_b32_e32 v145, v2
	s_cmp_lt_u32 s40, 2
	s_cbranch_scc1 .Lp9_norestore
	s_andn2_b64 vcc, exec, s[2:3]
	s_cbranch_vccnz .Lp9_norestore
	s_barrier
.Lp9_norestore:
.LBB0_1208:
	ds_read_b128 v[98:101], v175
	ds_read_b128 v[102:105], v175 offset:1024
	ds_read_b128 v[106:109], v175 offset:2048
	ds_read_b128 v[110:113], v175 offset:3072
	ds_read_b128 v[164:167], v176
	ds_read_b128 v[168:171], v176 offset:1024
	ds_read_b128 v[182:185], v176 offset:2048
	ds_read_b128 v[186:189], v176 offset:3072
	s_add_u32 s28, s26, 0xfff80080
	s_addc_u32 s29, s27, -1
	s_cmp_eq_u32 s58, 28
	s_cselect_b32 s31, s21, s29
	s_cselect_b32 s30, s50, s28
	s_cselect_b32 s29, s19, s57
	s_cselect_b32 s28, s51, s56
	v_lshl_add_u64 v[222:223], s[26:27], 0, v[156:157]
	s_add_i32 m0, s36, 0xc000
	ds_read_b128 v[190:193], v177
	ds_read_b128 v[194:197], v177 offset:1024
	ds_read_b128 v[198:201], v177 offset:2048
	ds_read_b128 v[202:205], v177 offset:3072
	ds_read_b128 v[206:209], v177 offset:4096
	ds_read_b128 v[210:213], v177 offset:5120
	ds_read_b128 v[214:217], v177 offset:6144
	ds_read_b128 v[218:221], v177 offset:7168
	global_load_lds_dwordx4 v[222:223], off
	v_lshl_add_u64 v[222:223], s[26:27], 0, v[158:159]
	s_add_i32 m0, s36, 0xe000
	s_nop 0
	global_load_lds_dwordx4 v[222:223], off
	s_waitcnt vmcnt(8)
	s_waitcnt lgkmcnt(0)
	s_setprio 1
	s_barrier
	v_mfma_f32_16x16x32_bf16 v[142:145], v[98:101], v[190:193], v[142:145]
	v_mfma_f32_16x16x32_bf16 v[138:141], v[106:109], v[190:193], v[138:141]
	v_mfma_f32_16x16x32_bf16 v[126:129], v[98:101], v[198:201], v[126:129]
	v_mfma_f32_16x16x32_bf16 v[122:125], v[106:109], v[198:201], v[122:125]
	v_mfma_f32_16x16x32_bf16 v[94:97], v[98:101], v[206:209], v[94:97]
	v_mfma_f32_16x16x32_bf16 v[90:93], v[106:109], v[206:209], v[90:93]
	v_mfma_f32_16x16x32_bf16 v[78:81], v[98:101], v[214:217], v[78:81]
	v_mfma_f32_16x16x32_bf16 v[74:77], v[106:109], v[214:217], v[74:77]
	v_mfma_f32_16x16x32_bf16 v[142:145], v[102:105], v[194:197], v[142:145]
	v_mfma_f32_16x16x32_bf16 v[138:141], v[110:113], v[194:197], v[138:141]
	v_mfma_f32_16x16x32_bf16 v[126:129], v[102:105], v[202:205], v[126:129]
	v_mfma_f32_16x16x32_bf16 v[122:125], v[110:113], v[202:205], v[122:125]
	v_mfma_f32_16x16x32_bf16 v[94:97], v[102:105], v[210:213], v[94:97]
	v_mfma_f32_16x16x32_bf16 v[90:93], v[110:113], v[210:213], v[90:93]
	v_mfma_f32_16x16x32_bf16 v[78:81], v[102:105], v[218:221], v[78:81]
	v_mfma_f32_16x16x32_bf16 v[74:77], v[110:113], v[218:221], v[74:77]
	v_mfma_f32_16x16x32_bf16 v[134:137], v[164:167], v[190:193], v[134:137]
	v_mfma_f32_16x16x32_bf16 v[130:133], v[182:185], v[190:193], v[130:133]
	v_mfma_f32_16x16x32_bf16 v[118:121], v[164:167], v[198:201], v[118:121]
	v_mfma_f32_16x16x32_bf16 v[114:117], v[182:185], v[198:201], v[114:117]
	v_mfma_f32_16x16x32_bf16 v[86:89], v[164:167], v[206:209], v[86:89]
	v_mfma_f32_16x16x32_bf16 v[82:85], v[182:185], v[206:209], v[82:85]
	v_mfma_f32_16x16x32_bf16 v[70:73], v[164:167], v[214:217], v[70:73]
	v_mfma_f32_16x16x32_bf16 v[66:69], v[182:185], v[214:217], v[66:69]
	v_mfma_f32_16x16x32_bf16 v[134:137], v[168:171], v[194:197], v[134:137]
	v_mfma_f32_16x16x32_bf16 v[130:133], v[186:189], v[194:197], v[130:133]
	v_mfma_f32_16x16x32_bf16 v[118:121], v[168:171], v[202:205], v[118:121]
	v_mfma_f32_16x16x32_bf16 v[114:117], v[186:189], v[202:205], v[114:117]
	v_mfma_f32_16x16x32_bf16 v[86:89], v[168:171], v[210:213], v[86:89]
	v_mfma_f32_16x16x32_bf16 v[82:85], v[186:189], v[210:213], v[82:85]
	v_mfma_f32_16x16x32_bf16 v[70:73], v[168:171], v[218:221], v[70:73]
	v_mfma_f32_16x16x32_bf16 v[66:69], v[186:189], v[218:221], v[66:69]
	s_barrier
	s_setprio 0
	s_add_i32 s59, s45, s33
	v_lshl_add_u64 v[222:223], s[28:29], 0, v[152:153]
	s_mov_b32 m0, s59
	ds_read_b128 v[190:193], v177 offset:16384
	ds_read_b128 v[194:197], v177 offset:17408
	ds_read_b128 v[198:201], v177 offset:18432
	ds_read_b128 v[202:205], v177 offset:19456
	ds_read_b128 v[206:209], v177 offset:20480
	ds_read_b128 v[210:213], v177 offset:21504
	ds_read_b128 v[214:217], v177 offset:22528
	ds_read_b128 v[218:221], v177 offset:23552
	global_load_lds_dwordx4 v[222:223], off
	s_add_i32 m0, s59, 0x2000
	s_add_u32 s68, s28, 0x80000
	v_lshl_add_u64 v[224:225], s[28:29], 0, v[148:149]
	s_addc_u32 s69, s29, 0
	s_add_i32 s59, s46, s33
	global_load_lds_dwordx4 v[224:225], off
	v_lshl_add_u64 v[226:227], s[68:69], 0, v[152:153]
	s_mov_b32 m0, s59
	v_lshl_add_u64 v[228:229], s[30:31], 0, v[150:151]
	global_load_lds_dwordx4 v[226:227], off
	v_lshl_add_u64 v[226:227], s[68:69], 0, v[148:149]
	s_add_i32 m0, s59, 0x2000
	s_nop 0
	global_load_lds_dwordx4 v[226:227], off
	v_lshl_add_u64 v[226:227], s[30:31], 0, v[154:155]
	s_mov_b32 m0, s36
	s_nop 0
	global_load_lds_dwordx4 v[226:227], off
	s_mov_b32 m0, s37
	s_nop 0
	global_load_lds_dwordx4 v[228:229], off
	s_waitcnt vmcnt(8)
	s_waitcnt lgkmcnt(0)
	s_setprio 1
	s_barrier
	v_mfma_f32_16x16x32_bf16 v[62:65], v[98:101], v[190:193], v[62:65]
	v_mfma_f32_16x16x32_bf16 v[58:61], v[106:109], v[190:193], v[58:61]
	v_mfma_f32_16x16x32_bf16 v[46:49], v[98:101], v[198:201], v[46:49]
	v_mfma_f32_16x16x32_bf16 v[42:45], v[106:109], v[198:201], v[42:45]
	v_mfma_f32_16x16x32_bf16 v[30:33], v[98:101], v[206:209], v[30:33]
	v_mfma_f32_16x16x32_bf16 v[26:29], v[106:109], v[206:209], v[26:29]
	v_mfma_f32_16x16x32_bf16 v[14:17], v[98:101], v[214:217], v[14:17]
	v_mfma_f32_16x16x32_bf16 v[10:13], v[106:109], v[214:217], v[10:13]
	v_mfma_f32_16x16x32_bf16 v[62:65], v[102:105], v[194:197], v[62:65]
	v_mfma_f32_16x16x32_bf16 v[58:61], v[110:113], v[194:197], v[58:61]
	v_mfma_f32_16x16x32_bf16 v[46:49], v[102:105], v[202:205], v[46:49]
	v_mfma_f32_16x16x32_bf16 v[42:45], v[110:113], v[202:205], v[42:45]
	v_mfma_f32_16x16x32_bf16 v[30:33], v[102:105], v[210:213], v[30:33]
	v_mfma_f32_16x16x32_bf16 v[26:29], v[110:113], v[210:213], v[26:29]
	v_mfma_f32_16x16x32_bf16 v[14:17], v[102:105], v[218:221], v[14:17]
	v_mfma_f32_16x16x32_bf16 v[10:13], v[110:113], v[218:221], v[10:13]
	v_mfma_f32_16x16x32_bf16 v[54:57], v[164:167], v[190:193], v[54:57]
	v_mfma_f32_16x16x32_bf16 v[50:53], v[182:185], v[190:193], v[50:53]
	v_mfma_f32_16x16x32_bf16 v[38:41], v[164:167], v[198:201], v[38:41]
	v_mfma_f32_16x16x32_bf16 v[34:37], v[182:185], v[198:201], v[34:37]
	v_mfma_f32_16x16x32_bf16 v[22:25], v[164:167], v[206:209], v[22:25]
	v_mfma_f32_16x16x32_bf16 v[18:21], v[182:185], v[206:209], v[18:21]
	v_mfma_f32_16x16x32_bf16 v[6:9], v[164:167], v[214:217], v[6:9]
	v_mfma_f32_16x16x32_bf16 v[2:5], v[182:185], v[214:217], v[2:5]
	v_mfma_f32_16x16x32_bf16 v[54:57], v[168:171], v[194:197], v[54:57]
	v_mfma_f32_16x16x32_bf16 v[50:53], v[186:189], v[194:197], v[50:53]
	v_mfma_f32_16x16x32_bf16 v[38:41], v[168:171], v[202:205], v[38:41]
	v_mfma_f32_16x16x32_bf16 v[34:37], v[186:189], v[202:205], v[34:37]
	v_mfma_f32_16x16x32_bf16 v[22:25], v[168:171], v[210:213], v[22:25]
	v_mfma_f32_16x16x32_bf16 v[18:21], v[186:189], v[210:213], v[18:21]
	v_mfma_f32_16x16x32_bf16 v[6:9], v[168:171], v[218:221], v[6:9]
	v_mfma_f32_16x16x32_bf16 v[2:5], v[186:189], v[218:221], v[2:5]
	s_barrier
	s_setprio 0
	s_add_i32 s59, 0, 0x18000
	s_add_i32 s68, 0, 0x1c000
	v_add_u32_e32 v110, s59, v173
	v_add_u32_e32 v181, s68, v173
	ds_read_b128 v[98:101], v110
	ds_read_b128 v[102:105], v110 offset:1024
	ds_read_b128 v[106:109], v110 offset:2048
	ds_read_b128 v[110:113], v110 offset:3072
	ds_read_b128 v[164:167], v181
	ds_read_b128 v[168:171], v181 offset:1024
	ds_read_b128 v[182:185], v181 offset:2048
	ds_read_b128 v[186:189], v181 offset:3072
	s_add_u32 s30, s30, 0x80000
	s_addc_u32 s31, s31, 0
	s_mov_b32 m0, s38
	v_lshl_add_u64 v[230:231], s[30:31], 0, v[154:155]
	ds_read_b128 v[190:193], v177 offset:32768
	ds_read_b128 v[194:197], v177 offset:33792
	ds_read_b128 v[198:201], v177 offset:34816
	ds_read_b128 v[202:205], v177 offset:35840
	ds_read_b128 v[206:209], v177 offset:36864
	ds_read_b128 v[210:213], v177 offset:37888
	ds_read_b128 v[214:217], v177 offset:38912
	ds_read_b128 v[218:221], v177 offset:39936
	global_load_lds_dwordx4 v[230:231], off
	v_lshl_add_u64 v[230:231], s[30:31], 0, v[150:151]
	s_mov_b32 m0, s39
	s_nop 0
	global_load_lds_dwordx4 v[230:231], off
	s_waitcnt vmcnt(8)
	s_waitcnt lgkmcnt(0)
	s_setprio 1
	s_barrier
	v_mfma_f32_16x16x32_bf16 v[142:145], v[98:101], v[190:193], v[142:145]
	v_mfma_f32_16x16x32_bf16 v[138:141], v[106:109], v[190:193], v[138:141]
	v_mfma_f32_16x16x32_bf16 v[126:129], v[98:101], v[198:201], v[126:129]
	v_mfma_f32_16x16x32_bf16 v[122:125], v[106:109], v[198:201], v[122:125]
	v_mfma_f32_16x16x32_bf16 v[94:97], v[98:101], v[206:209], v[94:97]
	v_mfma_f32_16x16x32_bf16 v[90:93], v[106:109], v[206:209], v[90:93]
	v_mfma_f32_16x16x32_bf16 v[78:81], v[98:101], v[214:217], v[78:81]
	v_mfma_f32_16x16x32_bf16 v[74:77], v[106:109], v[214:217], v[74:77]
	v_mfma_f32_16x16x32_bf16 v[142:145], v[102:105], v[194:197], v[142:145]
	v_mfma_f32_16x16x32_bf16 v[138:141], v[110:113], v[194:197], v[138:141]
	v_mfma_f32_16x16x32_bf16 v[126:129], v[102:105], v[202:205], v[126:129]
	v_mfma_f32_16x16x32_bf16 v[122:125], v[110:113], v[202:205], v[122:125]
	v_mfma_f32_16x16x32_bf16 v[94:97], v[102:105], v[210:213], v[94:97]
	v_mfma_f32_16x16x32_bf16 v[90:93], v[110:113], v[210:213], v[90:93]
	v_mfma_f32_16x16x32_bf16 v[78:81], v[102:105], v[218:221], v[78:81]
	v_mfma_f32_16x16x32_bf16 v[74:77], v[110:113], v[218:221], v[74:77]
	v_mfma_f32_16x16x32_bf16 v[134:137], v[164:167], v[190:193], v[134:137]
	v_mfma_f32_16x16x32_bf16 v[130:133], v[182:185], v[190:193], v[130:133]
	v_mfma_f32_16x16x32_bf16 v[118:121], v[164:167], v[198:201], v[118:121]
	v_mfma_f32_16x16x32_bf16 v[114:117], v[182:185], v[198:201], v[114:117]
	v_mfma_f32_16x16x32_bf16 v[86:89], v[164:167], v[206:209], v[86:89]
	v_mfma_f32_16x16x32_bf16 v[82:85], v[182:185], v[206:209], v[82:85]
	v_mfma_f32_16x16x32_bf16 v[70:73], v[164:167], v[214:217], v[70:73]
	v_mfma_f32_16x16x32_bf16 v[66:69], v[182:185], v[214:217], v[66:69]
	v_mfma_f32_16x16x32_bf16 v[134:137], v[168:171], v[194:197], v[134:137]
	v_mfma_f32_16x16x32_bf16 v[130:133], v[186:189], v[194:197], v[130:133]
	v_mfma_f32_16x16x32_bf16 v[118:121], v[168:171], v[202:205], v[118:121]
	v_mfma_f32_16x16x32_bf16 v[114:117], v[186:189], v[202:205], v[114:117]
	v_mfma_f32_16x16x32_bf16 v[86:89], v[168:171], v[210:213], v[86:89]
	v_mfma_f32_16x16x32_bf16 v[82:85], v[186:189], v[210:213], v[82:85]
	v_mfma_f32_16x16x32_bf16 v[70:73], v[168:171], v[218:221], v[70:73]
	v_mfma_f32_16x16x32_bf16 v[66:69], v[186:189], v[218:221], v[66:69]
	s_barrier
	s_setprio 0
	s_add_i32 s30, s59, s33
	v_lshl_add_u64 v[222:223], v[222:223], 0, s[8:9]
	s_mov_b32 m0, s30
	ds_read_b128 v[190:193], v177 offset:49152
	ds_read_b128 v[194:197], v177 offset:50176
	ds_read_b128 v[198:201], v177 offset:51200
	ds_read_b128 v[202:205], v177 offset:52224
	ds_read_b128 v[206:209], v177 offset:53248
	ds_read_b128 v[210:213], v177 offset:54272
	ds_read_b128 v[214:217], v177 offset:55296
	ds_read_b128 v[218:221], v177 offset:56320
	global_load_lds_dwordx4 v[222:223], off
	s_add_i32 m0, s30, 0x2000
	s_add_u32 s28, s28, 0x80080
	v_lshl_add_u64 v[222:223], v[224:225], 0, s[8:9]
	s_addc_u32 s29, s29, 0
	s_add_i32 s30, s68, s33
	global_load_lds_dwordx4 v[222:223], off
	v_lshl_add_u64 v[222:223], s[28:29], 0, v[152:153]
	s_mov_b32 m0, s30
	s_nop 0
	global_load_lds_dwordx4 v[222:223], off
	v_lshl_add_u64 v[222:223], s[28:29], 0, v[148:149]
	s_add_i32 m0, s30, 0x2000
	s_nop 0
	global_load_lds_dwordx4 v[222:223], off
	v_lshl_add_u64 v[222:223], v[226:227], 0, s[8:9]
	s_mov_b32 m0, s41
	s_nop 0
	global_load_lds_dwordx4 v[222:223], off
	v_lshl_add_u64 v[222:223], v[228:229], 0, s[8:9]
	s_mov_b32 m0, s42
	s_nop 0
	global_load_lds_dwordx4 v[222:223], off
	s_waitcnt vmcnt(8)
	s_waitcnt lgkmcnt(0)
	s_setprio 1
	s_barrier
	v_mfma_f32_16x16x32_bf16 v[62:65], v[98:101], v[190:193], v[62:65]
	v_mfma_f32_16x16x32_bf16 v[58:61], v[106:109], v[190:193], v[58:61]
	v_mfma_f32_16x16x32_bf16 v[46:49], v[98:101], v[198:201], v[46:49]
	v_mfma_f32_16x16x32_bf16 v[42:45], v[106:109], v[198:201], v[42:45]
	v_mfma_f32_16x16x32_bf16 v[30:33], v[98:101], v[206:209], v[30:33]
	v_mfma_f32_16x16x32_bf16 v[26:29], v[106:109], v[206:209], v[26:29]
	v_mfma_f32_16x16x32_bf16 v[14:17], v[98:101], v[214:217], v[14:17]
	v_mfma_f32_16x16x32_bf16 v[10:13], v[106:109], v[214:217], v[10:13]
	v_mfma_f32_16x16x32_bf16 v[62:65], v[102:105], v[194:197], v[62:65]
	v_mfma_f32_16x16x32_bf16 v[58:61], v[110:113], v[194:197], v[58:61]
	v_mfma_f32_16x16x32_bf16 v[46:49], v[102:105], v[202:205], v[46:49]
	v_mfma_f32_16x16x32_bf16 v[42:45], v[110:113], v[202:205], v[42:45]
	v_mfma_f32_16x16x32_bf16 v[30:33], v[102:105], v[210:213], v[30:33]
	v_mfma_f32_16x16x32_bf16 v[26:29], v[110:113], v[210:213], v[26:29]
	v_mfma_f32_16x16x32_bf16 v[14:17], v[102:105], v[218:221], v[14:17]
	v_mfma_f32_16x16x32_bf16 v[10:13], v[110:113], v[218:221], v[10:13]
	v_mfma_f32_16x16x32_bf16 v[54:57], v[164:167], v[190:193], v[54:57]
	v_mfma_f32_16x16x32_bf16 v[50:53], v[182:185], v[190:193], v[50:53]
	v_mfma_f32_16x16x32_bf16 v[38:41], v[164:167], v[198:201], v[38:41]
	v_mfma_f32_16x16x32_bf16 v[34:37], v[182:185], v[198:201], v[34:37]
	v_mfma_f32_16x16x32_bf16 v[22:25], v[164:167], v[206:209], v[22:25]
	v_mfma_f32_16x16x32_bf16 v[18:21], v[182:185], v[206:209], v[18:21]
	v_mfma_f32_16x16x32_bf16 v[6:9], v[164:167], v[214:217], v[6:9]
	v_mfma_f32_16x16x32_bf16 v[2:5], v[182:185], v[214:217], v[2:5]
	v_mfma_f32_16x16x32_bf16 v[54:57], v[168:171], v[194:197], v[54:57]
	v_mfma_f32_16x16x32_bf16 v[50:53], v[186:189], v[194:197], v[50:53]
	v_mfma_f32_16x16x32_bf16 v[38:41], v[168:171], v[202:205], v[38:41]
	v_mfma_f32_16x16x32_bf16 v[34:37], v[186:189], v[202:205], v[34:37]
	v_mfma_f32_16x16x32_bf16 v[22:25], v[168:171], v[210:213], v[22:25]
	v_mfma_f32_16x16x32_bf16 v[18:21], v[186:189], v[210:213], v[18:21]
	v_mfma_f32_16x16x32_bf16 v[6:9], v[168:171], v[218:221], v[6:9]
	v_mfma_f32_16x16x32_bf16 v[2:5], v[186:189], v[218:221], v[2:5]
	s_barrier
	s_setprio 0
	s_add_i32 s58, s58, 2
	s_add_u32 s26, s26, 0x100
	s_addc_u32 s27, s27, 0
	s_add_u32 s56, s56, 0x100
	s_addc_u32 s57, s57, 0
	s_cmp_gt_u32 s58, 29
	s_cbranch_scc0 .LBB0_1208
	s_and_b64 vcc, exec, s[16:17]
	s_cbranch_vccz .LBB0_1211
	s_barrier
.LBB0_1211:
	s_lshl_b32 s19, s6, 8
	v_add_u32_e32 v164, s19, v172
	s_addk_i32 s19, 0xe000
	s_lshr_b32 s19, s19, 12
	s_add_i32 s19, s19, 1
	v_ashrrev_i32_e32 v165, 31, v164
	s_cmp_gt_i32 s6, 31
	v_lshl_add_u64 v[166:167], v[164:165], 2, s[14:15]
	s_cselect_b32 s6, s19, 0
	global_load_dword v198, v[166:167], off
	global_load_dword v199, v[166:167], off offset:64
	global_load_dword v200, v[166:167], off offset:128
	global_load_dword v201, v[166:167], off offset:192
	global_load_dword v202, v[166:167], off offset:512
	global_load_dword v203, v[166:167], off offset:576
	global_load_dword v204, v[166:167], off offset:640
	global_load_dword v205, v[166:167], off offset:704
	s_mul_hi_u32 s19, s6, 0xb000
	s_mul_i32 s6, s6, 0xb000
	s_add_u32 s6, s12, s6
	s_addc_u32 s19, s13, s19
	s_lshl_b32 s26, s7, 8
	s_ashr_i32 s27, s26, 31
	s_lshl_b64 s[26:27], s[26:27], 2
	s_add_u32 s6, s6, s26
	s_addc_u32 s19, s19, s27
	s_add_u32 s26, s6, s47
	s_addc_u32 s27, s19, 0
	global_load_dwordx4 v[102:105], v179, s[26:27]
	global_load_dwordx4 v[110:113], v179, s[26:27] offset:512
	global_load_dwordx4 v[98:101], v179, s[26:27] offset:16
	global_load_dwordx4 v[106:109], v179, s[26:27] offset:528
	v_or_b32_e32 v184, 16, v164
	v_ashrrev_i32_e32 v185, 31, v184
	v_lshl_add_u64 v[186:187], v[184:185], 2, s[14:15]
	v_lshl_or_b32 v170, s7, 7, v174
	v_mov_b64_e32 v[168:169], s[54:55]
	v_ashrrev_i32_e32 v171, 31, v170
	v_mad_i64_i32 v[182:183], s[6:7], v164, s49, v[168:169]
	v_lshlrev_b64 v[170:171], 1, v[170:171]
	v_lshl_add_u64 v[182:183], v[182:183], 0, v[170:171]
	s_waitcnt vmcnt(0)
	v_fmamk_f32 v165, v198, 0x3a000000, v180
	v_mul_f32_e32 v181, 0x4b800000, v165
	v_cmp_gt_f32_e32 vcc, s48, v165
	s_nop 1
	v_cndmask_b32_e32 v165, v165, v181, vcc
	v_rsq_f32_e32 v165, v165
	s_nop 0
	v_mul_f32_e32 v181, 0x45800000, v165
	v_cndmask_b32_e32 v188, v165, v181, vcc
	v_pk_fma_f32 v[142:143], v[142:143], v[188:189], v[102:103] op_sel_hi:[1,0,1]
	v_pk_fma_f32 v[138:139], v[138:139], v[188:189], v[98:99] op_sel_hi:[1,0,1]
	v_pk_fma_f32 v[144:145], v[144:145], v[188:189], v[104:105] op_sel_hi:[1,0,1]
	v_pk_fma_f32 v[140:141], v[140:141], v[188:189], v[100:101] op_sel_hi:[1,0,1]
	v_pk_fma_f32 v[134:135], v[134:135], v[188:189], v[110:111] op_sel_hi:[1,0,1]
	v_pk_fma_f32 v[130:131], v[130:131], v[188:189], v[106:107] op_sel_hi:[1,0,1]
	v_pk_fma_f32 v[136:137], v[136:137], v[188:189], v[112:113] op_sel_hi:[1,0,1]
	v_pk_fma_f32 v[132:133], v[132:133], v[188:189], v[108:109] op_sel_hi:[1,0,1]
	v_mul_f32_e32 v165, 0xbfb8aa3b, v142
	v_mul_f32_e32 v181, 0xbfb8aa3b, v143
	v_mul_f32_e32 v185, 0xbfb8aa3b, v138
	v_mul_f32_e32 v188, 0xbfb8aa3b, v139
	v_mul_f32_e32 v189, 0xbfb8aa3b, v144
	v_mul_f32_e32 v190, 0xbfb8aa3b, v145
	v_mul_f32_e32 v191, 0xbfb8aa3b, v140
	v_mul_f32_e32 v192, 0xbfb8aa3b, v141
	v_exp_f32_e32 v165, v165
	v_exp_f32_e32 v181, v181
	v_exp_f32_e32 v185, v185
	v_exp_f32_e32 v188, v188
	v_exp_f32_e32 v189, v189
	v_exp_f32_e32 v190, v190
	v_exp_f32_e32 v191, v191
	v_exp_f32_e32 v192, v192
	v_add_f32_e32 v165, 1.0, v165
	v_add_f32_e32 v181, 1.0, v181
	v_add_f32_e32 v185, 1.0, v185
	v_add_f32_e32 v193, 1.0, v188
	v_add_f32_e32 v194, 1.0, v189
	v_add_f32_e32 v195, 1.0, v190
	v_add_f32_e32 v196, 1.0, v191
	v_add_f32_e32 v197, 1.0, v192
	v_rcp_f32_e32 v188, v165
	v_rcp_f32_e32 v189, v181
	v_rcp_f32_e32 v190, v185
	v_rcp_f32_e32 v191, v193
	v_rcp_f32_e32 v192, v194
	v_rcp_f32_e32 v193, v195
	v_rcp_f32_e32 v194, v196
	v_rcp_f32_e32 v195, v197
	v_pk_mul_f32 v[142:143], v[142:143], v[188:189]
	v_pk_mul_f32 v[138:139], v[138:139], v[190:191]
	v_pk_mul_f32 v[144:145], v[144:145], v[192:193]
	v_pk_mul_f32 v[140:141], v[140:141], v[194:195]
	v_pk_mul_f32 v[134:135], v[134:135], v[142:143]
	v_pk_mul_f32 v[138:139], v[130:131], v[138:139]
	v_pk_mul_f32 v[136:137], v[136:137], v[144:145]
	v_pk_mul_f32 v[140:141], v[132:133], v[140:141]
	v_cvt_pk_bf16_f32 v130, v134, v135
	v_cvt_pk_bf16_f32 v131, v136, v137
	v_cvt_pk_bf16_f32 v132, v138, v139
	v_cvt_pk_bf16_f32 v133, v140, v141
	global_store_dwordx4 v[182:183], v[130:133], off nt
	s_nop 0
	s_nop 0
	v_or_b32_e32 v130, 32, v164
	v_mad_i64_i32 v[132:133], s[6:7], v184, s49, v[168:169]
	v_lshl_add_u64 v[132:133], v[132:133], 0, v[170:171]
	s_nop 0
	v_fmamk_f32 v131, v199, 0x3a000000, v180
	v_mul_f32_e32 v134, 0x4b800000, v131
	v_cmp_gt_f32_e32 vcc, s48, v131
	s_nop 1
	v_cndmask_b32_e32 v131, v131, v134, vcc
	v_rsq_f32_e32 v136, v131
	v_ashrrev_i32_e32 v131, 31, v130
	v_lshl_add_u64 v[134:135], v[130:131], 2, s[14:15]
	v_mul_f32_e32 v131, 0x45800000, v136
	v_cndmask_b32_e32 v136, v136, v131, vcc
	v_pk_fma_f32 v[126:127], v[126:127], v[136:137], v[102:103] op_sel_hi:[1,0,1]
	v_pk_fma_f32 v[122:123], v[122:123], v[136:137], v[98:99] op_sel_hi:[1,0,1]
	v_pk_fma_f32 v[128:129], v[128:129], v[136:137], v[104:105] op_sel_hi:[1,0,1]
	v_pk_fma_f32 v[124:125], v[124:125], v[136:137], v[100:101] op_sel_hi:[1,0,1]
	v_pk_fma_f32 v[118:119], v[118:119], v[136:137], v[110:111] op_sel_hi:[1,0,1]
	v_pk_fma_f32 v[114:115], v[114:115], v[136:137], v[106:107] op_sel_hi:[1,0,1]
	v_pk_fma_f32 v[120:121], v[120:121], v[136:137], v[112:113] op_sel_hi:[1,0,1]
	v_pk_fma_f32 v[116:117], v[116:117], v[136:137], v[108:109] op_sel_hi:[1,0,1]
	v_mul_f32_e32 v131, 0xbfb8aa3b, v126
	v_mul_f32_e32 v136, 0xbfb8aa3b, v127
	v_mul_f32_e32 v137, 0xbfb8aa3b, v122
	v_mul_f32_e32 v138, 0xbfb8aa3b, v123
	v_mul_f32_e32 v139, 0xbfb8aa3b, v128
	v_mul_f32_e32 v140, 0xbfb8aa3b, v129
	v_mul_f32_e32 v141, 0xbfb8aa3b, v124
	v_mul_f32_e32 v142, 0xbfb8aa3b, v125
	v_exp_f32_e32 v131, v131
	v_exp_f32_e32 v136, v136
	v_exp_f32_e32 v137, v137
	v_exp_f32_e32 v138, v138
	v_exp_f32_e32 v139, v139
	v_exp_f32_e32 v140, v140
	v_exp_f32_e32 v141, v141
	v_exp_f32_e32 v142, v142
	v_add_f32_e32 v131, 1.0, v131
	v_add_f32_e32 v143, 1.0, v136
	v_add_f32_e32 v144, 1.0, v137
	v_add_f32_e32 v145, 1.0, v138
	v_add_f32_e32 v165, 1.0, v139
	v_add_f32_e32 v181, 1.0, v140
	v_add_f32_e32 v182, 1.0, v141
	v_add_f32_e32 v183, 1.0, v142
	v_rcp_f32_e32 v136, v131
	v_rcp_f32_e32 v137, v143
	v_rcp_f32_e32 v138, v144
	v_rcp_f32_e32 v139, v145
	v_rcp_f32_e32 v140, v165
	v_rcp_f32_e32 v141, v181
	v_rcp_f32_e32 v142, v182
	v_rcp_f32_e32 v143, v183
	v_pk_mul_f32 v[126:127], v[126:127], v[136:137]
	v_pk_mul_f32 v[122:123], v[122:123], v[138:139]
	v_pk_mul_f32 v[128:129], v[128:129], v[140:141]
	v_pk_mul_f32 v[124:125], v[124:125], v[142:143]
	v_pk_mul_f32 v[118:119], v[118:119], v[126:127]
	v_pk_mul_f32 v[122:123], v[114:115], v[122:123]
	v_pk_mul_f32 v[120:121], v[120:121], v[128:129]
	v_pk_mul_f32 v[124:125], v[116:117], v[124:125]
	v_cvt_pk_bf16_f32 v114, v118, v119
	v_cvt_pk_bf16_f32 v115, v120, v121
	v_cvt_pk_bf16_f32 v116, v122, v123
	v_cvt_pk_bf16_f32 v117, v124, v125
	global_store_dwordx4 v[132:133], v[114:117], off nt
	s_nop 0
	s_nop 0
	v_or_b32_e32 v114, 48, v164
	v_mad_i64_i32 v[116:117], s[6:7], v130, s49, v[168:169]
	v_lshl_add_u64 v[116:117], v[116:117], 0, v[170:171]
	s_nop 0
	v_fmamk_f32 v115, v200, 0x3a000000, v180
	v_mul_f32_e32 v118, 0x4b800000, v115
	v_cmp_gt_f32_e32 vcc, s48, v115
	s_nop 1
	v_cndmask_b32_e32 v115, v115, v118, vcc
	v_rsq_f32_e32 v120, v115
	v_ashrrev_i32_e32 v115, 31, v114
	v_lshl_add_u64 v[118:119], v[114:115], 2, s[14:15]
	v_mul_f32_e32 v115, 0x45800000, v120
	v_cndmask_b32_e32 v120, v120, v115, vcc
	v_pk_fma_f32 v[94:95], v[94:95], v[120:121], v[102:103] op_sel_hi:[1,0,1]
	v_pk_fma_f32 v[90:91], v[90:91], v[120:121], v[98:99] op_sel_hi:[1,0,1]
	v_pk_fma_f32 v[96:97], v[96:97], v[120:121], v[104:105] op_sel_hi:[1,0,1]
	v_pk_fma_f32 v[92:93], v[92:93], v[120:121], v[100:101] op_sel_hi:[1,0,1]
	v_pk_fma_f32 v[86:87], v[86:87], v[120:121], v[110:111] op_sel_hi:[1,0,1]
	v_pk_fma_f32 v[82:83], v[82:83], v[120:121], v[106:107] op_sel_hi:[1,0,1]
	v_pk_fma_f32 v[88:89], v[88:89], v[120:121], v[112:113] op_sel_hi:[1,0,1]
	v_pk_fma_f32 v[84:85], v[84:85], v[120:121], v[108:109] op_sel_hi:[1,0,1]
	v_mul_f32_e32 v115, 0xbfb8aa3b, v94
	v_mul_f32_e32 v120, 0xbfb8aa3b, v95
	v_mul_f32_e32 v121, 0xbfb8aa3b, v90
	v_mul_f32_e32 v122, 0xbfb8aa3b, v91
	v_mul_f32_e32 v123, 0xbfb8aa3b, v96
	v_mul_f32_e32 v124, 0xbfb8aa3b, v97
	v_mul_f32_e32 v125, 0xbfb8aa3b, v92
	v_mul_f32_e32 v126, 0xbfb8aa3b, v93
	v_exp_f32_e32 v115, v115
	v_exp_f32_e32 v120, v120
	v_exp_f32_e32 v121, v121
	v_exp_f32_e32 v122, v122
	v_exp_f32_e32 v123, v123
	v_exp_f32_e32 v124, v124
	v_exp_f32_e32 v125, v125
	v_exp_f32_e32 v126, v126
	v_add_f32_e32 v115, 1.0, v115
	v_add_f32_e32 v127, 1.0, v120
	v_add_f32_e32 v128, 1.0, v121
	v_add_f32_e32 v129, 1.0, v122
	v_add_f32_e32 v130, 1.0, v123
	v_add_f32_e32 v131, 1.0, v124
	v_add_f32_e32 v132, 1.0, v125
	v_add_f32_e32 v133, 1.0, v126
	v_rcp_f32_e32 v120, v115
	v_rcp_f32_e32 v121, v127
	v_rcp_f32_e32 v122, v128
	v_rcp_f32_e32 v123, v129
	v_rcp_f32_e32 v124, v130
	v_rcp_f32_e32 v125, v131
	v_rcp_f32_e32 v126, v132
	v_rcp_f32_e32 v127, v133
	v_pk_mul_f32 v[94:95], v[94:95], v[120:121]
	v_pk_mul_f32 v[90:91], v[90:91], v[122:123]
	v_pk_mul_f32 v[96:97], v[96:97], v[124:125]
	v_pk_mul_f32 v[92:93], v[92:93], v[126:127]
	v_pk_mul_f32 v[86:87], v[86:87], v[94:95]
	v_pk_mul_f32 v[90:91], v[82:83], v[90:91]
	v_pk_mul_f32 v[88:89], v[88:89], v[96:97]
	v_pk_mul_f32 v[92:93], v[84:85], v[92:93]
	v_cvt_pk_bf16_f32 v82, v86, v87
	v_cvt_pk_bf16_f32 v83, v88, v89
	v_cvt_pk_bf16_f32 v84, v90, v91
	v_cvt_pk_bf16_f32 v85, v92, v93
	global_store_dwordx4 v[116:117], v[82:85], off nt
	s_nop 0
	s_nop 0
	v_fmamk_f32 v82, v201, 0x3a000000, v180
	v_mul_f32_e32 v83, 0x4b800000, v82
	v_cmp_gt_f32_e32 vcc, s48, v82
	s_nop 1
	v_cndmask_b32_e32 v82, v82, v83, vcc
	v_rsq_f32_e32 v84, v82
	v_mad_i64_i32 v[82:83], s[6:7], v114, s49, v[168:169]
	v_lshl_add_u64 v[82:83], v[82:83], 0, v[170:171]
	v_mul_f32_e32 v85, 0x45800000, v84
	v_cndmask_b32_e32 v84, v84, v85, vcc
	v_pk_fma_f32 v[78:79], v[78:79], v[84:85], v[102:103] op_sel_hi:[1,0,1]
	v_pk_fma_f32 v[74:75], v[74:75], v[84:85], v[98:99] op_sel_hi:[1,0,1]
	v_pk_fma_f32 v[80:81], v[80:81], v[84:85], v[104:105] op_sel_hi:[1,0,1]
	v_pk_fma_f32 v[76:77], v[76:77], v[84:85], v[100:101] op_sel_hi:[1,0,1]
	v_pk_fma_f32 v[70:71], v[70:71], v[84:85], v[110:111] op_sel_hi:[1,0,1]
	v_pk_fma_f32 v[66:67], v[66:67], v[84:85], v[106:107] op_sel_hi:[1,0,1]
	v_pk_fma_f32 v[72:73], v[72:73], v[84:85], v[112:113] op_sel_hi:[1,0,1]
	v_pk_fma_f32 v[68:69], v[68:69], v[84:85], v[108:109] op_sel_hi:[1,0,1]
	v_mul_f32_e32 v84, 0xbfb8aa3b, v78
	v_mul_f32_e32 v85, 0xbfb8aa3b, v79
	v_mul_f32_e32 v86, 0xbfb8aa3b, v74
	v_mul_f32_e32 v87, 0xbfb8aa3b, v75
	v_mul_f32_e32 v88, 0xbfb8aa3b, v80
	v_mul_f32_e32 v89, 0xbfb8aa3b, v81
	v_mul_f32_e32 v90, 0xbfb8aa3b, v76
	v_mul_f32_e32 v91, 0xbfb8aa3b, v77
	v_exp_f32_e32 v84, v84
	v_exp_f32_e32 v85, v85
	v_exp_f32_e32 v86, v86
	v_exp_f32_e32 v87, v87
	v_exp_f32_e32 v88, v88
	v_exp_f32_e32 v89, v89
	v_exp_f32_e32 v90, v90
	v_exp_f32_e32 v91, v91
	v_add_f32_e32 v84, 1.0, v84
	v_add_f32_e32 v85, 1.0, v85
	v_add_f32_e32 v86, 1.0, v86
	v_add_f32_e32 v87, 1.0, v87
	v_add_f32_e32 v88, 1.0, v88
	v_add_f32_e32 v89, 1.0, v89
	v_add_f32_e32 v90, 1.0, v90
	v_add_f32_e32 v91, 1.0, v91
	v_rcp_f32_e32 v84, v84
	v_rcp_f32_e32 v85, v85
	v_rcp_f32_e32 v86, v86
	v_rcp_f32_e32 v87, v87
	v_rcp_f32_e32 v88, v88
	v_rcp_f32_e32 v89, v89
	v_rcp_f32_e32 v90, v90
	v_rcp_f32_e32 v91, v91
	v_pk_mul_f32 v[78:79], v[78:79], v[84:85]
	v_pk_mul_f32 v[74:75], v[74:75], v[86:87]
	v_pk_mul_f32 v[80:81], v[80:81], v[88:89]
	v_pk_mul_f32 v[76:77], v[76:77], v[90:91]
	v_pk_mul_f32 v[70:71], v[70:71], v[78:79]
	v_pk_mul_f32 v[74:75], v[66:67], v[74:75]
	v_pk_mul_f32 v[72:73], v[72:73], v[80:81]
	v_pk_mul_f32 v[76:77], v[68:69], v[76:77]
	v_cvt_pk_bf16_f32 v66, v70, v71
	v_cvt_pk_bf16_f32 v67, v72, v73
	v_cvt_pk_bf16_f32 v68, v74, v75
	v_cvt_pk_bf16_f32 v69, v76, v77
	global_store_dwordx4 v[82:83], v[66:69], off nt
	s_nop 0
	s_nop 0
	v_add_u32_e32 v67, 0x80, v164
	s_nop 0
	v_fmamk_f32 v66, v202, 0x3a000000, v180
	v_mul_f32_e32 v68, 0x4b800000, v66
	v_cmp_gt_f32_e32 vcc, s48, v66
	s_nop 1
	v_cndmask_b32_e32 v66, v66, v68, vcc
	v_rsq_f32_e32 v68, v66
	v_mad_i64_i32 v[66:67], s[6:7], v67, s49, v[168:169]
	v_lshl_add_u64 v[66:67], v[66:67], 0, v[170:171]
	v_mul_f32_e32 v69, 0x45800000, v68
	v_cndmask_b32_e32 v68, v68, v69, vcc
	v_pk_fma_f32 v[62:63], v[62:63], v[68:69], v[102:103] op_sel_hi:[1,0,1]
	v_pk_fma_f32 v[58:59], v[58:59], v[68:69], v[98:99] op_sel_hi:[1,0,1]
	v_pk_fma_f32 v[64:65], v[64:65], v[68:69], v[104:105] op_sel_hi:[1,0,1]
	v_pk_fma_f32 v[60:61], v[60:61], v[68:69], v[100:101] op_sel_hi:[1,0,1]
	v_pk_fma_f32 v[54:55], v[54:55], v[68:69], v[110:111] op_sel_hi:[1,0,1]
	v_pk_fma_f32 v[50:51], v[50:51], v[68:69], v[106:107] op_sel_hi:[1,0,1]
	v_pk_fma_f32 v[56:57], v[56:57], v[68:69], v[112:113] op_sel_hi:[1,0,1]
	v_pk_fma_f32 v[52:53], v[52:53], v[68:69], v[108:109] op_sel_hi:[1,0,1]
	v_mul_f32_e32 v68, 0xbfb8aa3b, v62
	v_mul_f32_e32 v69, 0xbfb8aa3b, v63
	v_mul_f32_e32 v70, 0xbfb8aa3b, v58
	v_mul_f32_e32 v71, 0xbfb8aa3b, v59
	v_mul_f32_e32 v72, 0xbfb8aa3b, v64
	v_mul_f32_e32 v73, 0xbfb8aa3b, v65
	v_mul_f32_e32 v74, 0xbfb8aa3b, v60
	v_mul_f32_e32 v75, 0xbfb8aa3b, v61
	v_exp_f32_e32 v68, v68
	v_exp_f32_e32 v69, v69
	v_exp_f32_e32 v70, v70
	v_exp_f32_e32 v71, v71
	v_exp_f32_e32 v72, v72
	v_exp_f32_e32 v73, v73
	v_exp_f32_e32 v74, v74
	v_exp_f32_e32 v75, v75
	v_add_f32_e32 v68, 1.0, v68
	v_add_f32_e32 v69, 1.0, v69
	v_add_f32_e32 v70, 1.0, v70
	v_add_f32_e32 v71, 1.0, v71
	v_add_f32_e32 v72, 1.0, v72
	v_add_f32_e32 v73, 1.0, v73
	v_add_f32_e32 v74, 1.0, v74
	v_add_f32_e32 v75, 1.0, v75
	v_rcp_f32_e32 v68, v68
	v_rcp_f32_e32 v69, v69
	v_rcp_f32_e32 v70, v70
	v_rcp_f32_e32 v71, v71
	v_rcp_f32_e32 v72, v72
	v_rcp_f32_e32 v73, v73
	v_rcp_f32_e32 v74, v74
	v_rcp_f32_e32 v75, v75
	v_pk_mul_f32 v[62:63], v[62:63], v[68:69]
	v_pk_mul_f32 v[58:59], v[58:59], v[70:71]
	v_pk_mul_f32 v[64:65], v[64:65], v[72:73]
	v_pk_mul_f32 v[60:61], v[60:61], v[74:75]
	v_pk_mul_f32 v[54:55], v[54:55], v[62:63]
	v_pk_mul_f32 v[58:59], v[50:51], v[58:59]
	v_pk_mul_f32 v[56:57], v[56:57], v[64:65]
	v_pk_mul_f32 v[60:61], v[52:53], v[60:61]
	v_cvt_pk_bf16_f32 v50, v54, v55
	v_cvt_pk_bf16_f32 v51, v56, v57
	v_cvt_pk_bf16_f32 v52, v58, v59
	v_cvt_pk_bf16_f32 v53, v60, v61
	global_store_dwordx4 v[66:67], v[50:53], off nt
	s_nop 0
	s_nop 0
	v_add_u32_e32 v51, 0x90, v164
	s_nop 0
	v_fmamk_f32 v50, v203, 0x3a000000, v180
	v_mul_f32_e32 v52, 0x4b800000, v50
	v_cmp_gt_f32_e32 vcc, s48, v50
	s_nop 1
	v_cndmask_b32_e32 v50, v50, v52, vcc
	v_rsq_f32_e32 v52, v50
	v_mad_i64_i32 v[50:51], s[6:7], v51, s49, v[168:169]
	v_lshl_add_u64 v[50:51], v[50:51], 0, v[170:171]
	v_mul_f32_e32 v53, 0x45800000, v52
	v_cndmask_b32_e32 v52, v52, v53, vcc
	v_pk_fma_f32 v[46:47], v[46:47], v[52:53], v[102:103] op_sel_hi:[1,0,1]
	v_pk_fma_f32 v[42:43], v[42:43], v[52:53], v[98:99] op_sel_hi:[1,0,1]
	v_pk_fma_f32 v[48:49], v[48:49], v[52:53], v[104:105] op_sel_hi:[1,0,1]
	v_pk_fma_f32 v[44:45], v[44:45], v[52:53], v[100:101] op_sel_hi:[1,0,1]
	v_pk_fma_f32 v[38:39], v[38:39], v[52:53], v[110:111] op_sel_hi:[1,0,1]
	v_pk_fma_f32 v[34:35], v[34:35], v[52:53], v[106:107] op_sel_hi:[1,0,1]
	v_pk_fma_f32 v[40:41], v[40:41], v[52:53], v[112:113] op_sel_hi:[1,0,1]
	v_pk_fma_f32 v[36:37], v[36:37], v[52:53], v[108:109] op_sel_hi:[1,0,1]
	v_mul_f32_e32 v52, 0xbfb8aa3b, v46
	v_mul_f32_e32 v53, 0xbfb8aa3b, v47
	v_mul_f32_e32 v54, 0xbfb8aa3b, v42
	v_mul_f32_e32 v55, 0xbfb8aa3b, v43
	v_mul_f32_e32 v56, 0xbfb8aa3b, v48
	v_mul_f32_e32 v57, 0xbfb8aa3b, v49
	v_mul_f32_e32 v58, 0xbfb8aa3b, v44
	v_mul_f32_e32 v59, 0xbfb8aa3b, v45
	v_exp_f32_e32 v52, v52
	v_exp_f32_e32 v53, v53
	v_exp_f32_e32 v54, v54
	v_exp_f32_e32 v55, v55
	v_exp_f32_e32 v56, v56
	v_exp_f32_e32 v57, v57
	v_exp_f32_e32 v58, v58
	v_exp_f32_e32 v59, v59
	v_add_f32_e32 v52, 1.0, v52
	v_add_f32_e32 v53, 1.0, v53
	v_add_f32_e32 v54, 1.0, v54
	v_add_f32_e32 v55, 1.0, v55
	v_add_f32_e32 v56, 1.0, v56
	v_add_f32_e32 v57, 1.0, v57
	v_add_f32_e32 v58, 1.0, v58
	v_add_f32_e32 v59, 1.0, v59
	v_rcp_f32_e32 v52, v52
	v_rcp_f32_e32 v53, v53
	v_rcp_f32_e32 v54, v54
	v_rcp_f32_e32 v55, v55
	v_rcp_f32_e32 v56, v56
	v_rcp_f32_e32 v57, v57
	v_rcp_f32_e32 v58, v58
	v_rcp_f32_e32 v59, v59
	v_pk_mul_f32 v[46:47], v[46:47], v[52:53]
	v_pk_mul_f32 v[42:43], v[42:43], v[54:55]
	v_pk_mul_f32 v[48:49], v[48:49], v[56:57]
	v_pk_mul_f32 v[44:45], v[44:45], v[58:59]
	v_pk_mul_f32 v[38:39], v[38:39], v[46:47]
	v_pk_mul_f32 v[42:43], v[34:35], v[42:43]
	v_pk_mul_f32 v[40:41], v[40:41], v[48:49]
	v_pk_mul_f32 v[44:45], v[36:37], v[44:45]
	v_cvt_pk_bf16_f32 v34, v38, v39
	v_cvt_pk_bf16_f32 v35, v40, v41
	v_cvt_pk_bf16_f32 v36, v42, v43
	v_cvt_pk_bf16_f32 v37, v44, v45
	global_store_dwordx4 v[50:51], v[34:37], off nt
	s_nop 0
	s_nop 0
	v_add_u32_e32 v35, 0xa0, v164
	s_nop 0
	v_fmamk_f32 v34, v204, 0x3a000000, v180
	v_mul_f32_e32 v36, 0x4b800000, v34
	v_cmp_gt_f32_e32 vcc, s48, v34
	s_nop 1
	v_cndmask_b32_e32 v34, v34, v36, vcc
	v_rsq_f32_e32 v36, v34
	v_mad_i64_i32 v[34:35], s[6:7], v35, s49, v[168:169]
	v_lshl_add_u64 v[34:35], v[34:35], 0, v[170:171]
	v_mul_f32_e32 v37, 0x45800000, v36
	v_cndmask_b32_e32 v36, v36, v37, vcc
	v_pk_fma_f32 v[30:31], v[30:31], v[36:37], v[102:103] op_sel_hi:[1,0,1]
	v_pk_fma_f32 v[26:27], v[26:27], v[36:37], v[98:99] op_sel_hi:[1,0,1]
	v_pk_fma_f32 v[32:33], v[32:33], v[36:37], v[104:105] op_sel_hi:[1,0,1]
	v_pk_fma_f32 v[28:29], v[28:29], v[36:37], v[100:101] op_sel_hi:[1,0,1]
	v_pk_fma_f32 v[22:23], v[22:23], v[36:37], v[110:111] op_sel_hi:[1,0,1]
	v_pk_fma_f32 v[18:19], v[18:19], v[36:37], v[106:107] op_sel_hi:[1,0,1]
	v_pk_fma_f32 v[24:25], v[24:25], v[36:37], v[112:113] op_sel_hi:[1,0,1]
	v_pk_fma_f32 v[20:21], v[20:21], v[36:37], v[108:109] op_sel_hi:[1,0,1]
	v_mul_f32_e32 v36, 0xbfb8aa3b, v30
	v_mul_f32_e32 v37, 0xbfb8aa3b, v31
	v_mul_f32_e32 v38, 0xbfb8aa3b, v26
	v_mul_f32_e32 v39, 0xbfb8aa3b, v27
	v_mul_f32_e32 v40, 0xbfb8aa3b, v32
	v_mul_f32_e32 v41, 0xbfb8aa3b, v33
	v_mul_f32_e32 v42, 0xbfb8aa3b, v28
	v_mul_f32_e32 v43, 0xbfb8aa3b, v29
	v_exp_f32_e32 v36, v36
	v_exp_f32_e32 v37, v37
	v_exp_f32_e32 v38, v38
	v_exp_f32_e32 v39, v39
	v_exp_f32_e32 v40, v40
	v_exp_f32_e32 v41, v41
	v_exp_f32_e32 v42, v42
	v_exp_f32_e32 v43, v43
	v_add_f32_e32 v36, 1.0, v36
	v_add_f32_e32 v37, 1.0, v37
	v_add_f32_e32 v38, 1.0, v38
	v_add_f32_e32 v39, 1.0, v39
	v_add_f32_e32 v40, 1.0, v40
	v_add_f32_e32 v41, 1.0, v41
	v_add_f32_e32 v42, 1.0, v42
	v_add_f32_e32 v43, 1.0, v43
	v_rcp_f32_e32 v36, v36
	v_rcp_f32_e32 v37, v37
	v_rcp_f32_e32 v38, v38
	v_rcp_f32_e32 v39, v39
	v_rcp_f32_e32 v40, v40
	v_rcp_f32_e32 v41, v41
	v_rcp_f32_e32 v42, v42
	v_rcp_f32_e32 v43, v43
	v_pk_mul_f32 v[30:31], v[30:31], v[36:37]
	v_pk_mul_f32 v[26:27], v[26:27], v[38:39]
	v_pk_mul_f32 v[32:33], v[32:33], v[40:41]
	v_pk_mul_f32 v[28:29], v[28:29], v[42:43]
	v_pk_mul_f32 v[22:23], v[22:23], v[30:31]
	v_pk_mul_f32 v[26:27], v[18:19], v[26:27]
	v_pk_mul_f32 v[24:25], v[24:25], v[32:33]
	v_pk_mul_f32 v[28:29], v[20:21], v[28:29]
	v_cvt_pk_bf16_f32 v18, v22, v23
	v_cvt_pk_bf16_f32 v19, v24, v25
	v_cvt_pk_bf16_f32 v20, v26, v27
	v_cvt_pk_bf16_f32 v21, v28, v29
	global_store_dwordx4 v[34:35], v[18:21], off nt
	s_nop 0
	s_andn2_b64 vcc, exec, s[0:1]
	v_add_u32_e32 v19, 0xb0, v164
	s_mov_b64 s[0:1], -1
	s_nop 0
	v_fmamk_f32 v18, v205, 0x3a000000, v180
	v_mul_f32_e32 v20, 0x4b800000, v18
	v_cmp_gt_f32_e64 s[6:7], s48, v18
	s_nop 1
	v_cndmask_b32_e64 v18, v18, v20, s[6:7]
	v_rsq_f32_e32 v20, v18
	v_mad_i64_i32 v[18:19], s[26:27], v19, s49, v[168:169]
	v_lshl_add_u64 v[18:19], v[18:19], 0, v[170:171]
	v_mul_f32_e32 v21, 0x45800000, v20
	v_cndmask_b32_e64 v20, v20, v21, s[6:7]
	v_pk_fma_f32 v[14:15], v[14:15], v[20:21], v[102:103] op_sel_hi:[1,0,1]
	v_pk_fma_f32 v[10:11], v[10:11], v[20:21], v[98:99] op_sel_hi:[1,0,1]
	v_pk_fma_f32 v[16:17], v[16:17], v[20:21], v[104:105] op_sel_hi:[1,0,1]
	v_pk_fma_f32 v[12:13], v[12:13], v[20:21], v[100:101] op_sel_hi:[1,0,1]
	v_pk_fma_f32 v[6:7], v[6:7], v[20:21], v[110:111] op_sel_hi:[1,0,1]
	v_pk_fma_f32 v[2:3], v[2:3], v[20:21], v[106:107] op_sel_hi:[1,0,1]
	v_pk_fma_f32 v[8:9], v[8:9], v[20:21], v[112:113] op_sel_hi:[1,0,1]
	v_pk_fma_f32 v[4:5], v[4:5], v[20:21], v[108:109] op_sel_hi:[1,0,1]
	v_mul_f32_e32 v20, 0xbfb8aa3b, v14
	v_mul_f32_e32 v21, 0xbfb8aa3b, v15
	v_mul_f32_e32 v22, 0xbfb8aa3b, v10
	v_mul_f32_e32 v23, 0xbfb8aa3b, v11
	v_mul_f32_e32 v24, 0xbfb8aa3b, v16
	v_mul_f32_e32 v25, 0xbfb8aa3b, v17
	v_mul_f32_e32 v26, 0xbfb8aa3b, v12
	v_mul_f32_e32 v27, 0xbfb8aa3b, v13
	v_exp_f32_e32 v20, v20
	v_exp_f32_e32 v21, v21
	v_exp_f32_e32 v22, v22
	v_exp_f32_e32 v23, v23
	v_exp_f32_e32 v24, v24
	v_exp_f32_e32 v25, v25
	v_exp_f32_e32 v26, v26
	v_exp_f32_e32 v27, v27
	v_add_f32_e32 v20, 1.0, v20
	v_add_f32_e32 v21, 1.0, v21
	v_add_f32_e32 v22, 1.0, v22
	v_add_f32_e32 v23, 1.0, v23
	v_add_f32_e32 v24, 1.0, v24
	v_add_f32_e32 v25, 1.0, v25
	v_add_f32_e32 v26, 1.0, v26
	v_add_f32_e32 v27, 1.0, v27
	v_rcp_f32_e32 v20, v20
	v_rcp_f32_e32 v21, v21
	v_rcp_f32_e32 v22, v22
	v_rcp_f32_e32 v23, v23
	v_rcp_f32_e32 v24, v24
	v_rcp_f32_e32 v25, v25
	v_rcp_f32_e32 v26, v26
	v_rcp_f32_e32 v27, v27
	v_pk_mul_f32 v[14:15], v[14:15], v[20:21]
	v_pk_mul_f32 v[10:11], v[10:11], v[22:23]
	v_pk_mul_f32 v[16:17], v[16:17], v[24:25]
	v_pk_mul_f32 v[12:13], v[12:13], v[26:27]
	v_pk_mul_f32 v[6:7], v[6:7], v[14:15]
	v_pk_mul_f32 v[10:11], v[2:3], v[10:11]
	v_pk_mul_f32 v[8:9], v[8:9], v[16:17]
	v_pk_mul_f32 v[12:13], v[4:5], v[12:13]
	v_cvt_pk_bf16_f32 v2, v6, v7
	v_cvt_pk_bf16_f32 v3, v8, v9
	v_cvt_pk_bf16_f32 v4, v10, v11
	v_cvt_pk_bf16_f32 v5, v12, v13
	global_store_dwordx4 v[18:19], v[2:5], off nt
	s_cbranch_vccnz .LBB0_1204
	s_andn2_b64 vcc, exec, s[2:3]
	s_cbranch_vccnz .LBB0_1203
	s_branch .LBB0_1203

.LBB0_1283:
	s_add_u32 s58, s28, 0x100
	v_mov_b32_e32 v2, 0
	s_addc_u32 s59, s29, 0
	s_mov_b32 s60, -2
	v_mov_b32_e32 v3, v2
	v_mov_b32_e32 v4, v2
	v_mov_b32_e32 v5, v2
	v_mov_b32_e32 v6, v2
	v_mov_b32_e32 v7, v2
	v_mov_b32_e32 v8, v2
	v_mov_b32_e32 v9, v2
	v_mov_b32_e32 v18, v2
	v_mov_b32_e32 v19, v2
	v_mov_b32_e32 v20, v2
	v_mov_b32_e32 v21, v2
	s_waitcnt vmcnt(0)
	v_mov_b32_e32 v22, v2
	v_mov_b32_e32 v23, v2
	v_mov_b32_e32 v24, v2
	v_mov_b32_e32 v25, v2
	v_mov_b32_e32 v34, v2
	v_mov_b32_e32 v35, v2
	v_mov_b32_e32 v36, v2
	v_mov_b32_e32 v37, v2
	v_mov_b32_e32 v38, v2
	v_mov_b32_e32 v39, v2
	v_mov_b32_e32 v40, v2
	v_mov_b32_e32 v41, v2
	v_mov_b32_e32 v50, v2
	v_mov_b32_e32 v51, v2
	v_mov_b32_e32 v52, v2
	v_mov_b32_e32 v53, v2
	v_mov_b32_e32 v54, v2
	v_mov_b32_e32 v55, v2
	v_mov_b32_e32 v56, v2
	v_mov_b32_e32 v57, v2
	v_mov_b32_e32 v10, v2
	v_mov_b32_e32 v11, v2
	v_mov_b32_e32 v12, v2
	v_mov_b32_e32 v13, v2
	v_mov_b32_e32 v14, v2
	v_mov_b32_e32 v15, v2
	v_mov_b32_e32 v16, v2
	v_mov_b32_e32 v17, v2
	v_mov_b32_e32 v26, v2
	v_mov_b32_e32 v27, v2
	v_mov_b32_e32 v28, v2
	v_mov_b32_e32 v29, v2
	v_mov_b32_e32 v30, v2
	v_mov_b32_e32 v31, v2
	v_mov_b32_e32 v32, v2
	v_mov_b32_e32 v33, v2
	v_mov_b32_e32 v42, v2
	v_mov_b32_e32 v43, v2
	v_mov_b32_e32 v44, v2
	v_mov_b32_e32 v45, v2
	v_mov_b32_e32 v46, v2
	v_mov_b32_e32 v47, v2
	v_mov_b32_e32 v48, v2
	v_mov_b32_e32 v49, v2
	v_mov_b32_e32 v58, v2
	v_mov_b32_e32 v59, v2
	v_mov_b32_e32 v60, v2
	v_mov_b32_e32 v61, v2
	v_mov_b32_e32 v62, v2
	v_mov_b32_e32 v63, v2
	v_mov_b32_e32 v64, v2
	v_mov_b32_e32 v65, v2
	v_mov_b32_e32 v66, v2
	v_mov_b32_e32 v67, v2
	v_mov_b32_e32 v68, v2
	v_mov_b32_e32 v69, v2
	v_mov_b32_e32 v70, v2
	v_mov_b32_e32 v71, v2
	v_mov_b32_e32 v72, v2
	v_mov_b32_e32 v73, v2
	v_mov_b32_e32 v82, v2
	v_mov_b32_e32 v83, v2
	v_mov_b32_e32 v84, v2
	v_mov_b32_e32 v85, v2
	v_mov_b32_e32 v86, v2
	v_mov_b32_e32 v87, v2
	v_mov_b32_e32 v88, v2
	v_mov_b32_e32 v89, v2
	v_mov_b32_e32 v98, v2
	v_mov_b32_e32 v99, v2
	v_mov_b32_e32 v100, v2
	v_mov_b32_e32 v101, v2
	v_mov_b32_e32 v102, v2
	v_mov_b32_e32 v103, v2
	v_mov_b32_e32 v104, v2
	v_mov_b32_e32 v105, v2
	v_mov_b32_e32 v114, v2
	v_mov_b32_e32 v115, v2
	v_mov_b32_e32 v116, v2
	v_mov_b32_e32 v117, v2
	v_mov_b32_e32 v118, v2
	v_mov_b32_e32 v119, v2
	v_mov_b32_e32 v120, v2
	v_mov_b32_e32 v121, v2
	v_mov_b32_e32 v74, v2
	v_mov_b32_e32 v75, v2
	v_mov_b32_e32 v76, v2
	v_mov_b32_e32 v77, v2
	v_mov_b32_e32 v78, v2
	v_mov_b32_e32 v79, v2
	v_mov_b32_e32 v80, v2
	v_mov_b32_e32 v81, v2
	v_mov_b32_e32 v90, v2
	v_mov_b32_e32 v91, v2
	v_mov_b32_e32 v92, v2
	v_mov_b32_e32 v93, v2
	v_mov_b32_e32 v94, v2
	v_mov_b32_e32 v95, v2
	v_mov_b32_e32 v96, v2
	v_mov_b32_e32 v97, v2
	v_mov_b32_e32 v106, v2
	v_mov_b32_e32 v107, v2
	v_mov_b32_e32 v108, v2
	v_mov_b32_e32 v109, v2
	v_mov_b32_e32 v110, v2
	v_mov_b32_e32 v111, v2
	v_mov_b32_e32 v112, v2
	v_mov_b32_e32 v113, v2
	v_mov_b32_e32 v138, v2
	v_mov_b32_e32 v139, v2
	v_mov_b32_e32 v140, v2
	v_mov_b32_e32 v141, v2
	v_mov_b32_e32 v142, v2
	v_mov_b32_e32 v143, v2
	v_mov_b32_e32 v144, v2
	v_mov_b32_e32 v145, v2
	s_cmp_lt_u32 s42, 2
	s_cbranch_scc1 .Lp10_norestore
	s_andn2_b64 vcc, exec, s[6:7]
	s_cbranch_vccnz .Lp10_norestore
	s_barrier
.Lp10_norestore:
.LBB0_1284:
	ds_read_b128 v[122:125], v173
	ds_read_b128 v[126:129], v173 offset:1024
	ds_read_b128 v[130:133], v173 offset:2048
	ds_read_b128 v[134:137], v173 offset:3072
	ds_read_b128 v[164:167], v174
	ds_read_b128 v[180:183], v174 offset:1024
	ds_read_b128 v[184:187], v174 offset:2048
	ds_read_b128 v[188:191], v174 offset:3072
	s_add_u32 s28, s26, 0x100
	s_addc_u32 s29, s27, 0
	s_cmpk_eq_i32 s60, 0x54
	s_cselect_b32 s35, s5, s29
	s_cselect_b32 s34, s4, s28
	s_cselect_b32 s31, s25, s59
	s_cselect_b32 s30, s24, s58
	v_lshl_add_u64 v[168:169], s[26:27], 0, v[156:157]
	s_add_i32 m0, s38, 0xc000
	ds_read_b128 v[192:195], v175
	ds_read_b128 v[196:199], v175 offset:1024
	ds_read_b128 v[200:203], v175 offset:2048
	ds_read_b128 v[204:207], v175 offset:3072
	ds_read_b128 v[208:211], v175 offset:4096
	ds_read_b128 v[212:215], v175 offset:5120
	ds_read_b128 v[216:219], v175 offset:6144
	ds_read_b128 v[220:223], v175 offset:7168
	global_load_lds_dwordx4 v[168:169], off
	v_lshl_add_u64 v[168:169], s[26:27], 0, v[158:159]
	s_add_i32 m0, s38, 0xe000
	s_nop 0
	global_load_lds_dwordx4 v[168:169], off
	s_waitcnt vmcnt(8)
	s_waitcnt lgkmcnt(0)
	s_setprio 1
	s_barrier
	v_mfma_f32_16x16x32_bf16 v[142:145], v[122:125], v[192:195], v[142:145]
	v_mfma_f32_16x16x32_bf16 v[138:141], v[130:133], v[192:195], v[138:141]
	v_mfma_f32_16x16x32_bf16 v[110:113], v[122:125], v[200:203], v[110:113]
	v_mfma_f32_16x16x32_bf16 v[106:109], v[130:133], v[200:203], v[106:109]
	v_mfma_f32_16x16x32_bf16 v[94:97], v[122:125], v[208:211], v[94:97]
	v_mfma_f32_16x16x32_bf16 v[90:93], v[130:133], v[208:211], v[90:93]
	v_mfma_f32_16x16x32_bf16 v[78:81], v[122:125], v[216:219], v[78:81]
	v_mfma_f32_16x16x32_bf16 v[74:77], v[130:133], v[216:219], v[74:77]
	v_mfma_f32_16x16x32_bf16 v[142:145], v[126:129], v[196:199], v[142:145]
	v_mfma_f32_16x16x32_bf16 v[138:141], v[134:137], v[196:199], v[138:141]
	v_mfma_f32_16x16x32_bf16 v[110:113], v[126:129], v[204:207], v[110:113]
	v_mfma_f32_16x16x32_bf16 v[106:109], v[134:137], v[204:207], v[106:109]
	v_mfma_f32_16x16x32_bf16 v[94:97], v[126:129], v[212:215], v[94:97]
	v_mfma_f32_16x16x32_bf16 v[90:93], v[134:137], v[212:215], v[90:93]
	v_mfma_f32_16x16x32_bf16 v[78:81], v[126:129], v[220:223], v[78:81]
	v_mfma_f32_16x16x32_bf16 v[74:77], v[134:137], v[220:223], v[74:77]
	v_mfma_f32_16x16x32_bf16 v[118:121], v[164:167], v[192:195], v[118:121]
	v_mfma_f32_16x16x32_bf16 v[114:117], v[184:187], v[192:195], v[114:117]
	v_mfma_f32_16x16x32_bf16 v[102:105], v[164:167], v[200:203], v[102:105]
	v_mfma_f32_16x16x32_bf16 v[98:101], v[184:187], v[200:203], v[98:101]
	v_mfma_f32_16x16x32_bf16 v[86:89], v[164:167], v[208:211], v[86:89]
	v_mfma_f32_16x16x32_bf16 v[82:85], v[184:187], v[208:211], v[82:85]
	v_mfma_f32_16x16x32_bf16 v[70:73], v[164:167], v[216:219], v[70:73]
	v_mfma_f32_16x16x32_bf16 v[66:69], v[184:187], v[216:219], v[66:69]
	v_mfma_f32_16x16x32_bf16 v[118:121], v[180:183], v[196:199], v[118:121]
	v_mfma_f32_16x16x32_bf16 v[114:117], v[188:191], v[196:199], v[114:117]
	v_mfma_f32_16x16x32_bf16 v[102:105], v[180:183], v[204:207], v[102:105]
	v_mfma_f32_16x16x32_bf16 v[98:101], v[188:191], v[204:207], v[98:101]
	v_mfma_f32_16x16x32_bf16 v[86:89], v[180:183], v[212:215], v[86:89]
	v_mfma_f32_16x16x32_bf16 v[82:85], v[188:191], v[212:215], v[82:85]
	v_mfma_f32_16x16x32_bf16 v[70:73], v[180:183], v[220:223], v[70:73]
	v_mfma_f32_16x16x32_bf16 v[66:69], v[188:191], v[220:223], v[66:69]
	s_barrier
	s_setprio 0
	s_add_i32 s26, s48, s33
	v_lshl_add_u64 v[168:169], s[30:31], 0, v[152:153]
	s_mov_b32 m0, s26
	ds_read_b128 v[192:195], v175 offset:16384
	ds_read_b128 v[196:199], v175 offset:17408
	ds_read_b128 v[200:203], v175 offset:18432
	ds_read_b128 v[204:207], v175 offset:19456
	ds_read_b128 v[208:211], v175 offset:20480
	ds_read_b128 v[212:215], v175 offset:21504
	ds_read_b128 v[216:219], v175 offset:22528
	ds_read_b128 v[220:223], v175 offset:23552
	global_load_lds_dwordx4 v[168:169], off
	s_add_i32 m0, s26, 0x2000
	s_add_u32 s26, s30, 0x160000
	v_lshl_add_u64 v[176:177], s[30:31], 0, v[148:149]
	s_addc_u32 s27, s31, 0
	s_add_i32 s61, s49, s33
	global_load_lds_dwordx4 v[176:177], off
	v_lshl_add_u64 v[224:225], s[26:27], 0, v[152:153]
	s_mov_b32 m0, s61
	v_lshl_add_u64 v[226:227], s[34:35], 0, v[150:151]
	global_load_lds_dwordx4 v[224:225], off
	v_lshl_add_u64 v[224:225], s[26:27], 0, v[148:149]
	s_add_i32 m0, s61, 0x2000
	s_nop 0
	global_load_lds_dwordx4 v[224:225], off
	v_lshl_add_u64 v[224:225], s[34:35], 0, v[154:155]
	s_mov_b32 m0, s38
	s_nop 0
	global_load_lds_dwordx4 v[224:225], off
	s_mov_b32 m0, s39
	s_nop 0
	global_load_lds_dwordx4 v[226:227], off
	s_waitcnt vmcnt(8)
	s_waitcnt lgkmcnt(0)
	s_setprio 1
	s_barrier
	v_mfma_f32_16x16x32_bf16 v[62:65], v[122:125], v[192:195], v[62:65]
	v_mfma_f32_16x16x32_bf16 v[58:61], v[130:133], v[192:195], v[58:61]
	v_mfma_f32_16x16x32_bf16 v[46:49], v[122:125], v[200:203], v[46:49]
	v_mfma_f32_16x16x32_bf16 v[42:45], v[130:133], v[200:203], v[42:45]
	v_mfma_f32_16x16x32_bf16 v[30:33], v[122:125], v[208:211], v[30:33]
	v_mfma_f32_16x16x32_bf16 v[26:29], v[130:133], v[208:211], v[26:29]
	v_mfma_f32_16x16x32_bf16 v[14:17], v[122:125], v[216:219], v[14:17]
	v_mfma_f32_16x16x32_bf16 v[10:13], v[130:133], v[216:219], v[10:13]
	v_mfma_f32_16x16x32_bf16 v[62:65], v[126:129], v[196:199], v[62:65]
	v_mfma_f32_16x16x32_bf16 v[58:61], v[134:137], v[196:199], v[58:61]
	v_mfma_f32_16x16x32_bf16 v[46:49], v[126:129], v[204:207], v[46:49]
	v_mfma_f32_16x16x32_bf16 v[42:45], v[134:137], v[204:207], v[42:45]
	v_mfma_f32_16x16x32_bf16 v[30:33], v[126:129], v[212:215], v[30:33]
	v_mfma_f32_16x16x32_bf16 v[26:29], v[134:137], v[212:215], v[26:29]
	v_mfma_f32_16x16x32_bf16 v[14:17], v[126:129], v[220:223], v[14:17]
	v_mfma_f32_16x16x32_bf16 v[10:13], v[134:137], v[220:223], v[10:13]
	v_mfma_f32_16x16x32_bf16 v[54:57], v[164:167], v[192:195], v[54:57]
	v_mfma_f32_16x16x32_bf16 v[50:53], v[184:187], v[192:195], v[50:53]
	v_mfma_f32_16x16x32_bf16 v[38:41], v[164:167], v[200:203], v[38:41]
	v_mfma_f32_16x16x32_bf16 v[34:37], v[184:187], v[200:203], v[34:37]
	v_mfma_f32_16x16x32_bf16 v[22:25], v[164:167], v[208:211], v[22:25]
	v_mfma_f32_16x16x32_bf16 v[18:21], v[184:187], v[208:211], v[18:21]
	v_mfma_f32_16x16x32_bf16 v[6:9], v[164:167], v[216:219], v[6:9]
	v_mfma_f32_16x16x32_bf16 v[2:5], v[184:187], v[216:219], v[2:5]
	v_mfma_f32_16x16x32_bf16 v[54:57], v[180:183], v[196:199], v[54:57]
	v_mfma_f32_16x16x32_bf16 v[50:53], v[188:191], v[196:199], v[50:53]
	v_mfma_f32_16x16x32_bf16 v[38:41], v[180:183], v[204:207], v[38:41]
	v_mfma_f32_16x16x32_bf16 v[34:37], v[188:191], v[204:207], v[34:37]
	v_mfma_f32_16x16x32_bf16 v[22:25], v[180:183], v[212:215], v[22:25]
	v_mfma_f32_16x16x32_bf16 v[18:21], v[188:191], v[212:215], v[18:21]
	v_mfma_f32_16x16x32_bf16 v[6:9], v[180:183], v[220:223], v[6:9]
	v_mfma_f32_16x16x32_bf16 v[2:5], v[188:191], v[220:223], v[2:5]
	s_barrier
	s_setprio 0
	s_add_i32 s61, 0, 0x18000
	s_add_i32 s68, 0, 0x1c000
	v_add_u32_e32 v134, s61, v171
	v_add_u32_e32 v179, s68, v171
	ds_read_b128 v[122:125], v134
	ds_read_b128 v[126:129], v134 offset:1024
	ds_read_b128 v[130:133], v134 offset:2048
	ds_read_b128 v[134:137], v134 offset:3072
	ds_read_b128 v[164:167], v179
	ds_read_b128 v[180:183], v179 offset:1024
	ds_read_b128 v[184:187], v179 offset:2048
	ds_read_b128 v[188:191], v179 offset:3072
	s_add_u32 s26, s34, 0x160000
	s_addc_u32 s27, s35, 0
	s_mov_b32 m0, s40
	v_lshl_add_u64 v[228:229], s[26:27], 0, v[154:155]
	ds_read_b128 v[192:195], v175 offset:32768
	ds_read_b128 v[196:199], v175 offset:33792
	ds_read_b128 v[200:203], v175 offset:34816
	ds_read_b128 v[204:207], v175 offset:35840
	ds_read_b128 v[208:211], v175 offset:36864
	ds_read_b128 v[212:215], v175 offset:37888
	ds_read_b128 v[216:219], v175 offset:38912
	ds_read_b128 v[220:223], v175 offset:39936
	global_load_lds_dwordx4 v[228:229], off
	v_lshl_add_u64 v[228:229], s[26:27], 0, v[150:151]
	s_mov_b32 m0, s41
	s_nop 0
	global_load_lds_dwordx4 v[228:229], off
	s_waitcnt vmcnt(8)
	s_waitcnt lgkmcnt(0)
	s_setprio 1
	s_barrier
	v_mfma_f32_16x16x32_bf16 v[142:145], v[122:125], v[192:195], v[142:145]
	v_mfma_f32_16x16x32_bf16 v[138:141], v[130:133], v[192:195], v[138:141]
	v_mfma_f32_16x16x32_bf16 v[110:113], v[122:125], v[200:203], v[110:113]
	v_mfma_f32_16x16x32_bf16 v[106:109], v[130:133], v[200:203], v[106:109]
	v_mfma_f32_16x16x32_bf16 v[94:97], v[122:125], v[208:211], v[94:97]
	v_mfma_f32_16x16x32_bf16 v[90:93], v[130:133], v[208:211], v[90:93]
	v_mfma_f32_16x16x32_bf16 v[78:81], v[122:125], v[216:219], v[78:81]
	v_mfma_f32_16x16x32_bf16 v[74:77], v[130:133], v[216:219], v[74:77]
	v_mfma_f32_16x16x32_bf16 v[142:145], v[126:129], v[196:199], v[142:145]
	v_mfma_f32_16x16x32_bf16 v[138:141], v[134:137], v[196:199], v[138:141]
	v_mfma_f32_16x16x32_bf16 v[110:113], v[126:129], v[204:207], v[110:113]
	v_mfma_f32_16x16x32_bf16 v[106:109], v[134:137], v[204:207], v[106:109]
	v_mfma_f32_16x16x32_bf16 v[94:97], v[126:129], v[212:215], v[94:97]
	v_mfma_f32_16x16x32_bf16 v[90:93], v[134:137], v[212:215], v[90:93]
	v_mfma_f32_16x16x32_bf16 v[78:81], v[126:129], v[220:223], v[78:81]
	v_mfma_f32_16x16x32_bf16 v[74:77], v[134:137], v[220:223], v[74:77]
	v_mfma_f32_16x16x32_bf16 v[118:121], v[164:167], v[192:195], v[118:121]
	v_mfma_f32_16x16x32_bf16 v[114:117], v[184:187], v[192:195], v[114:117]
	v_mfma_f32_16x16x32_bf16 v[102:105], v[164:167], v[200:203], v[102:105]
	v_mfma_f32_16x16x32_bf16 v[98:101], v[184:187], v[200:203], v[98:101]
	v_mfma_f32_16x16x32_bf16 v[86:89], v[164:167], v[208:211], v[86:89]
	v_mfma_f32_16x16x32_bf16 v[82:85], v[184:187], v[208:211], v[82:85]
	v_mfma_f32_16x16x32_bf16 v[70:73], v[164:167], v[216:219], v[70:73]
	v_mfma_f32_16x16x32_bf16 v[66:69], v[184:187], v[216:219], v[66:69]
	v_mfma_f32_16x16x32_bf16 v[118:121], v[180:183], v[196:199], v[118:121]
	v_mfma_f32_16x16x32_bf16 v[114:117], v[188:191], v[196:199], v[114:117]
	v_mfma_f32_16x16x32_bf16 v[102:105], v[180:183], v[204:207], v[102:105]
	v_mfma_f32_16x16x32_bf16 v[98:101], v[188:191], v[204:207], v[98:101]
	v_mfma_f32_16x16x32_bf16 v[86:89], v[180:183], v[212:215], v[86:89]
	v_mfma_f32_16x16x32_bf16 v[82:85], v[188:191], v[212:215], v[82:85]
	v_mfma_f32_16x16x32_bf16 v[70:73], v[180:183], v[220:223], v[70:73]
	v_mfma_f32_16x16x32_bf16 v[66:69], v[188:191], v[220:223], v[66:69]
	s_barrier
	s_setprio 0
	s_add_i32 s26, s61, s33
	v_lshl_add_u64 v[168:169], v[168:169], 0, s[8:9]
	s_mov_b32 m0, s26
	ds_read_b128 v[192:195], v175 offset:49152
	ds_read_b128 v[196:199], v175 offset:50176
	ds_read_b128 v[200:203], v175 offset:51200
	ds_read_b128 v[204:207], v175 offset:52224
	ds_read_b128 v[208:211], v175 offset:53248
	ds_read_b128 v[212:215], v175 offset:54272
	ds_read_b128 v[216:219], v175 offset:55296
	ds_read_b128 v[220:223], v175 offset:56320
	global_load_lds_dwordx4 v[168:169], off
	s_add_i32 m0, s26, 0x2000
	s_add_u32 s26, s30, 0x160080
	v_lshl_add_u64 v[168:169], v[176:177], 0, s[8:9]
	s_addc_u32 s27, s31, 0
	s_add_i32 s30, s68, s33
	global_load_lds_dwordx4 v[168:169], off
	v_lshl_add_u64 v[168:169], s[26:27], 0, v[152:153]
	s_mov_b32 m0, s30
	s_nop 0
	global_load_lds_dwordx4 v[168:169], off
	v_lshl_add_u64 v[168:169], s[26:27], 0, v[148:149]
	s_add_i32 m0, s30, 0x2000
	s_nop 0
	global_load_lds_dwordx4 v[168:169], off
	v_lshl_add_u64 v[168:169], v[224:225], 0, s[8:9]
	s_mov_b32 m0, s43
	s_nop 0
	global_load_lds_dwordx4 v[168:169], off
	v_lshl_add_u64 v[168:169], v[226:227], 0, s[8:9]
	s_mov_b32 m0, s44
	s_nop 0
	global_load_lds_dwordx4 v[168:169], off
	s_waitcnt vmcnt(8)
	s_waitcnt lgkmcnt(0)
	s_setprio 1
	s_barrier
	v_mfma_f32_16x16x32_bf16 v[62:65], v[122:125], v[192:195], v[62:65]
	v_mfma_f32_16x16x32_bf16 v[58:61], v[130:133], v[192:195], v[58:61]
	v_mfma_f32_16x16x32_bf16 v[46:49], v[122:125], v[200:203], v[46:49]
	v_mfma_f32_16x16x32_bf16 v[42:45], v[130:133], v[200:203], v[42:45]
	v_mfma_f32_16x16x32_bf16 v[30:33], v[122:125], v[208:211], v[30:33]
	v_mfma_f32_16x16x32_bf16 v[26:29], v[130:133], v[208:211], v[26:29]
	v_mfma_f32_16x16x32_bf16 v[14:17], v[122:125], v[216:219], v[14:17]
	v_mfma_f32_16x16x32_bf16 v[10:13], v[130:133], v[216:219], v[10:13]
	v_mfma_f32_16x16x32_bf16 v[62:65], v[126:129], v[196:199], v[62:65]
	v_mfma_f32_16x16x32_bf16 v[58:61], v[134:137], v[196:199], v[58:61]
	v_mfma_f32_16x16x32_bf16 v[46:49], v[126:129], v[204:207], v[46:49]
	v_mfma_f32_16x16x32_bf16 v[42:45], v[134:137], v[204:207], v[42:45]
	v_mfma_f32_16x16x32_bf16 v[30:33], v[126:129], v[212:215], v[30:33]
	v_mfma_f32_16x16x32_bf16 v[26:29], v[134:137], v[212:215], v[26:29]
	v_mfma_f32_16x16x32_bf16 v[14:17], v[126:129], v[220:223], v[14:17]
	v_mfma_f32_16x16x32_bf16 v[10:13], v[134:137], v[220:223], v[10:13]
	v_mfma_f32_16x16x32_bf16 v[54:57], v[164:167], v[192:195], v[54:57]
	v_mfma_f32_16x16x32_bf16 v[50:53], v[184:187], v[192:195], v[50:53]
	v_mfma_f32_16x16x32_bf16 v[38:41], v[164:167], v[200:203], v[38:41]
	v_mfma_f32_16x16x32_bf16 v[34:37], v[184:187], v[200:203], v[34:37]
	v_mfma_f32_16x16x32_bf16 v[22:25], v[164:167], v[208:211], v[22:25]
	v_mfma_f32_16x16x32_bf16 v[18:21], v[184:187], v[208:211], v[18:21]
	v_mfma_f32_16x16x32_bf16 v[6:9], v[164:167], v[216:219], v[6:9]
	v_mfma_f32_16x16x32_bf16 v[2:5], v[184:187], v[216:219], v[2:5]
	v_mfma_f32_16x16x32_bf16 v[54:57], v[180:183], v[196:199], v[54:57]
	v_mfma_f32_16x16x32_bf16 v[50:53], v[188:191], v[196:199], v[50:53]
	v_mfma_f32_16x16x32_bf16 v[38:41], v[180:183], v[204:207], v[38:41]
	v_mfma_f32_16x16x32_bf16 v[34:37], v[188:191], v[204:207], v[34:37]
	v_mfma_f32_16x16x32_bf16 v[22:25], v[180:183], v[212:215], v[22:25]
	v_mfma_f32_16x16x32_bf16 v[18:21], v[188:191], v[212:215], v[18:21]
	v_mfma_f32_16x16x32_bf16 v[6:9], v[180:183], v[220:223], v[6:9]
	v_mfma_f32_16x16x32_bf16 v[2:5], v[188:191], v[220:223], v[2:5]
	s_barrier
	s_setprio 0
	s_add_i32 s60, s60, 2
	s_add_u32 s58, s58, 0x100
	s_addc_u32 s59, s59, 0
	s_cmpk_gt_u32 s60, 0x55
	s_mov_b64 s[26:27], s[28:29]
	s_cbranch_scc0 .LBB0_1284
	s_and_b64 vcc, exec, s[12:13]
	s_cbranch_vccz .LBB0_1287
	s_barrier
.LBB0_1287:
	s_lshl_b32 s27, s56, 8
	s_add_i32 s26, s27, 0xffffe000
	s_lshr_b32 s26, s26, 12
	s_add_i32 s26, s26, 1
	s_cmp_gt_i32 s56, 31
	s_cselect_b32 s26, s26, 0
	s_mul_hi_u32 s28, s26, 0xc000
	s_mul_i32 s26, s26, 0xc000
	v_add_u32_e32 v168, s27, v170
	v_lshl_or_b32 v122, s57, 8, v172
	s_add_u32 s26, s66, s26
	v_ashrrev_i32_e32 v169, 31, v168
	v_ashrrev_i32_e32 v123, 31, v122
	v_lshlrev_b64 v[166:167], 12, v[168:169]
	s_addc_u32 s27, s67, s28
	v_lshl_add_u64 v[124:125], s[64:65], 0, v[166:167]
	v_lshlrev_b64 v[164:165], 1, v[122:123]
	v_lshl_add_u64 v[122:123], v[122:123], 2, s[26:27]
	v_lshl_add_u64 v[176:177], v[124:125], 0, v[164:165]
	v_lshl_add_u64 v[124:125], v[122:123], 0, s[14:15]
	v_add_co_u32_e32 v122, vcc, s45, v122
	s_nop 0
	s_nop 0
	v_addc_co_u32_e32 v123, vcc, 0, v123, vcc
	global_load_dwordx4 v[130:133], v[124:125], off offset:16
	global_load_dwordx4 v[134:137], v[122:123], off
	v_lshl_add_u64 v[122:123], s[52:53], 0, v[166:167]
	v_lshl_add_u64 v[184:185], v[122:123], 0, v[164:165]
	global_load_dwordx4 v[126:129], v[124:125], off offset:512
	s_nop 0
	global_load_dwordx4 v[122:125], v[124:125], off offset:528
	v_mov_b32_e32 v228, 0x10000
	v_mov_b32_e32 v229, 0
	v_lshl_add_u64 v[222:223], v[176:177], 0, v[228:229]
	v_lshl_add_u64 v[224:225], v[222:223], 0, v[228:229]
	v_lshl_add_u64 v[226:227], v[224:225], 0, v[228:229]
	global_load_dwordx4 v[190:193], v[176:177], off
	global_load_dwordx4 v[194:197], v[176:177], off offset:256
	global_load_dwordx4 v[198:201], v[222:223], off
	global_load_dwordx4 v[202:205], v[222:223], off offset:256
	global_load_dwordx4 v[206:209], v[224:225], off
	global_load_dwordx4 v[210:213], v[224:225], off offset:256
	global_load_dwordx4 v[214:217], v[226:227], off
	global_load_dwordx4 v[218:221], v[226:227], off offset:256
	v_lshl_add_u64 v[222:223], v[228:229], 3, v[176:177]
	v_lshl_add_u64 v[224:225], v[222:223], 0, v[228:229]
	v_lshl_add_u64 v[226:227], v[224:225], 0, v[228:229]
	v_lshl_add_u64 v[228:229], v[226:227], 0, v[228:229]
	s_and_b64 vcc, exec, s[0:1]
	s_mov_b64 s[0:1], -1
	s_waitcnt vmcnt(7)
	v_lshlrev_b32_e32 v186, 16, v190
	v_and_b32_e32 v187, 0xffff0000, v190
	v_lshlrev_b32_e32 v180, 16, v191
	v_and_b32_e32 v181, 0xffff0000, v191
	v_lshlrev_b32_e32 v188, 16, v192
	v_and_b32_e32 v189, 0xffff0000, v192
	v_lshlrev_b32_e32 v182, 16, v193
	v_and_b32_e32 v183, 0xffff0000, v193
	global_load_dwordx4 v[190:193], v[222:223], off
	v_pk_fma_f32 v[182:183], v[140:141], v[132:133], v[182:183]
	v_pk_fma_f32 v[138:139], v[138:139], v[130:131], v[188:189]
	v_pk_fma_f32 v[144:145], v[144:145], v[136:137], v[180:181]
	v_pk_fma_f32 v[142:143], v[142:143], v[134:135], v[186:187]
	v_cvt_pk_bf16_f32 v140, v138, v139
	v_cvt_pk_bf16_f32 v141, v182, v183
	v_cvt_pk_bf16_f32 v138, v142, v143
	v_cvt_pk_bf16_f32 v139, v144, v145
	global_store_dwordx4 v[184:185], v[138:141], off
	s_nop 0
	v_or_b32_e32 v142, 16, v168
	v_ashrrev_i32_e32 v143, 31, v142
	v_lshlrev_b64 v[142:143], 12, v[142:143]
	v_lshl_add_u64 v[144:145], s[64:65], 0, v[142:143]
	v_lshl_add_u64 v[144:145], v[144:145], 0, v[164:165]
	s_waitcnt vmcnt(8)
	v_lshlrev_b32_e32 v176, 16, v194
	v_and_b32_e32 v177, 0xffff0000, v194
	v_lshlrev_b32_e32 v138, 16, v195
	v_and_b32_e32 v139, 0xffff0000, v195
	v_lshlrev_b32_e32 v180, 16, v196
	v_and_b32_e32 v181, 0xffff0000, v196
	v_lshlrev_b32_e32 v140, 16, v197
	v_and_b32_e32 v141, 0xffff0000, v197
	global_load_dwordx4 v[194:197], v[222:223], off offset:256
	v_pk_fma_f32 v[120:121], v[120:121], v[128:129], v[138:139]
	v_pk_fma_f32 v[118:119], v[118:119], v[126:127], v[176:177]
	v_pk_fma_f32 v[138:139], v[116:117], v[124:125], v[140:141]
	v_pk_fma_f32 v[116:117], v[114:115], v[122:123], v[180:181]
	v_cvt_pk_bf16_f32 v114, v118, v119
	v_cvt_pk_bf16_f32 v115, v120, v121
	v_cvt_pk_bf16_f32 v116, v116, v117
	v_cvt_pk_bf16_f32 v117, v138, v139
	global_store_dwordx4 v[184:185], v[114:117], off offset:256
	s_nop 0
	v_lshl_add_u64 v[118:119], s[52:53], 0, v[142:143]
	v_lshl_add_u64 v[118:119], v[118:119], 0, v[164:165]
	s_waitcnt vmcnt(9)
	v_lshlrev_b32_e32 v120, 16, v198
	v_and_b32_e32 v121, 0xffff0000, v198
	v_lshlrev_b32_e32 v114, 16, v199
	v_and_b32_e32 v115, 0xffff0000, v199
	v_lshlrev_b32_e32 v138, 16, v200
	v_and_b32_e32 v139, 0xffff0000, v200
	v_lshlrev_b32_e32 v116, 16, v201
	v_and_b32_e32 v117, 0xffff0000, v201
	global_load_dwordx4 v[198:201], v[224:225], off
	v_pk_fma_f32 v[112:113], v[112:113], v[136:137], v[114:115]
	v_pk_fma_f32 v[110:111], v[110:111], v[134:135], v[120:121]
	v_pk_fma_f32 v[114:115], v[108:109], v[132:133], v[116:117]
	v_pk_fma_f32 v[108:109], v[106:107], v[130:131], v[138:139]
	v_cvt_pk_bf16_f32 v106, v110, v111
	v_cvt_pk_bf16_f32 v107, v112, v113
	v_cvt_pk_bf16_f32 v108, v108, v109
	v_cvt_pk_bf16_f32 v109, v114, v115
	global_store_dwordx4 v[118:119], v[106:109], off
	s_nop 0
	v_or_b32_e32 v110, 32, v168
	v_ashrrev_i32_e32 v111, 31, v110
	v_lshlrev_b64 v[110:111], 12, v[110:111]
	v_lshl_add_u64 v[112:113], s[64:65], 0, v[110:111]
	v_lshl_add_u64 v[112:113], v[112:113], 0, v[164:165]
	s_waitcnt vmcnt(10)
	v_lshlrev_b32_e32 v114, 16, v202
	v_and_b32_e32 v115, 0xffff0000, v202
	v_lshlrev_b32_e32 v106, 16, v203
	v_and_b32_e32 v107, 0xffff0000, v203
	v_lshlrev_b32_e32 v116, 16, v204
	v_and_b32_e32 v117, 0xffff0000, v204
	v_lshlrev_b32_e32 v108, 16, v205
	v_and_b32_e32 v109, 0xffff0000, v205
	global_load_dwordx4 v[202:205], v[224:225], off offset:256
	v_pk_fma_f32 v[104:105], v[104:105], v[128:129], v[106:107]
	v_pk_fma_f32 v[102:103], v[102:103], v[126:127], v[114:115]
	v_pk_fma_f32 v[106:107], v[100:101], v[124:125], v[108:109]
	v_pk_fma_f32 v[100:101], v[98:99], v[122:123], v[116:117]
	v_cvt_pk_bf16_f32 v98, v102, v103
	v_cvt_pk_bf16_f32 v99, v104, v105
	v_cvt_pk_bf16_f32 v100, v100, v101
	v_cvt_pk_bf16_f32 v101, v106, v107
	global_store_dwordx4 v[118:119], v[98:101], off offset:256
	s_nop 0
	v_lshl_add_u64 v[102:103], s[52:53], 0, v[110:111]
	v_lshl_add_u64 v[102:103], v[102:103], 0, v[164:165]
	s_waitcnt vmcnt(11)
	v_lshlrev_b32_e32 v104, 16, v206
	v_and_b32_e32 v105, 0xffff0000, v206
	v_lshlrev_b32_e32 v98, 16, v207
	v_and_b32_e32 v99, 0xffff0000, v207
	v_lshlrev_b32_e32 v106, 16, v208
	v_and_b32_e32 v107, 0xffff0000, v208
	v_lshlrev_b32_e32 v100, 16, v209
	v_and_b32_e32 v101, 0xffff0000, v209
	global_load_dwordx4 v[206:209], v[226:227], off
	v_pk_fma_f32 v[96:97], v[96:97], v[136:137], v[98:99]
	v_pk_fma_f32 v[94:95], v[94:95], v[134:135], v[104:105]
	v_pk_fma_f32 v[98:99], v[92:93], v[132:133], v[100:101]
	v_pk_fma_f32 v[92:93], v[90:91], v[130:131], v[106:107]
	v_cvt_pk_bf16_f32 v90, v94, v95
	v_cvt_pk_bf16_f32 v91, v96, v97
	v_cvt_pk_bf16_f32 v92, v92, v93
	v_cvt_pk_bf16_f32 v93, v98, v99
	global_store_dwordx4 v[102:103], v[90:93], off
	s_nop 0
	v_or_b32_e32 v94, 48, v168
	v_ashrrev_i32_e32 v95, 31, v94
	v_lshlrev_b64 v[94:95], 12, v[94:95]
	v_lshl_add_u64 v[96:97], s[64:65], 0, v[94:95]
	v_lshl_add_u64 v[96:97], v[96:97], 0, v[164:165]
	s_waitcnt vmcnt(12)
	v_lshlrev_b32_e32 v98, 16, v210
	v_and_b32_e32 v99, 0xffff0000, v210
	v_lshlrev_b32_e32 v90, 16, v211
	v_and_b32_e32 v91, 0xffff0000, v211
	v_lshlrev_b32_e32 v100, 16, v212
	v_and_b32_e32 v101, 0xffff0000, v212
	v_lshlrev_b32_e32 v92, 16, v213
	v_and_b32_e32 v93, 0xffff0000, v213
	global_load_dwordx4 v[210:213], v[226:227], off offset:256
	v_pk_fma_f32 v[88:89], v[88:89], v[128:129], v[90:91]
	v_pk_fma_f32 v[86:87], v[86:87], v[126:127], v[98:99]
	v_pk_fma_f32 v[90:91], v[84:85], v[124:125], v[92:93]
	v_pk_fma_f32 v[84:85], v[82:83], v[122:123], v[100:101]
	v_cvt_pk_bf16_f32 v82, v86, v87
	v_cvt_pk_bf16_f32 v83, v88, v89
	v_cvt_pk_bf16_f32 v84, v84, v85
	v_cvt_pk_bf16_f32 v85, v90, v91
	global_store_dwordx4 v[102:103], v[82:85], off offset:256
	s_nop 0
	v_lshl_add_u64 v[86:87], s[52:53], 0, v[94:95]
	v_lshl_add_u64 v[86:87], v[86:87], 0, v[164:165]
	s_waitcnt vmcnt(13)
	v_lshlrev_b32_e32 v88, 16, v214
	v_and_b32_e32 v89, 0xffff0000, v214
	v_lshlrev_b32_e32 v82, 16, v215
	v_and_b32_e32 v83, 0xffff0000, v215
	v_lshlrev_b32_e32 v90, 16, v216
	v_and_b32_e32 v91, 0xffff0000, v216
	v_lshlrev_b32_e32 v84, 16, v217
	v_and_b32_e32 v85, 0xffff0000, v217
	global_load_dwordx4 v[214:217], v[228:229], off
	v_pk_fma_f32 v[80:81], v[80:81], v[136:137], v[82:83]
	v_pk_fma_f32 v[78:79], v[78:79], v[134:135], v[88:89]
	v_pk_fma_f32 v[82:83], v[76:77], v[132:133], v[84:85]
	v_pk_fma_f32 v[76:77], v[74:75], v[130:131], v[90:91]
	v_cvt_pk_bf16_f32 v74, v78, v79
	v_cvt_pk_bf16_f32 v75, v80, v81
	v_cvt_pk_bf16_f32 v76, v76, v77
	v_cvt_pk_bf16_f32 v77, v82, v83
	global_store_dwordx4 v[86:87], v[74:77], off
	s_nop 0
	v_lshl_add_u64 v[78:79], v[166:167], 0, s[16:17]
	v_lshl_add_u64 v[80:81], s[64:65], 0, v[78:79]
	v_lshl_add_u64 v[80:81], v[80:81], 0, v[164:165]
	s_waitcnt vmcnt(14)
	v_lshlrev_b32_e32 v82, 16, v218
	v_and_b32_e32 v83, 0xffff0000, v218
	v_lshlrev_b32_e32 v74, 16, v219
	v_and_b32_e32 v75, 0xffff0000, v219
	v_lshlrev_b32_e32 v84, 16, v220
	v_and_b32_e32 v85, 0xffff0000, v220
	v_lshlrev_b32_e32 v76, 16, v221
	v_and_b32_e32 v77, 0xffff0000, v221
	global_load_dwordx4 v[218:221], v[228:229], off offset:256
	v_pk_fma_f32 v[72:73], v[72:73], v[128:129], v[74:75]
	v_pk_fma_f32 v[70:71], v[70:71], v[126:127], v[82:83]
	v_pk_fma_f32 v[74:75], v[68:69], v[124:125], v[76:77]
	v_pk_fma_f32 v[68:69], v[66:67], v[122:123], v[84:85]
	v_cvt_pk_bf16_f32 v66, v70, v71
	v_cvt_pk_bf16_f32 v67, v72, v73
	v_cvt_pk_bf16_f32 v68, v68, v69
	v_cvt_pk_bf16_f32 v69, v74, v75
	global_store_dwordx4 v[86:87], v[66:69], off offset:256
	s_nop 0
	v_lshl_add_u64 v[70:71], s[52:53], 0, v[78:79]
	v_lshl_add_u64 v[70:71], v[70:71], 0, v[164:165]
	s_waitcnt vmcnt(15)
	v_lshlrev_b32_e32 v72, 16, v190
	v_and_b32_e32 v73, 0xffff0000, v190
	v_lshlrev_b32_e32 v66, 16, v191
	v_and_b32_e32 v67, 0xffff0000, v191
	v_lshlrev_b32_e32 v74, 16, v192
	v_and_b32_e32 v75, 0xffff0000, v192
	v_lshlrev_b32_e32 v68, 16, v193
	v_and_b32_e32 v69, 0xffff0000, v193
	v_pk_fma_f32 v[64:65], v[64:65], v[136:137], v[66:67]
	v_pk_fma_f32 v[62:63], v[62:63], v[134:135], v[72:73]
	v_pk_fma_f32 v[66:67], v[60:61], v[132:133], v[68:69]
	v_pk_fma_f32 v[60:61], v[58:59], v[130:131], v[74:75]
	v_cvt_pk_bf16_f32 v58, v62, v63
	v_cvt_pk_bf16_f32 v59, v64, v65
	v_cvt_pk_bf16_f32 v60, v60, v61
	v_cvt_pk_bf16_f32 v61, v66, v67
	global_store_dwordx4 v[70:71], v[58:61], off
	s_nop 0
	v_lshl_add_u64 v[62:63], v[166:167], 0, s[18:19]
	v_lshl_add_u64 v[64:65], s[64:65], 0, v[62:63]
	v_lshl_add_u64 v[64:65], v[64:65], 0, v[164:165]
	s_waitcnt vmcnt(14)
	v_lshlrev_b32_e32 v66, 16, v194
	v_and_b32_e32 v67, 0xffff0000, v194
	v_lshlrev_b32_e32 v58, 16, v195
	v_and_b32_e32 v59, 0xffff0000, v195
	v_lshlrev_b32_e32 v68, 16, v196
	v_and_b32_e32 v69, 0xffff0000, v196
	v_lshlrev_b32_e32 v60, 16, v197
	v_and_b32_e32 v61, 0xffff0000, v197
	v_pk_fma_f32 v[56:57], v[56:57], v[128:129], v[58:59]
	v_pk_fma_f32 v[54:55], v[54:55], v[126:127], v[66:67]
	v_pk_fma_f32 v[58:59], v[52:53], v[124:125], v[60:61]
	v_pk_fma_f32 v[52:53], v[50:51], v[122:123], v[68:69]
	v_cvt_pk_bf16_f32 v50, v54, v55
	v_cvt_pk_bf16_f32 v51, v56, v57
	v_cvt_pk_bf16_f32 v52, v52, v53
	v_cvt_pk_bf16_f32 v53, v58, v59
	global_store_dwordx4 v[70:71], v[50:53], off offset:256
	s_nop 0
	v_lshl_add_u64 v[54:55], s[52:53], 0, v[62:63]
	v_lshl_add_u64 v[54:55], v[54:55], 0, v[164:165]
	s_waitcnt vmcnt(13)
	v_lshlrev_b32_e32 v56, 16, v198
	v_and_b32_e32 v57, 0xffff0000, v198
	v_lshlrev_b32_e32 v50, 16, v199
	v_and_b32_e32 v51, 0xffff0000, v199
	v_lshlrev_b32_e32 v58, 16, v200
	v_and_b32_e32 v59, 0xffff0000, v200
	v_lshlrev_b32_e32 v52, 16, v201
	v_and_b32_e32 v53, 0xffff0000, v201
	v_pk_fma_f32 v[48:49], v[48:49], v[136:137], v[50:51]
	v_pk_fma_f32 v[46:47], v[46:47], v[134:135], v[56:57]
	v_pk_fma_f32 v[50:51], v[44:45], v[132:133], v[52:53]
	v_pk_fma_f32 v[44:45], v[42:43], v[130:131], v[58:59]
	v_cvt_pk_bf16_f32 v42, v46, v47
	v_cvt_pk_bf16_f32 v43, v48, v49
	v_cvt_pk_bf16_f32 v44, v44, v45
	v_cvt_pk_bf16_f32 v45, v50, v51
	global_store_dwordx4 v[54:55], v[42:45], off
	s_nop 0
	v_lshl_add_u64 v[46:47], v[166:167], 0, s[20:21]
	v_lshl_add_u64 v[48:49], s[64:65], 0, v[46:47]
	v_lshl_add_u64 v[48:49], v[48:49], 0, v[164:165]
	s_waitcnt vmcnt(12)
	v_lshlrev_b32_e32 v50, 16, v202
	v_and_b32_e32 v51, 0xffff0000, v202
	v_lshlrev_b32_e32 v42, 16, v203
	v_and_b32_e32 v43, 0xffff0000, v203
	v_lshlrev_b32_e32 v52, 16, v204
	v_and_b32_e32 v53, 0xffff0000, v204
	v_lshlrev_b32_e32 v44, 16, v205
	v_and_b32_e32 v45, 0xffff0000, v205
	v_pk_fma_f32 v[40:41], v[40:41], v[128:129], v[42:43]
	v_pk_fma_f32 v[38:39], v[38:39], v[126:127], v[50:51]
	v_pk_fma_f32 v[42:43], v[36:37], v[124:125], v[44:45]
	v_pk_fma_f32 v[36:37], v[34:35], v[122:123], v[52:53]
	v_cvt_pk_bf16_f32 v34, v38, v39
	v_cvt_pk_bf16_f32 v35, v40, v41
	v_cvt_pk_bf16_f32 v36, v36, v37
	v_cvt_pk_bf16_f32 v37, v42, v43
	global_store_dwordx4 v[54:55], v[34:37], off offset:256
	s_nop 0
	v_lshl_add_u64 v[38:39], s[52:53], 0, v[46:47]
	v_lshl_add_u64 v[38:39], v[38:39], 0, v[164:165]
	s_waitcnt vmcnt(11)
	v_lshlrev_b32_e32 v40, 16, v206
	v_and_b32_e32 v41, 0xffff0000, v206
	v_lshlrev_b32_e32 v34, 16, v207
	v_and_b32_e32 v35, 0xffff0000, v207
	v_lshlrev_b32_e32 v42, 16, v208
	v_and_b32_e32 v43, 0xffff0000, v208
	v_lshlrev_b32_e32 v36, 16, v209
	v_and_b32_e32 v37, 0xffff0000, v209
	v_pk_fma_f32 v[32:33], v[32:33], v[136:137], v[34:35]
	v_pk_fma_f32 v[30:31], v[30:31], v[134:135], v[40:41]
	v_pk_fma_f32 v[34:35], v[28:29], v[132:133], v[36:37]
	v_pk_fma_f32 v[28:29], v[26:27], v[130:131], v[42:43]
	v_cvt_pk_bf16_f32 v26, v30, v31
	v_cvt_pk_bf16_f32 v27, v32, v33
	v_cvt_pk_bf16_f32 v28, v28, v29
	v_cvt_pk_bf16_f32 v29, v34, v35
	global_store_dwordx4 v[38:39], v[26:29], off
	s_nop 0
	v_lshl_add_u64 v[30:31], v[166:167], 0, s[22:23]
	v_lshl_add_u64 v[32:33], s[64:65], 0, v[30:31]
	v_lshl_add_u64 v[32:33], v[32:33], 0, v[164:165]
	s_waitcnt vmcnt(10)
	v_lshlrev_b32_e32 v34, 16, v210
	v_and_b32_e32 v35, 0xffff0000, v210
	v_lshlrev_b32_e32 v26, 16, v211
	v_and_b32_e32 v27, 0xffff0000, v211
	v_lshlrev_b32_e32 v36, 16, v212
	v_and_b32_e32 v37, 0xffff0000, v212
	v_lshlrev_b32_e32 v28, 16, v213
	v_and_b32_e32 v29, 0xffff0000, v213
	v_pk_fma_f32 v[24:25], v[24:25], v[128:129], v[26:27]
	v_pk_fma_f32 v[22:23], v[22:23], v[126:127], v[34:35]
	v_pk_fma_f32 v[26:27], v[20:21], v[124:125], v[28:29]
	v_pk_fma_f32 v[20:21], v[18:19], v[122:123], v[36:37]
	v_cvt_pk_bf16_f32 v18, v22, v23
	v_cvt_pk_bf16_f32 v19, v24, v25
	v_cvt_pk_bf16_f32 v20, v20, v21
	v_cvt_pk_bf16_f32 v21, v26, v27
	global_store_dwordx4 v[38:39], v[18:21], off offset:256
	s_nop 0
	v_lshl_add_u64 v[22:23], s[52:53], 0, v[30:31]
	v_lshl_add_u64 v[22:23], v[22:23], 0, v[164:165]
	s_waitcnt vmcnt(9)
	v_lshlrev_b32_e32 v24, 16, v214
	v_and_b32_e32 v25, 0xffff0000, v214
	v_lshlrev_b32_e32 v18, 16, v215
	v_and_b32_e32 v19, 0xffff0000, v215
	v_lshlrev_b32_e32 v26, 16, v216
	v_and_b32_e32 v27, 0xffff0000, v216
	v_lshlrev_b32_e32 v20, 16, v217
	v_and_b32_e32 v21, 0xffff0000, v217
	v_pk_fma_f32 v[16:17], v[16:17], v[136:137], v[18:19]
	v_pk_fma_f32 v[14:15], v[14:15], v[134:135], v[24:25]
	v_pk_fma_f32 v[18:19], v[12:13], v[132:133], v[20:21]
	v_pk_fma_f32 v[12:13], v[10:11], v[130:131], v[26:27]
	v_cvt_pk_bf16_f32 v10, v14, v15
	v_cvt_pk_bf16_f32 v11, v16, v17
	v_cvt_pk_bf16_f32 v12, v12, v13
	v_cvt_pk_bf16_f32 v13, v18, v19
	global_store_dwordx4 v[22:23], v[10:13], off
	s_nop 0
	s_waitcnt vmcnt(8)
	v_lshlrev_b32_e32 v14, 16, v218
	v_and_b32_e32 v15, 0xffff0000, v218
	v_lshlrev_b32_e32 v10, 16, v219
	v_and_b32_e32 v11, 0xffff0000, v219
	v_lshlrev_b32_e32 v16, 16, v220
	v_and_b32_e32 v17, 0xffff0000, v220
	v_lshlrev_b32_e32 v12, 16, v221
	v_and_b32_e32 v13, 0xffff0000, v221
	v_pk_fma_f32 v[8:9], v[8:9], v[128:129], v[10:11]
	v_pk_fma_f32 v[6:7], v[6:7], v[126:127], v[14:15]
	v_pk_fma_f32 v[10:11], v[4:5], v[124:125], v[12:13]
	v_pk_fma_f32 v[4:5], v[2:3], v[122:123], v[16:17]
	v_cvt_pk_bf16_f32 v2, v6, v7
	v_cvt_pk_bf16_f32 v3, v8, v9
	v_cvt_pk_bf16_f32 v4, v4, v5
	v_cvt_pk_bf16_f32 v5, v10, v11
	global_store_dwordx4 v[22:23], v[2:5], off offset:256
	s_cbranch_vccnz .LBB0_1276
	s_andn2_b64 vcc, exec, s[6:7]
	s_cbranch_vccnz .LBB0_1275
	s_branch .LBB0_1275
